# 64-MFMA K-loop segments with split lead/trail staging rolled out to P1 P4 P5 P7 GLU (P6 before)
# speedup vs baseline: 1.0114x; 1.0079x over previous
.LBB0_156:
	v_bfe_u32 v15, v8, 4, 2
	v_and_b32_e32 v139, 15, v8
	v_lshlrev_b32_e32 v17, 4, v15
	v_lshlrev_b32_e32 v8, 2, v8
	s_mov_b64 s[34:35], 0x80
	s_and_b32 s1, s4, 3
	v_lshl_or_b32 v17, v139, 6, v17
	s_lshl_b32 s4, s11, 13
	v_and_b32_e32 v8, 32, v8
	s_add_i32 m0, s23, 0x18000
	v_lshl_add_u64 v[6:7], v[6:7], 0, s[34:35]
	s_lshl_b32 s27, s11, 6
	s_waitcnt vmcnt(0)
	v_bitop3_b32 v18, v17, s4, v8 bitop3:0xde
	s_lshl_b32 s4, s1, 12
	s_waitcnt vmcnt(0)
	s_barrier
	s_add_u32 vcc_lo, s14, 0x80080
	s_addc_u32 vcc_hi, s15, 0
	s_add_i32 m0, s23, 0xc000
	s_nop 0
	global_load_lds_dwordx4 v128, vcc
	s_add_i32 m0, s23, 0x18000
	s_nop 0
	global_load_lds_dwordx4 v[6:7], off
	v_lshl_add_u64 v[4:5], v[4:5], 0, s[34:35]
	s_add_i32 m0, s23, 0x1a000
	s_add_i32 s31, s23, 0x8000
	s_add_i32 s51, s23, 0xa000
	global_load_lds_dwordx4 v[4:5], off
	v_lshl_add_u64 v[0:1], v[0:1], 0, s[34:35]
	s_mov_b32 m0, s31
	s_add_u32 s12, s16, 0x80080
	global_load_lds_dwordx4 v[0:1], off
	v_lshl_add_u64 v[0:1], v[2:3], 0, s[34:35]
	s_mov_b32 m0, s51
	s_addc_u32 s13, s17, 0
	global_load_lds_dwordx4 v[0:1], off
	s_add_i32 m0, s23, 0x1c000
	v_lshl_add_u64 v[0:1], s[12:13], 0, v[130:131]
	global_load_lds_dwordx4 v[0:1], off
	v_lshl_add_u64 v[0:1], s[12:13], 0, v[134:135]
	s_add_i32 m0, s23, 0x1e000
	s_cmpk_lt_u32 s10, 0x100
	global_load_lds_dwordx4 v[0:1], off
	v_lshlrev_b32_e32 v0, 2, v15
	v_cvt_f32_ubyte0_e32 v1, v0
	v_mul_f32_e32 v1, 0xbf549a78, v1
	v_exp_f32_e32 v161, v1
	v_or_b32_e32 v1, 1, v0
	v_cvt_f32_ubyte0_e32 v1, v1
	v_mul_f32_e32 v1, 0xbf549a78, v1
	v_exp_f32_e32 v162, v1
	v_or_b32_e32 v1, 2, v0
	v_or_b32_e32 v0, 3, v0
	v_cvt_f32_ubyte0_e32 v0, v0
	v_mul_f32_e32 v0, 0xbf549a78, v0
	v_cvt_f32_ubyte0_e32 v1, v1
	v_exp_f32_e32 v164, v0
	v_lshlrev_b32_e32 v0, 15, v9
	v_mul_f32_e32 v1, 0xbf549a78, v1
	v_and_b32_e32 v0, 0xffff0000, v0
	v_exp_f32_e32 v163, v1
	v_lshl_add_u32 v0, v10, 12, v0
	v_and_b32_e32 v1, 1, v9
	v_lshl_or_b32 v0, v1, 6, v0
	v_lshl_add_u32 v142, v11, 1, v0
	v_lshlrev_b32_e32 v0, 15, v12
	v_and_b32_e32 v0, 0xffff0000, v0
	v_lshlrev_b32_e32 v16, 3, v15
	s_cselect_b64 s[36:37], -1, 0
	s_cmp_lt_u32 s1, 2
	v_lshl_add_u32 v0, v13, 12, v0
	v_and_b32_e32 v1, 1, v12
	s_waitcnt vmcnt(6)
	v_lshl_or_b32 v138, s1, 5, v16
	s_cselect_b64 s[42:43], -1, 0
	s_cmp_eq_u32 s1, 0
	v_lshl_or_b32 v0, v1, 6, v0
	v_bitop3_b32 v160, v17, s4, v8 bitop3:0xde
	s_cselect_b64 s[38:39], -1, 0
	v_lshlrev_b32_e32 v136, 1, v138
	v_lshl_add_u32 v144, v14, 1, v0
	s_add_i32 s56, 0, 0x10000
	s_add_i32 s57, 0, 0x14000
	v_mbcnt_lo_u32_b32 v0, -1, 0
	v_or_b32_e32 v165, 16, v139
	v_or_b32_e32 v166, 32, v139
	v_or_b32_e32 v167, 48, v139
	v_cmp_eq_u32_e64 s[40:41], 0, v15
	v_lshl_add_u64 v[140:141], s[52:53], 0, v[136:137]
	v_mov_b32_e32 v143, v137
	v_mov_b32_e32 v145, v137
	v_mov_b64_e32 v[146:147], 0x2ff
	v_add_u32_e32 v168, s56, v160
	v_add_u32_e32 v169, s57, v160
	v_add_u32_e32 v170, 0, v18
	s_movk_i32 s60, 0x600
	v_mbcnt_hi_u32_b32 v171, -1, v0
	s_mov_b32 s61, 0
	s_barrier
	s_branch .LBB0_159

.LBB0_165:
	s_add_u32 s16, s14, 0xfff80080
	s_addc_u32 s17, s15, -1
	s_cmp_eq_u32 s64, 28
	s_cselect_b32 s19, s1, s17
	s_cselect_b32 s18, s4, s16
	s_cselect_b32 s17, s11, s21
	s_cselect_b32 s16, s13, s20
	s_and_b64 vcc, exec, s[36:37]
	s_cbranch_vccz .Lk64_trail_p1
	s_sub_u32 vcc_lo, s20, 0x80
	s_subb_u32 vcc_hi, s21, 0
	s_add_i32 m0, s23, 0x18000
	s_nop 0
	global_load_lds_dwordx4 v130, vcc
	s_add_i32 m0, s23, 0x1a000
	s_nop 0
	global_load_lds_dwordx4 v134, vcc
	s_add_u32 vcc_lo, vcc_lo, 0x20000
	s_addc_u32 vcc_hi, vcc_hi, 0
	s_add_i32 m0, s23, 0x19000
	s_nop 0
	global_load_lds_dwordx4 v130, vcc
	s_add_i32 m0, s23, 0x1b000
	s_nop 0
	global_load_lds_dwordx4 v134, vcc
	s_add_u32 vcc_lo, vcc_lo, 0x60000
	s_addc_u32 vcc_hi, vcc_hi, 0
	s_add_i32 m0, s23, 0x1c000
	s_nop 0
	global_load_lds_dwordx4 v130, vcc
	s_add_i32 m0, s23, 0x1e000
	s_nop 0
	global_load_lds_dwordx4 v134, vcc
	s_add_u32 vcc_lo, vcc_lo, 0x20000
	s_addc_u32 vcc_hi, vcc_hi, 0
	s_add_i32 m0, s23, 0x1d000
	s_nop 0
	global_load_lds_dwordx4 v130, vcc
	s_add_i32 m0, s23, 0x1f000
	s_nop 0
	global_load_lds_dwordx4 v134, vcc
	ds_read_b128 v[148:151], v168 offset:0
	ds_read_b128 v[152:155], v168 offset:1024
	ds_read_b128 v[156:159], v168 offset:2048
	ds_read_b128 v[172:175], v168 offset:3072
	ds_read_b128 v[176:179], v169 offset:0
	ds_read_b128 v[180:183], v169 offset:1024
	ds_read_b128 v[184:187], v169 offset:2048
	ds_read_b128 v[188:191], v169 offset:3072
	ds_read_b128 v[192:195], v170 offset:0
	ds_read_b128 v[196:199], v170 offset:1024
	ds_read_b128 v[200:203], v170 offset:2048
	ds_read_b128 v[204:207], v170 offset:3072
	ds_read_b128 v[208:211], v170 offset:4096
	ds_read_b128 v[212:215], v170 offset:5120
	ds_read_b128 v[216:219], v170 offset:6144
	ds_read_b128 v[220:223], v170 offset:7168
	ds_read_b128 v[142:145], v170 offset:16384
	ds_read_b128 v[224:227], v170 offset:17408
	ds_read_b128 v[228:231], v170 offset:18432
	ds_read_b128 v[232:235], v170 offset:19456
	ds_read_b128 v[236:239], v170 offset:20480
	ds_read_b128 v[240:243], v170 offset:21504
	ds_read_b128 v[244:247], v170 offset:22528
	ds_read_b128 v[248:251], v170 offset:23552
	s_nop 15
	s_nop 15
	s_waitcnt lgkmcnt(0)
	s_barrier
	s_setprio 1
	v_mfma_f32_16x16x32_bf16 v[124:127], v[148:151], v[192:195], v[124:127]
	v_mfma_f32_16x16x32_bf16 v[120:123], v[156:159], v[192:195], v[120:123]
	v_mfma_f32_16x16x32_bf16 v[116:119], v[148:151], v[200:203], v[116:119]
	v_mfma_f32_16x16x32_bf16 v[112:115], v[156:159], v[200:203], v[112:115]
	v_mfma_f32_16x16x32_bf16 v[100:103], v[148:151], v[208:211], v[100:103]
	v_mfma_f32_16x16x32_bf16 v[96:99], v[156:159], v[208:211], v[96:99]
	v_mfma_f32_16x16x32_bf16 v[84:87], v[148:151], v[216:219], v[84:87]
	v_mfma_f32_16x16x32_bf16 v[80:83], v[156:159], v[216:219], v[80:83]
	v_mfma_f32_16x16x32_bf16 v[124:127], v[152:155], v[196:199], v[124:127]
	v_mfma_f32_16x16x32_bf16 v[120:123], v[172:175], v[196:199], v[120:123]
	v_mfma_f32_16x16x32_bf16 v[116:119], v[152:155], v[204:207], v[116:119]
	v_mfma_f32_16x16x32_bf16 v[112:115], v[172:175], v[204:207], v[112:115]
	v_mfma_f32_16x16x32_bf16 v[100:103], v[152:155], v[212:215], v[100:103]
	v_mfma_f32_16x16x32_bf16 v[96:99], v[172:175], v[212:215], v[96:99]
	v_mfma_f32_16x16x32_bf16 v[84:87], v[152:155], v[220:223], v[84:87]
	v_mfma_f32_16x16x32_bf16 v[80:83], v[172:175], v[220:223], v[80:83]
	s_setprio 0
	s_setprio 1
	v_mfma_f32_16x16x32_bf16 v[108:111], v[176:179], v[192:195], v[108:111]
	v_mfma_f32_16x16x32_bf16 v[104:107], v[184:187], v[192:195], v[104:107]
	v_mfma_f32_16x16x32_bf16 v[92:95], v[176:179], v[200:203], v[92:95]
	v_mfma_f32_16x16x32_bf16 v[88:91], v[184:187], v[200:203], v[88:91]
	v_mfma_f32_16x16x32_bf16 v[76:79], v[176:179], v[208:211], v[76:79]
	v_mfma_f32_16x16x32_bf16 v[72:75], v[184:187], v[208:211], v[72:75]
	v_mfma_f32_16x16x32_bf16 v[68:71], v[176:179], v[216:219], v[68:71]
	v_mfma_f32_16x16x32_bf16 v[64:67], v[184:187], v[216:219], v[64:67]
	v_mfma_f32_16x16x32_bf16 v[108:111], v[180:183], v[196:199], v[108:111]
	v_mfma_f32_16x16x32_bf16 v[104:107], v[188:191], v[196:199], v[104:107]
	v_mfma_f32_16x16x32_bf16 v[92:95], v[180:183], v[204:207], v[92:95]
	v_mfma_f32_16x16x32_bf16 v[88:91], v[188:191], v[204:207], v[88:91]
	v_mfma_f32_16x16x32_bf16 v[76:79], v[180:183], v[212:215], v[76:79]
	v_mfma_f32_16x16x32_bf16 v[72:75], v[188:191], v[212:215], v[72:75]
	v_mfma_f32_16x16x32_bf16 v[68:71], v[180:183], v[220:223], v[68:71]
	v_mfma_f32_16x16x32_bf16 v[64:67], v[188:191], v[220:223], v[64:67]
	s_setprio 0
	s_setprio 1
	v_mfma_f32_16x16x32_bf16 v[60:63], v[148:151], v[142:145], v[60:63]
	v_mfma_f32_16x16x32_bf16 v[56:59], v[156:159], v[142:145], v[56:59]
	v_mfma_f32_16x16x32_bf16 v[52:55], v[148:151], v[228:231], v[52:55]
	v_mfma_f32_16x16x32_bf16 v[48:51], v[156:159], v[228:231], v[48:51]
	v_mfma_f32_16x16x32_bf16 v[36:39], v[148:151], v[236:239], v[36:39]
	v_mfma_f32_16x16x32_bf16 v[32:35], v[156:159], v[236:239], v[32:35]
	v_mfma_f32_16x16x32_bf16 v[20:23], v[148:151], v[244:247], v[20:23]
	v_mfma_f32_16x16x32_bf16 v[16:19], v[156:159], v[244:247], v[16:19]
	v_mfma_f32_16x16x32_bf16 v[60:63], v[152:155], v[224:227], v[60:63]
	v_mfma_f32_16x16x32_bf16 v[56:59], v[172:175], v[224:227], v[56:59]
	v_mfma_f32_16x16x32_bf16 v[52:55], v[152:155], v[232:235], v[52:55]
	v_mfma_f32_16x16x32_bf16 v[48:51], v[172:175], v[232:235], v[48:51]
	v_mfma_f32_16x16x32_bf16 v[36:39], v[152:155], v[240:243], v[36:39]
	v_mfma_f32_16x16x32_bf16 v[32:35], v[172:175], v[240:243], v[32:35]
	v_mfma_f32_16x16x32_bf16 v[20:23], v[152:155], v[248:251], v[20:23]
	v_mfma_f32_16x16x32_bf16 v[16:19], v[172:175], v[248:251], v[16:19]
	s_setprio 0
	s_setprio 1
	v_mfma_f32_16x16x32_bf16 v[44:47], v[176:179], v[142:145], v[44:47]
	v_mfma_f32_16x16x32_bf16 v[40:43], v[184:187], v[142:145], v[40:43]
	v_mfma_f32_16x16x32_bf16 v[28:31], v[176:179], v[228:231], v[28:31]
	v_mfma_f32_16x16x32_bf16 v[24:27], v[184:187], v[228:231], v[24:27]
	v_mfma_f32_16x16x32_bf16 v[12:15], v[176:179], v[236:239], v[12:15]
	v_mfma_f32_16x16x32_bf16 v[8:11], v[184:187], v[236:239], v[8:11]
	v_mfma_f32_16x16x32_bf16 v[4:7], v[176:179], v[244:247], v[4:7]
	v_mfma_f32_16x16x32_bf16 v[0:3], v[184:187], v[244:247], v[0:3]
	v_mfma_f32_16x16x32_bf16 v[44:47], v[180:183], v[224:227], v[44:47]
	v_mfma_f32_16x16x32_bf16 v[40:43], v[188:191], v[224:227], v[40:43]
	v_mfma_f32_16x16x32_bf16 v[28:31], v[180:183], v[232:235], v[28:31]
	v_mfma_f32_16x16x32_bf16 v[24:27], v[188:191], v[232:235], v[24:27]
	v_mfma_f32_16x16x32_bf16 v[12:15], v[180:183], v[240:243], v[12:15]
	v_mfma_f32_16x16x32_bf16 v[8:11], v[188:191], v[240:243], v[8:11]
	v_mfma_f32_16x16x32_bf16 v[4:7], v[180:183], v[248:251], v[4:7]
	v_mfma_f32_16x16x32_bf16 v[0:3], v[188:191], v[248:251], v[0:3]
	s_setprio 0
	s_waitcnt vmcnt(0)
	s_barrier
	s_add_u32 vcc_lo, s16, 0x0
	s_addc_u32 vcc_hi, s17, 0
	s_add_i32 m0, s23, 0x10000
	s_nop 0
	global_load_lds_dwordx4 v130, vcc
	s_add_i32 m0, s23, 0x12000
	s_nop 0
	global_load_lds_dwordx4 v134, vcc
	s_add_u32 vcc_lo, vcc_lo, 0x20000
	s_addc_u32 vcc_hi, vcc_hi, 0
	s_add_i32 m0, s23, 0x11000
	s_nop 0
	global_load_lds_dwordx4 v130, vcc
	s_add_i32 m0, s23, 0x13000
	s_nop 0
	global_load_lds_dwordx4 v134, vcc
	s_add_u32 vcc_lo, vcc_lo, 0x60000
	s_addc_u32 vcc_hi, vcc_hi, 0
	s_add_i32 m0, s23, 0x14000
	s_nop 0
	global_load_lds_dwordx4 v130, vcc
	s_add_i32 m0, s23, 0x16000
	s_nop 0
	global_load_lds_dwordx4 v134, vcc
	s_add_u32 vcc_lo, vcc_lo, 0x20000
	s_addc_u32 vcc_hi, vcc_hi, 0
	s_add_i32 m0, s23, 0x15000
	s_nop 0
	global_load_lds_dwordx4 v130, vcc
	s_add_i32 m0, s23, 0x17000
	s_nop 0
	global_load_lds_dwordx4 v134, vcc
	ds_read_b128 v[148:151], v168 offset:32768
	ds_read_b128 v[152:155], v168 offset:33792
	ds_read_b128 v[156:159], v168 offset:34816
	ds_read_b128 v[172:175], v168 offset:35840
	ds_read_b128 v[176:179], v169 offset:32768
	ds_read_b128 v[180:183], v169 offset:33792
	ds_read_b128 v[184:187], v169 offset:34816
	ds_read_b128 v[188:191], v169 offset:35840
	ds_read_b128 v[192:195], v170 offset:32768
	ds_read_b128 v[196:199], v170 offset:33792
	ds_read_b128 v[200:203], v170 offset:34816
	ds_read_b128 v[204:207], v170 offset:35840
	ds_read_b128 v[208:211], v170 offset:36864
	ds_read_b128 v[212:215], v170 offset:37888
	ds_read_b128 v[216:219], v170 offset:38912
	ds_read_b128 v[220:223], v170 offset:39936
	ds_read_b128 v[142:145], v170 offset:49152
	ds_read_b128 v[224:227], v170 offset:50176
	ds_read_b128 v[228:231], v170 offset:51200
	ds_read_b128 v[232:235], v170 offset:52224
	ds_read_b128 v[236:239], v170 offset:53248
	ds_read_b128 v[240:243], v170 offset:54272
	ds_read_b128 v[244:247], v170 offset:55296
	ds_read_b128 v[248:251], v170 offset:56320
	s_nop 15
	s_nop 15
	s_waitcnt lgkmcnt(0)
	s_barrier
	s_setprio 1
	v_mfma_f32_16x16x32_bf16 v[124:127], v[148:151], v[192:195], v[124:127]
	v_mfma_f32_16x16x32_bf16 v[120:123], v[156:159], v[192:195], v[120:123]
	v_mfma_f32_16x16x32_bf16 v[116:119], v[148:151], v[200:203], v[116:119]
	v_mfma_f32_16x16x32_bf16 v[112:115], v[156:159], v[200:203], v[112:115]
	v_mfma_f32_16x16x32_bf16 v[100:103], v[148:151], v[208:211], v[100:103]
	v_mfma_f32_16x16x32_bf16 v[96:99], v[156:159], v[208:211], v[96:99]
	v_mfma_f32_16x16x32_bf16 v[84:87], v[148:151], v[216:219], v[84:87]
	v_mfma_f32_16x16x32_bf16 v[80:83], v[156:159], v[216:219], v[80:83]
	v_mfma_f32_16x16x32_bf16 v[124:127], v[152:155], v[196:199], v[124:127]
	v_mfma_f32_16x16x32_bf16 v[120:123], v[172:175], v[196:199], v[120:123]
	v_mfma_f32_16x16x32_bf16 v[116:119], v[152:155], v[204:207], v[116:119]
	v_mfma_f32_16x16x32_bf16 v[112:115], v[172:175], v[204:207], v[112:115]
	v_mfma_f32_16x16x32_bf16 v[100:103], v[152:155], v[212:215], v[100:103]
	v_mfma_f32_16x16x32_bf16 v[96:99], v[172:175], v[212:215], v[96:99]
	v_mfma_f32_16x16x32_bf16 v[84:87], v[152:155], v[220:223], v[84:87]
	v_mfma_f32_16x16x32_bf16 v[80:83], v[172:175], v[220:223], v[80:83]
	s_setprio 0
	s_setprio 1
	v_mfma_f32_16x16x32_bf16 v[108:111], v[176:179], v[192:195], v[108:111]
	v_mfma_f32_16x16x32_bf16 v[104:107], v[184:187], v[192:195], v[104:107]
	v_mfma_f32_16x16x32_bf16 v[92:95], v[176:179], v[200:203], v[92:95]
	v_mfma_f32_16x16x32_bf16 v[88:91], v[184:187], v[200:203], v[88:91]
	v_mfma_f32_16x16x32_bf16 v[76:79], v[176:179], v[208:211], v[76:79]
	v_mfma_f32_16x16x32_bf16 v[72:75], v[184:187], v[208:211], v[72:75]
	v_mfma_f32_16x16x32_bf16 v[68:71], v[176:179], v[216:219], v[68:71]
	v_mfma_f32_16x16x32_bf16 v[64:67], v[184:187], v[216:219], v[64:67]
	v_mfma_f32_16x16x32_bf16 v[108:111], v[180:183], v[196:199], v[108:111]
	v_mfma_f32_16x16x32_bf16 v[104:107], v[188:191], v[196:199], v[104:107]
	v_mfma_f32_16x16x32_bf16 v[92:95], v[180:183], v[204:207], v[92:95]
	v_mfma_f32_16x16x32_bf16 v[88:91], v[188:191], v[204:207], v[88:91]
	v_mfma_f32_16x16x32_bf16 v[76:79], v[180:183], v[212:215], v[76:79]
	v_mfma_f32_16x16x32_bf16 v[72:75], v[188:191], v[212:215], v[72:75]
	v_mfma_f32_16x16x32_bf16 v[68:71], v[180:183], v[220:223], v[68:71]
	v_mfma_f32_16x16x32_bf16 v[64:67], v[188:191], v[220:223], v[64:67]
	s_setprio 0
	s_setprio 1
	v_mfma_f32_16x16x32_bf16 v[60:63], v[148:151], v[142:145], v[60:63]
	v_mfma_f32_16x16x32_bf16 v[56:59], v[156:159], v[142:145], v[56:59]
	v_mfma_f32_16x16x32_bf16 v[52:55], v[148:151], v[228:231], v[52:55]
	v_mfma_f32_16x16x32_bf16 v[48:51], v[156:159], v[228:231], v[48:51]
	v_mfma_f32_16x16x32_bf16 v[36:39], v[148:151], v[236:239], v[36:39]
	v_mfma_f32_16x16x32_bf16 v[32:35], v[156:159], v[236:239], v[32:35]
	v_mfma_f32_16x16x32_bf16 v[20:23], v[148:151], v[244:247], v[20:23]
	v_mfma_f32_16x16x32_bf16 v[16:19], v[156:159], v[244:247], v[16:19]
	v_mfma_f32_16x16x32_bf16 v[60:63], v[152:155], v[224:227], v[60:63]
	v_mfma_f32_16x16x32_bf16 v[56:59], v[172:175], v[224:227], v[56:59]
	v_mfma_f32_16x16x32_bf16 v[52:55], v[152:155], v[232:235], v[52:55]
	v_mfma_f32_16x16x32_bf16 v[48:51], v[172:175], v[232:235], v[48:51]
	v_mfma_f32_16x16x32_bf16 v[36:39], v[152:155], v[240:243], v[36:39]
	v_mfma_f32_16x16x32_bf16 v[32:35], v[172:175], v[240:243], v[32:35]
	v_mfma_f32_16x16x32_bf16 v[20:23], v[152:155], v[248:251], v[20:23]
	v_mfma_f32_16x16x32_bf16 v[16:19], v[172:175], v[248:251], v[16:19]
	s_setprio 0
	s_setprio 1
	v_mfma_f32_16x16x32_bf16 v[44:47], v[176:179], v[142:145], v[44:47]
	v_mfma_f32_16x16x32_bf16 v[40:43], v[184:187], v[142:145], v[40:43]
	v_mfma_f32_16x16x32_bf16 v[28:31], v[176:179], v[228:231], v[28:31]
	v_mfma_f32_16x16x32_bf16 v[24:27], v[184:187], v[228:231], v[24:27]
	v_mfma_f32_16x16x32_bf16 v[12:15], v[176:179], v[236:239], v[12:15]
	v_mfma_f32_16x16x32_bf16 v[8:11], v[184:187], v[236:239], v[8:11]
	v_mfma_f32_16x16x32_bf16 v[4:7], v[176:179], v[244:247], v[4:7]
	v_mfma_f32_16x16x32_bf16 v[0:3], v[184:187], v[244:247], v[0:3]
	v_mfma_f32_16x16x32_bf16 v[44:47], v[180:183], v[224:227], v[44:47]
	v_mfma_f32_16x16x32_bf16 v[40:43], v[188:191], v[224:227], v[40:43]
	v_mfma_f32_16x16x32_bf16 v[28:31], v[180:183], v[232:235], v[28:31]
	v_mfma_f32_16x16x32_bf16 v[24:27], v[188:191], v[232:235], v[24:27]
	v_mfma_f32_16x16x32_bf16 v[12:15], v[180:183], v[240:243], v[12:15]
	v_mfma_f32_16x16x32_bf16 v[8:11], v[188:191], v[240:243], v[8:11]
	v_mfma_f32_16x16x32_bf16 v[4:7], v[180:183], v[248:251], v[4:7]
	v_mfma_f32_16x16x32_bf16 v[0:3], v[188:191], v[248:251], v[0:3]
	s_setprio 0
	s_waitcnt vmcnt(0)
	s_barrier
	s_add_i32 s64, s64, 2
	s_add_u32 s14, s14, 0x100
	s_addc_u32 s15, s15, 0
	s_add_u32 s20, s20, 0x100
	s_addc_u32 s21, s21, 0
	s_cmp_gt_u32 s64, 29
	s_cbranch_scc0 .LBB0_165
	s_branch .Lk64_done_p1
.Lk64_trail_p1:
	s_sub_u32 vcc_lo, s14, 0x80000
	s_subb_u32 vcc_hi, s15, 0
	s_add_i32 m0, s23, 0xa000
	s_nop 0
	global_load_lds_dwordx4 v132, vcc
	s_add_u32 vcc_lo, vcc_lo, 0x20000
	s_addc_u32 vcc_hi, vcc_hi, 0
	s_add_i32 m0, s23, 0x9000
	s_nop 0
	global_load_lds_dwordx4 v128, vcc
	s_add_u32 vcc_lo, vcc_lo, 0x60000
	s_addc_u32 vcc_hi, vcc_hi, 0
	s_add_i32 m0, s23, 0xe000
	s_nop 0
	global_load_lds_dwordx4 v132, vcc
	s_add_u32 vcc_lo, vcc_lo, 0x20000
	s_addc_u32 vcc_hi, vcc_hi, 0
	s_add_i32 m0, s23, 0xd000
	s_nop 0
	global_load_lds_dwordx4 v128, vcc
	s_add_u32 vcc_lo, s18, 0x0
	s_addc_u32 vcc_hi, s19, 0
	s_mov_b32 m0, s23
	s_nop 0
	global_load_lds_dwordx4 v128, vcc
	s_sub_u32 vcc_lo, vcc_lo, 0x20000
	s_subb_u32 vcc_hi, vcc_hi, 0
	s_sub_i32 m0, s23, 0x1000
	s_nop 0
	global_load_lds_dwordx4 v128, vcc
	s_add_u32 vcc_lo, vcc_lo, 0xa0000
	s_addc_u32 vcc_hi, vcc_hi, 0
	s_add_i32 m0, s23, 0x4000
	s_nop 0
	global_load_lds_dwordx4 v128, vcc
	s_sub_u32 vcc_lo, vcc_lo, 0x20000
	s_subb_u32 vcc_hi, vcc_hi, 0
	s_add_i32 m0, s23, 0x3000
	s_nop 0
	global_load_lds_dwordx4 v128, vcc
	ds_read_b128 v[148:151], v168 offset:0
	ds_read_b128 v[152:155], v168 offset:1024
	ds_read_b128 v[156:159], v168 offset:2048
	ds_read_b128 v[172:175], v168 offset:3072
	ds_read_b128 v[176:179], v169 offset:0
	ds_read_b128 v[180:183], v169 offset:1024
	ds_read_b128 v[184:187], v169 offset:2048
	ds_read_b128 v[188:191], v169 offset:3072
	ds_read_b128 v[192:195], v170 offset:0
	ds_read_b128 v[196:199], v170 offset:1024
	ds_read_b128 v[200:203], v170 offset:2048
	ds_read_b128 v[204:207], v170 offset:3072
	ds_read_b128 v[208:211], v170 offset:4096
	ds_read_b128 v[212:215], v170 offset:5120
	ds_read_b128 v[216:219], v170 offset:6144
	ds_read_b128 v[220:223], v170 offset:7168
	ds_read_b128 v[142:145], v170 offset:16384
	ds_read_b128 v[224:227], v170 offset:17408
	ds_read_b128 v[228:231], v170 offset:18432
	ds_read_b128 v[232:235], v170 offset:19456
	ds_read_b128 v[236:239], v170 offset:20480
	ds_read_b128 v[240:243], v170 offset:21504
	ds_read_b128 v[244:247], v170 offset:22528
	ds_read_b128 v[248:251], v170 offset:23552
	s_nop 15
	s_nop 15
	s_waitcnt lgkmcnt(0)
	s_barrier
	s_setprio 1
	v_mfma_f32_16x16x32_bf16 v[124:127], v[148:151], v[192:195], v[124:127]
	v_mfma_f32_16x16x32_bf16 v[120:123], v[156:159], v[192:195], v[120:123]
	v_mfma_f32_16x16x32_bf16 v[116:119], v[148:151], v[200:203], v[116:119]
	v_mfma_f32_16x16x32_bf16 v[112:115], v[156:159], v[200:203], v[112:115]
	v_mfma_f32_16x16x32_bf16 v[100:103], v[148:151], v[208:211], v[100:103]
	v_mfma_f32_16x16x32_bf16 v[96:99], v[156:159], v[208:211], v[96:99]
	v_mfma_f32_16x16x32_bf16 v[84:87], v[148:151], v[216:219], v[84:87]
	v_mfma_f32_16x16x32_bf16 v[80:83], v[156:159], v[216:219], v[80:83]
	v_mfma_f32_16x16x32_bf16 v[124:127], v[152:155], v[196:199], v[124:127]
	v_mfma_f32_16x16x32_bf16 v[120:123], v[172:175], v[196:199], v[120:123]
	v_mfma_f32_16x16x32_bf16 v[116:119], v[152:155], v[204:207], v[116:119]
	v_mfma_f32_16x16x32_bf16 v[112:115], v[172:175], v[204:207], v[112:115]
	v_mfma_f32_16x16x32_bf16 v[100:103], v[152:155], v[212:215], v[100:103]
	v_mfma_f32_16x16x32_bf16 v[96:99], v[172:175], v[212:215], v[96:99]
	v_mfma_f32_16x16x32_bf16 v[84:87], v[152:155], v[220:223], v[84:87]
	v_mfma_f32_16x16x32_bf16 v[80:83], v[172:175], v[220:223], v[80:83]
	s_setprio 0
	s_setprio 1
	v_mfma_f32_16x16x32_bf16 v[108:111], v[176:179], v[192:195], v[108:111]
	v_mfma_f32_16x16x32_bf16 v[104:107], v[184:187], v[192:195], v[104:107]
	v_mfma_f32_16x16x32_bf16 v[92:95], v[176:179], v[200:203], v[92:95]
	v_mfma_f32_16x16x32_bf16 v[88:91], v[184:187], v[200:203], v[88:91]
	v_mfma_f32_16x16x32_bf16 v[76:79], v[176:179], v[208:211], v[76:79]
	v_mfma_f32_16x16x32_bf16 v[72:75], v[184:187], v[208:211], v[72:75]
	v_mfma_f32_16x16x32_bf16 v[68:71], v[176:179], v[216:219], v[68:71]
	v_mfma_f32_16x16x32_bf16 v[64:67], v[184:187], v[216:219], v[64:67]
	v_mfma_f32_16x16x32_bf16 v[108:111], v[180:183], v[196:199], v[108:111]
	v_mfma_f32_16x16x32_bf16 v[104:107], v[188:191], v[196:199], v[104:107]
	v_mfma_f32_16x16x32_bf16 v[92:95], v[180:183], v[204:207], v[92:95]
	v_mfma_f32_16x16x32_bf16 v[88:91], v[188:191], v[204:207], v[88:91]
	v_mfma_f32_16x16x32_bf16 v[76:79], v[180:183], v[212:215], v[76:79]
	v_mfma_f32_16x16x32_bf16 v[72:75], v[188:191], v[212:215], v[72:75]
	v_mfma_f32_16x16x32_bf16 v[68:71], v[180:183], v[220:223], v[68:71]
	v_mfma_f32_16x16x32_bf16 v[64:67], v[188:191], v[220:223], v[64:67]
	s_setprio 0
	s_setprio 1
	v_mfma_f32_16x16x32_bf16 v[60:63], v[148:151], v[142:145], v[60:63]
	v_mfma_f32_16x16x32_bf16 v[56:59], v[156:159], v[142:145], v[56:59]
	v_mfma_f32_16x16x32_bf16 v[52:55], v[148:151], v[228:231], v[52:55]
	v_mfma_f32_16x16x32_bf16 v[48:51], v[156:159], v[228:231], v[48:51]
	v_mfma_f32_16x16x32_bf16 v[36:39], v[148:151], v[236:239], v[36:39]
	v_mfma_f32_16x16x32_bf16 v[32:35], v[156:159], v[236:239], v[32:35]
	v_mfma_f32_16x16x32_bf16 v[20:23], v[148:151], v[244:247], v[20:23]
	v_mfma_f32_16x16x32_bf16 v[16:19], v[156:159], v[244:247], v[16:19]
	v_mfma_f32_16x16x32_bf16 v[60:63], v[152:155], v[224:227], v[60:63]
	v_mfma_f32_16x16x32_bf16 v[56:59], v[172:175], v[224:227], v[56:59]
	v_mfma_f32_16x16x32_bf16 v[52:55], v[152:155], v[232:235], v[52:55]
	v_mfma_f32_16x16x32_bf16 v[48:51], v[172:175], v[232:235], v[48:51]
	v_mfma_f32_16x16x32_bf16 v[36:39], v[152:155], v[240:243], v[36:39]
	v_mfma_f32_16x16x32_bf16 v[32:35], v[172:175], v[240:243], v[32:35]
	v_mfma_f32_16x16x32_bf16 v[20:23], v[152:155], v[248:251], v[20:23]
	v_mfma_f32_16x16x32_bf16 v[16:19], v[172:175], v[248:251], v[16:19]
	s_setprio 0
	s_setprio 1
	v_mfma_f32_16x16x32_bf16 v[44:47], v[176:179], v[142:145], v[44:47]
	v_mfma_f32_16x16x32_bf16 v[40:43], v[184:187], v[142:145], v[40:43]
	v_mfma_f32_16x16x32_bf16 v[28:31], v[176:179], v[228:231], v[28:31]
	v_mfma_f32_16x16x32_bf16 v[24:27], v[184:187], v[228:231], v[24:27]
	v_mfma_f32_16x16x32_bf16 v[12:15], v[176:179], v[236:239], v[12:15]
	v_mfma_f32_16x16x32_bf16 v[8:11], v[184:187], v[236:239], v[8:11]
	v_mfma_f32_16x16x32_bf16 v[4:7], v[176:179], v[244:247], v[4:7]
	v_mfma_f32_16x16x32_bf16 v[0:3], v[184:187], v[244:247], v[0:3]
	v_mfma_f32_16x16x32_bf16 v[44:47], v[180:183], v[224:227], v[44:47]
	v_mfma_f32_16x16x32_bf16 v[40:43], v[188:191], v[224:227], v[40:43]
	v_mfma_f32_16x16x32_bf16 v[28:31], v[180:183], v[232:235], v[28:31]
	v_mfma_f32_16x16x32_bf16 v[24:27], v[188:191], v[232:235], v[24:27]
	v_mfma_f32_16x16x32_bf16 v[12:15], v[180:183], v[240:243], v[12:15]
	v_mfma_f32_16x16x32_bf16 v[8:11], v[188:191], v[240:243], v[8:11]
	v_mfma_f32_16x16x32_bf16 v[4:7], v[180:183], v[248:251], v[4:7]
	v_mfma_f32_16x16x32_bf16 v[0:3], v[188:191], v[248:251], v[0:3]
	s_setprio 0
	s_waitcnt vmcnt(0)
	s_barrier
	s_add_u32 vcc_lo, s18, 0x0
	s_addc_u32 vcc_hi, s19, 0
	s_add_i32 m0, s23, 0x2000
	s_nop 0
	global_load_lds_dwordx4 v132, vcc
	s_add_u32 vcc_lo, vcc_lo, 0x20000
	s_addc_u32 vcc_hi, vcc_hi, 0
	s_add_i32 m0, s23, 0x1000
	s_nop 0
	global_load_lds_dwordx4 v128, vcc
	s_add_u32 vcc_lo, vcc_lo, 0x60000
	s_addc_u32 vcc_hi, vcc_hi, 0
	s_add_i32 m0, s23, 0x6000
	s_nop 0
	global_load_lds_dwordx4 v132, vcc
	s_add_u32 vcc_lo, vcc_lo, 0x20000
	s_addc_u32 vcc_hi, vcc_hi, 0
	s_add_i32 m0, s23, 0x5000
	s_nop 0
	global_load_lds_dwordx4 v128, vcc
	s_add_u32 vcc_lo, s18, 0x80
	s_addc_u32 vcc_hi, s19, 0
	s_add_i32 m0, s23, 0x8000
	s_nop 0
	global_load_lds_dwordx4 v128, vcc
	s_sub_u32 vcc_lo, vcc_lo, 0x20000
	s_subb_u32 vcc_hi, vcc_hi, 0
	s_add_i32 m0, s23, 0x7000
	s_nop 0
	global_load_lds_dwordx4 v128, vcc
	s_add_u32 vcc_lo, vcc_lo, 0xa0000
	s_addc_u32 vcc_hi, vcc_hi, 0
	s_add_i32 m0, s23, 0xc000
	s_nop 0
	global_load_lds_dwordx4 v128, vcc
	s_sub_u32 vcc_lo, vcc_lo, 0x20000
	s_subb_u32 vcc_hi, vcc_hi, 0
	s_add_i32 m0, s23, 0xb000
	s_nop 0
	global_load_lds_dwordx4 v128, vcc
	ds_read_b128 v[148:151], v168 offset:32768
	ds_read_b128 v[152:155], v168 offset:33792
	ds_read_b128 v[156:159], v168 offset:34816
	ds_read_b128 v[172:175], v168 offset:35840
	ds_read_b128 v[176:179], v169 offset:32768
	ds_read_b128 v[180:183], v169 offset:33792
	ds_read_b128 v[184:187], v169 offset:34816
	ds_read_b128 v[188:191], v169 offset:35840
	ds_read_b128 v[192:195], v170 offset:32768
	ds_read_b128 v[196:199], v170 offset:33792
	ds_read_b128 v[200:203], v170 offset:34816
	ds_read_b128 v[204:207], v170 offset:35840
	ds_read_b128 v[208:211], v170 offset:36864
	ds_read_b128 v[212:215], v170 offset:37888
	ds_read_b128 v[216:219], v170 offset:38912
	ds_read_b128 v[220:223], v170 offset:39936
	ds_read_b128 v[142:145], v170 offset:49152
	ds_read_b128 v[224:227], v170 offset:50176
	ds_read_b128 v[228:231], v170 offset:51200
	ds_read_b128 v[232:235], v170 offset:52224
	ds_read_b128 v[236:239], v170 offset:53248
	ds_read_b128 v[240:243], v170 offset:54272
	ds_read_b128 v[244:247], v170 offset:55296
	ds_read_b128 v[248:251], v170 offset:56320
	s_nop 15
	s_nop 15
	s_waitcnt lgkmcnt(0)
	s_barrier
	s_setprio 1
	v_mfma_f32_16x16x32_bf16 v[124:127], v[148:151], v[192:195], v[124:127]
	v_mfma_f32_16x16x32_bf16 v[120:123], v[156:159], v[192:195], v[120:123]
	v_mfma_f32_16x16x32_bf16 v[116:119], v[148:151], v[200:203], v[116:119]
	v_mfma_f32_16x16x32_bf16 v[112:115], v[156:159], v[200:203], v[112:115]
	v_mfma_f32_16x16x32_bf16 v[100:103], v[148:151], v[208:211], v[100:103]
	v_mfma_f32_16x16x32_bf16 v[96:99], v[156:159], v[208:211], v[96:99]
	v_mfma_f32_16x16x32_bf16 v[84:87], v[148:151], v[216:219], v[84:87]
	v_mfma_f32_16x16x32_bf16 v[80:83], v[156:159], v[216:219], v[80:83]
	v_mfma_f32_16x16x32_bf16 v[124:127], v[152:155], v[196:199], v[124:127]
	v_mfma_f32_16x16x32_bf16 v[120:123], v[172:175], v[196:199], v[120:123]
	v_mfma_f32_16x16x32_bf16 v[116:119], v[152:155], v[204:207], v[116:119]
	v_mfma_f32_16x16x32_bf16 v[112:115], v[172:175], v[204:207], v[112:115]
	v_mfma_f32_16x16x32_bf16 v[100:103], v[152:155], v[212:215], v[100:103]
	v_mfma_f32_16x16x32_bf16 v[96:99], v[172:175], v[212:215], v[96:99]
	v_mfma_f32_16x16x32_bf16 v[84:87], v[152:155], v[220:223], v[84:87]
	v_mfma_f32_16x16x32_bf16 v[80:83], v[172:175], v[220:223], v[80:83]
	s_setprio 0
	s_setprio 1
	v_mfma_f32_16x16x32_bf16 v[108:111], v[176:179], v[192:195], v[108:111]
	v_mfma_f32_16x16x32_bf16 v[104:107], v[184:187], v[192:195], v[104:107]
	v_mfma_f32_16x16x32_bf16 v[92:95], v[176:179], v[200:203], v[92:95]
	v_mfma_f32_16x16x32_bf16 v[88:91], v[184:187], v[200:203], v[88:91]
	v_mfma_f32_16x16x32_bf16 v[76:79], v[176:179], v[208:211], v[76:79]
	v_mfma_f32_16x16x32_bf16 v[72:75], v[184:187], v[208:211], v[72:75]
	v_mfma_f32_16x16x32_bf16 v[68:71], v[176:179], v[216:219], v[68:71]
	v_mfma_f32_16x16x32_bf16 v[64:67], v[184:187], v[216:219], v[64:67]
	v_mfma_f32_16x16x32_bf16 v[108:111], v[180:183], v[196:199], v[108:111]
	v_mfma_f32_16x16x32_bf16 v[104:107], v[188:191], v[196:199], v[104:107]
	v_mfma_f32_16x16x32_bf16 v[92:95], v[180:183], v[204:207], v[92:95]
	v_mfma_f32_16x16x32_bf16 v[88:91], v[188:191], v[204:207], v[88:91]
	v_mfma_f32_16x16x32_bf16 v[76:79], v[180:183], v[212:215], v[76:79]
	v_mfma_f32_16x16x32_bf16 v[72:75], v[188:191], v[212:215], v[72:75]
	v_mfma_f32_16x16x32_bf16 v[68:71], v[180:183], v[220:223], v[68:71]
	v_mfma_f32_16x16x32_bf16 v[64:67], v[188:191], v[220:223], v[64:67]
	s_setprio 0
	s_setprio 1
	v_mfma_f32_16x16x32_bf16 v[60:63], v[148:151], v[142:145], v[60:63]
	v_mfma_f32_16x16x32_bf16 v[56:59], v[156:159], v[142:145], v[56:59]
	v_mfma_f32_16x16x32_bf16 v[52:55], v[148:151], v[228:231], v[52:55]
	v_mfma_f32_16x16x32_bf16 v[48:51], v[156:159], v[228:231], v[48:51]
	v_mfma_f32_16x16x32_bf16 v[36:39], v[148:151], v[236:239], v[36:39]
	v_mfma_f32_16x16x32_bf16 v[32:35], v[156:159], v[236:239], v[32:35]
	v_mfma_f32_16x16x32_bf16 v[20:23], v[148:151], v[244:247], v[20:23]
	v_mfma_f32_16x16x32_bf16 v[16:19], v[156:159], v[244:247], v[16:19]
	v_mfma_f32_16x16x32_bf16 v[60:63], v[152:155], v[224:227], v[60:63]
	v_mfma_f32_16x16x32_bf16 v[56:59], v[172:175], v[224:227], v[56:59]
	v_mfma_f32_16x16x32_bf16 v[52:55], v[152:155], v[232:235], v[52:55]
	v_mfma_f32_16x16x32_bf16 v[48:51], v[172:175], v[232:235], v[48:51]
	v_mfma_f32_16x16x32_bf16 v[36:39], v[152:155], v[240:243], v[36:39]
	v_mfma_f32_16x16x32_bf16 v[32:35], v[172:175], v[240:243], v[32:35]
	v_mfma_f32_16x16x32_bf16 v[20:23], v[152:155], v[248:251], v[20:23]
	v_mfma_f32_16x16x32_bf16 v[16:19], v[172:175], v[248:251], v[16:19]
	s_setprio 0
	s_setprio 1
	v_mfma_f32_16x16x32_bf16 v[44:47], v[176:179], v[142:145], v[44:47]
	v_mfma_f32_16x16x32_bf16 v[40:43], v[184:187], v[142:145], v[40:43]
	v_mfma_f32_16x16x32_bf16 v[28:31], v[176:179], v[228:231], v[28:31]
	v_mfma_f32_16x16x32_bf16 v[24:27], v[184:187], v[228:231], v[24:27]
	v_mfma_f32_16x16x32_bf16 v[12:15], v[176:179], v[236:239], v[12:15]
	v_mfma_f32_16x16x32_bf16 v[8:11], v[184:187], v[236:239], v[8:11]
	v_mfma_f32_16x16x32_bf16 v[4:7], v[176:179], v[244:247], v[4:7]
	v_mfma_f32_16x16x32_bf16 v[0:3], v[184:187], v[244:247], v[0:3]
	v_mfma_f32_16x16x32_bf16 v[44:47], v[180:183], v[224:227], v[44:47]
	v_mfma_f32_16x16x32_bf16 v[40:43], v[188:191], v[224:227], v[40:43]
	v_mfma_f32_16x16x32_bf16 v[28:31], v[180:183], v[232:235], v[28:31]
	v_mfma_f32_16x16x32_bf16 v[24:27], v[188:191], v[232:235], v[24:27]
	v_mfma_f32_16x16x32_bf16 v[12:15], v[180:183], v[240:243], v[12:15]
	v_mfma_f32_16x16x32_bf16 v[8:11], v[188:191], v[240:243], v[8:11]
	v_mfma_f32_16x16x32_bf16 v[4:7], v[180:183], v[248:251], v[4:7]
	v_mfma_f32_16x16x32_bf16 v[0:3], v[188:191], v[248:251], v[0:3]
	s_setprio 0
	s_waitcnt vmcnt(0)
	s_barrier
	s_add_i32 s64, s64, 2
	s_add_u32 s14, s14, 0x100
	s_addc_u32 s15, s15, 0
	s_add_u32 s20, s20, 0x100
	s_addc_u32 s21, s21, 0
	s_cmp_gt_u32 s64, 29
	s_cbranch_scc0 .LBB0_165
.Lk64_done_p1:
	s_and_b64 vcc, exec, s[36:37]
	s_cbranch_vccz .LBB0_168
	s_barrier

.LBB0_603:
	v_lshrrev_b32_e32 v16, 1, v14
	v_and_b32_e32 v16, 24, v16
	v_and_b32_e32 v15, 15, v14
	v_lshlrev_b32_e32 v17, 1, v16
	v_lshlrev_b32_e32 v14, 2, v14
	s_sext_i32_i8 s21, s4
	v_lshl_or_b32 v148, s7, 6, v15
	v_lshl_or_b32 v15, v15, 6, v17
	s_lshl_b32 s4, s7, 13
	v_and_b32_e32 v14, 32, v14
	v_bitop3_b32 v17, v15, s4, v14 bitop3:0xde
	s_lshl_b32 s4, s5, 5
	s_and_b32 s12, s4, 0x60
	s_lshl_b32 s4, s12, 7
	v_bitop3_b32 v149, v15, s4, v14 bitop3:0xde
	s_mov_b64 s[4:5], 0x80
	s_add_i32 m0, s28, 0x18000
	v_lshl_add_u64 v[6:7], v[6:7], 0, s[4:5]
	s_waitcnt vmcnt(0)
	s_barrier
	s_add_u32 vcc_lo, s22, 0x40080
	s_addc_u32 vcc_hi, s23, 0
	s_add_i32 m0, s28, 0xc000
	s_nop 0
	global_load_lds_dwordx4 v134, vcc
	s_add_i32 m0, s28, 0x18000
	s_nop 0
	global_load_lds_dwordx4 v[6:7], off
	v_lshl_add_u64 v[4:5], v[4:5], 0, s[4:5]
	s_add_i32 m0, s28, 0x1a000
	s_add_i32 s35, s28, 0x8000
	s_add_i32 s36, s28, 0xa000
	global_load_lds_dwordx4 v[4:5], off
	v_lshl_add_u64 v[0:1], v[0:1], 0, s[4:5]
	s_mov_b32 m0, s35
	s_add_u32 s10, s24, 0x40080
	global_load_lds_dwordx4 v[0:1], off
	v_lshl_add_u64 v[0:1], v[2:3], 0, s[4:5]
	s_mov_b32 m0, s36
	s_addc_u32 s11, s25, 0
	global_load_lds_dwordx4 v[0:1], off
	s_add_i32 m0, s28, 0x1c000
	v_lshl_add_u64 v[0:1], s[10:11], 0, v[132:133]
	global_load_lds_dwordx4 v[0:1], off
	v_lshl_add_u64 v[0:1], s[10:11], 0, v[128:129]
	s_add_i32 m0, s28, 0x1e000
	s_cmpk_lt_u32 s6, 0x100
	global_load_lds_dwordx4 v[0:1], off
	v_lshlrev_b32_e32 v0, 14, v12
	v_and_b32_e32 v0, 0xffff8000, v0
	v_lshl_add_u32 v0, v11, 11, v0
	v_and_b32_e32 v1, 1, v12
	v_lshl_or_b32 v0, v1, 6, v0
	v_lshl_add_u32 v136, v13, 1, v0
	v_lshlrev_b32_e32 v0, 14, v8
	v_and_b32_e32 v0, 0xffff8000, v0
	s_waitcnt vmcnt(6)
	v_lshl_add_u32 v0, v9, 11, v0
	v_and_b32_e32 v1, 1, v8
	s_cselect_b64 s[6:7], -1, 0
	v_lshl_or_b32 v0, v1, 6, v0
	s_add_i32 s37, 0, 0x10000
	s_add_i32 s40, 0, 0x14000
	v_or_b32_e32 v150, s12, v16
	v_mov_b32_e32 v137, v133
	v_lshl_add_u32 v138, v10, 1, v0
	v_mov_b32_e32 v139, v133
	v_mov_b64_e32 v[140:141], 0x200
	v_mov_b64_e32 v[142:143], 0x1ff
	v_add_u32_e32 v151, s37, v149
	v_add_u32_e32 v152, s40, v149
	v_add_u32_e32 v153, 0, v17
	s_barrier
	s_branch .LBB0_606

.LBB0_613:
	s_add_u32 s24, s22, 0xfffc0080
	s_addc_u32 s25, s23, -1
	s_cmp_eq_u32 s49, 12
	s_cselect_b32 s27, s13, s25
	s_cselect_b32 s26, s41, s24
	s_cselect_b32 s25, s11, s48
	s_cselect_b32 s24, s46, s47
	s_and_b64 vcc, exec, s[6:7]
	s_cbranch_vccz .Lk64_trail_glu
	s_sub_u32 vcc_lo, s47, 0x80
	s_subb_u32 vcc_hi, s48, 0
	s_add_i32 m0, s28, 0x18000
	s_nop 0
	global_load_lds_dwordx4 v132, vcc
	s_add_i32 m0, s28, 0x1a000
	s_nop 0
	global_load_lds_dwordx4 v128, vcc
	s_add_u32 vcc_lo, vcc_lo, 0x10000
	s_addc_u32 vcc_hi, vcc_hi, 0
	s_add_i32 m0, s28, 0x19000
	s_nop 0
	global_load_lds_dwordx4 v132, vcc
	s_add_i32 m0, s28, 0x1b000
	s_nop 0
	global_load_lds_dwordx4 v128, vcc
	s_add_u32 vcc_lo, vcc_lo, 0x30000
	s_addc_u32 vcc_hi, vcc_hi, 0
	s_add_i32 m0, s28, 0x1c000
	s_nop 0
	global_load_lds_dwordx4 v132, vcc
	s_add_i32 m0, s28, 0x1e000
	s_nop 0
	global_load_lds_dwordx4 v128, vcc
	s_add_u32 vcc_lo, vcc_lo, 0x10000
	s_addc_u32 vcc_hi, vcc_hi, 0
	s_add_i32 m0, s28, 0x1d000
	s_nop 0
	global_load_lds_dwordx4 v132, vcc
	s_add_i32 m0, s28, 0x1f000
	s_nop 0
	global_load_lds_dwordx4 v128, vcc
	ds_read_b128 v[144:147], v151 offset:0
	ds_read_b128 v[154:157], v151 offset:1024
	ds_read_b128 v[158:161], v151 offset:2048
	ds_read_b128 v[162:165], v151 offset:3072
	ds_read_b128 v[166:169], v152 offset:0
	ds_read_b128 v[170:173], v152 offset:1024
	ds_read_b128 v[174:177], v152 offset:2048
	ds_read_b128 v[178:181], v152 offset:3072
	ds_read_b128 v[182:185], v153 offset:0
	ds_read_b128 v[186:189], v153 offset:1024
	ds_read_b128 v[190:193], v153 offset:2048
	ds_read_b128 v[194:197], v153 offset:3072
	ds_read_b128 v[198:201], v153 offset:4096
	ds_read_b128 v[202:205], v153 offset:5120
	ds_read_b128 v[206:209], v153 offset:6144
	ds_read_b128 v[210:213], v153 offset:7168
	ds_read_b128 v[220:223], v153 offset:16384
	ds_read_b128 v[224:227], v153 offset:17408
	ds_read_b128 v[228:231], v153 offset:18432
	ds_read_b128 v[232:235], v153 offset:19456
	ds_read_b128 v[236:239], v153 offset:20480
	ds_read_b128 v[240:243], v153 offset:21504
	ds_read_b128 v[244:247], v153 offset:22528
	ds_read_b128 v[248:251], v153 offset:23552
	s_nop 15
	s_nop 15
	s_waitcnt lgkmcnt(0)
	s_barrier
	s_setprio 1
	v_mfma_f32_16x16x32_bf16 v[124:127], v[144:147], v[182:185], v[124:127]
	v_mfma_f32_16x16x32_bf16 v[120:123], v[158:161], v[182:185], v[120:123]
	v_mfma_f32_16x16x32_bf16 v[108:111], v[144:147], v[190:193], v[108:111]
	v_mfma_f32_16x16x32_bf16 v[104:107], v[158:161], v[190:193], v[104:107]
	v_mfma_f32_16x16x32_bf16 v[92:95], v[144:147], v[198:201], v[92:95]
	v_mfma_f32_16x16x32_bf16 v[88:91], v[158:161], v[198:201], v[88:91]
	v_mfma_f32_16x16x32_bf16 v[76:79], v[144:147], v[206:209], v[76:79]
	v_mfma_f32_16x16x32_bf16 v[72:75], v[158:161], v[206:209], v[72:75]
	v_mfma_f32_16x16x32_bf16 v[124:127], v[154:157], v[186:189], v[124:127]
	v_mfma_f32_16x16x32_bf16 v[120:123], v[162:165], v[186:189], v[120:123]
	v_mfma_f32_16x16x32_bf16 v[108:111], v[154:157], v[194:197], v[108:111]
	v_mfma_f32_16x16x32_bf16 v[104:107], v[162:165], v[194:197], v[104:107]
	v_mfma_f32_16x16x32_bf16 v[92:95], v[154:157], v[202:205], v[92:95]
	v_mfma_f32_16x16x32_bf16 v[88:91], v[162:165], v[202:205], v[88:91]
	v_mfma_f32_16x16x32_bf16 v[76:79], v[154:157], v[210:213], v[76:79]
	v_mfma_f32_16x16x32_bf16 v[72:75], v[162:165], v[210:213], v[72:75]
	s_setprio 0
	s_setprio 1
	v_mfma_f32_16x16x32_bf16 v[116:119], v[166:169], v[182:185], v[116:119]
	v_mfma_f32_16x16x32_bf16 v[112:115], v[174:177], v[182:185], v[112:115]
	v_mfma_f32_16x16x32_bf16 v[100:103], v[166:169], v[190:193], v[100:103]
	v_mfma_f32_16x16x32_bf16 v[96:99], v[174:177], v[190:193], v[96:99]
	v_mfma_f32_16x16x32_bf16 v[84:87], v[166:169], v[198:201], v[84:87]
	v_mfma_f32_16x16x32_bf16 v[80:83], v[174:177], v[198:201], v[80:83]
	v_mfma_f32_16x16x32_bf16 v[68:71], v[166:169], v[206:209], v[68:71]
	v_mfma_f32_16x16x32_bf16 v[64:67], v[174:177], v[206:209], v[64:67]
	v_mfma_f32_16x16x32_bf16 v[116:119], v[170:173], v[186:189], v[116:119]
	v_mfma_f32_16x16x32_bf16 v[112:115], v[178:181], v[186:189], v[112:115]
	v_mfma_f32_16x16x32_bf16 v[100:103], v[170:173], v[194:197], v[100:103]
	v_mfma_f32_16x16x32_bf16 v[96:99], v[178:181], v[194:197], v[96:99]
	v_mfma_f32_16x16x32_bf16 v[84:87], v[170:173], v[202:205], v[84:87]
	v_mfma_f32_16x16x32_bf16 v[80:83], v[178:181], v[202:205], v[80:83]
	v_mfma_f32_16x16x32_bf16 v[68:71], v[170:173], v[210:213], v[68:71]
	v_mfma_f32_16x16x32_bf16 v[64:67], v[178:181], v[210:213], v[64:67]
	s_setprio 0
	s_setprio 1
	v_mfma_f32_16x16x32_bf16 v[60:63], v[144:147], v[220:223], v[60:63]
	v_mfma_f32_16x16x32_bf16 v[56:59], v[158:161], v[220:223], v[56:59]
	v_mfma_f32_16x16x32_bf16 v[44:47], v[144:147], v[228:231], v[44:47]
	v_mfma_f32_16x16x32_bf16 v[40:43], v[158:161], v[228:231], v[40:43]
	v_mfma_f32_16x16x32_bf16 v[28:31], v[144:147], v[236:239], v[28:31]
	v_mfma_f32_16x16x32_bf16 v[24:27], v[158:161], v[236:239], v[24:27]
	v_mfma_f32_16x16x32_bf16 v[12:15], v[144:147], v[244:247], v[12:15]
	v_mfma_f32_16x16x32_bf16 v[8:11], v[158:161], v[244:247], v[8:11]
	v_mfma_f32_16x16x32_bf16 v[60:63], v[154:157], v[224:227], v[60:63]
	v_mfma_f32_16x16x32_bf16 v[56:59], v[162:165], v[224:227], v[56:59]
	v_mfma_f32_16x16x32_bf16 v[44:47], v[154:157], v[232:235], v[44:47]
	v_mfma_f32_16x16x32_bf16 v[40:43], v[162:165], v[232:235], v[40:43]
	v_mfma_f32_16x16x32_bf16 v[28:31], v[154:157], v[240:243], v[28:31]
	v_mfma_f32_16x16x32_bf16 v[24:27], v[162:165], v[240:243], v[24:27]
	v_mfma_f32_16x16x32_bf16 v[12:15], v[154:157], v[248:251], v[12:15]
	v_mfma_f32_16x16x32_bf16 v[8:11], v[162:165], v[248:251], v[8:11]
	s_setprio 0
	s_setprio 1
	v_mfma_f32_16x16x32_bf16 v[52:55], v[166:169], v[220:223], v[52:55]
	v_mfma_f32_16x16x32_bf16 v[48:51], v[174:177], v[220:223], v[48:51]
	v_mfma_f32_16x16x32_bf16 v[36:39], v[166:169], v[228:231], v[36:39]
	v_mfma_f32_16x16x32_bf16 v[32:35], v[174:177], v[228:231], v[32:35]
	v_mfma_f32_16x16x32_bf16 v[20:23], v[166:169], v[236:239], v[20:23]
	v_mfma_f32_16x16x32_bf16 v[16:19], v[174:177], v[236:239], v[16:19]
	v_mfma_f32_16x16x32_bf16 v[4:7], v[166:169], v[244:247], v[4:7]
	v_mfma_f32_16x16x32_bf16 v[0:3], v[174:177], v[244:247], v[0:3]
	v_mfma_f32_16x16x32_bf16 v[52:55], v[170:173], v[224:227], v[52:55]
	v_mfma_f32_16x16x32_bf16 v[48:51], v[178:181], v[224:227], v[48:51]
	v_mfma_f32_16x16x32_bf16 v[36:39], v[170:173], v[232:235], v[36:39]
	v_mfma_f32_16x16x32_bf16 v[32:35], v[178:181], v[232:235], v[32:35]
	v_mfma_f32_16x16x32_bf16 v[20:23], v[170:173], v[240:243], v[20:23]
	v_mfma_f32_16x16x32_bf16 v[16:19], v[178:181], v[240:243], v[16:19]
	v_mfma_f32_16x16x32_bf16 v[4:7], v[170:173], v[248:251], v[4:7]
	v_mfma_f32_16x16x32_bf16 v[0:3], v[178:181], v[248:251], v[0:3]
	s_setprio 0
	s_waitcnt vmcnt(0)
	s_barrier
	s_add_u32 vcc_lo, s24, 0x0
	s_addc_u32 vcc_hi, s25, 0
	s_add_i32 m0, s28, 0x10000
	s_nop 0
	global_load_lds_dwordx4 v132, vcc
	s_add_i32 m0, s28, 0x12000
	s_nop 0
	global_load_lds_dwordx4 v128, vcc
	s_add_u32 vcc_lo, vcc_lo, 0x10000
	s_addc_u32 vcc_hi, vcc_hi, 0
	s_add_i32 m0, s28, 0x11000
	s_nop 0
	global_load_lds_dwordx4 v132, vcc
	s_add_i32 m0, s28, 0x13000
	s_nop 0
	global_load_lds_dwordx4 v128, vcc
	s_add_u32 vcc_lo, vcc_lo, 0x30000
	s_addc_u32 vcc_hi, vcc_hi, 0
	s_add_i32 m0, s28, 0x14000
	s_nop 0
	global_load_lds_dwordx4 v132, vcc
	s_add_i32 m0, s28, 0x16000
	s_nop 0
	global_load_lds_dwordx4 v128, vcc
	s_add_u32 vcc_lo, vcc_lo, 0x10000
	s_addc_u32 vcc_hi, vcc_hi, 0
	s_add_i32 m0, s28, 0x15000
	s_nop 0
	global_load_lds_dwordx4 v132, vcc
	s_add_i32 m0, s28, 0x17000
	s_nop 0
	global_load_lds_dwordx4 v128, vcc
	ds_read_b128 v[144:147], v151 offset:32768
	ds_read_b128 v[154:157], v151 offset:33792
	ds_read_b128 v[158:161], v151 offset:34816
	ds_read_b128 v[162:165], v151 offset:35840
	ds_read_b128 v[166:169], v152 offset:32768
	ds_read_b128 v[170:173], v152 offset:33792
	ds_read_b128 v[174:177], v152 offset:34816
	ds_read_b128 v[178:181], v152 offset:35840
	ds_read_b128 v[182:185], v153 offset:32768
	ds_read_b128 v[186:189], v153 offset:33792
	ds_read_b128 v[190:193], v153 offset:34816
	ds_read_b128 v[194:197], v153 offset:35840
	ds_read_b128 v[198:201], v153 offset:36864
	ds_read_b128 v[202:205], v153 offset:37888
	ds_read_b128 v[206:209], v153 offset:38912
	ds_read_b128 v[210:213], v153 offset:39936
	ds_read_b128 v[220:223], v153 offset:49152
	ds_read_b128 v[224:227], v153 offset:50176
	ds_read_b128 v[228:231], v153 offset:51200
	ds_read_b128 v[232:235], v153 offset:52224
	ds_read_b128 v[236:239], v153 offset:53248
	ds_read_b128 v[240:243], v153 offset:54272
	ds_read_b128 v[244:247], v153 offset:55296
	ds_read_b128 v[248:251], v153 offset:56320
	s_nop 15
	s_nop 15
	s_waitcnt lgkmcnt(0)
	s_barrier
	s_setprio 1
	v_mfma_f32_16x16x32_bf16 v[124:127], v[144:147], v[182:185], v[124:127]
	v_mfma_f32_16x16x32_bf16 v[120:123], v[158:161], v[182:185], v[120:123]
	v_mfma_f32_16x16x32_bf16 v[108:111], v[144:147], v[190:193], v[108:111]
	v_mfma_f32_16x16x32_bf16 v[104:107], v[158:161], v[190:193], v[104:107]
	v_mfma_f32_16x16x32_bf16 v[92:95], v[144:147], v[198:201], v[92:95]
	v_mfma_f32_16x16x32_bf16 v[88:91], v[158:161], v[198:201], v[88:91]
	v_mfma_f32_16x16x32_bf16 v[76:79], v[144:147], v[206:209], v[76:79]
	v_mfma_f32_16x16x32_bf16 v[72:75], v[158:161], v[206:209], v[72:75]
	v_mfma_f32_16x16x32_bf16 v[124:127], v[154:157], v[186:189], v[124:127]
	v_mfma_f32_16x16x32_bf16 v[120:123], v[162:165], v[186:189], v[120:123]
	v_mfma_f32_16x16x32_bf16 v[108:111], v[154:157], v[194:197], v[108:111]
	v_mfma_f32_16x16x32_bf16 v[104:107], v[162:165], v[194:197], v[104:107]
	v_mfma_f32_16x16x32_bf16 v[92:95], v[154:157], v[202:205], v[92:95]
	v_mfma_f32_16x16x32_bf16 v[88:91], v[162:165], v[202:205], v[88:91]
	v_mfma_f32_16x16x32_bf16 v[76:79], v[154:157], v[210:213], v[76:79]
	v_mfma_f32_16x16x32_bf16 v[72:75], v[162:165], v[210:213], v[72:75]
	s_setprio 0
	s_setprio 1
	v_mfma_f32_16x16x32_bf16 v[116:119], v[166:169], v[182:185], v[116:119]
	v_mfma_f32_16x16x32_bf16 v[112:115], v[174:177], v[182:185], v[112:115]
	v_mfma_f32_16x16x32_bf16 v[100:103], v[166:169], v[190:193], v[100:103]
	v_mfma_f32_16x16x32_bf16 v[96:99], v[174:177], v[190:193], v[96:99]
	v_mfma_f32_16x16x32_bf16 v[84:87], v[166:169], v[198:201], v[84:87]
	v_mfma_f32_16x16x32_bf16 v[80:83], v[174:177], v[198:201], v[80:83]
	v_mfma_f32_16x16x32_bf16 v[68:71], v[166:169], v[206:209], v[68:71]
	v_mfma_f32_16x16x32_bf16 v[64:67], v[174:177], v[206:209], v[64:67]
	v_mfma_f32_16x16x32_bf16 v[116:119], v[170:173], v[186:189], v[116:119]
	v_mfma_f32_16x16x32_bf16 v[112:115], v[178:181], v[186:189], v[112:115]
	v_mfma_f32_16x16x32_bf16 v[100:103], v[170:173], v[194:197], v[100:103]
	v_mfma_f32_16x16x32_bf16 v[96:99], v[178:181], v[194:197], v[96:99]
	v_mfma_f32_16x16x32_bf16 v[84:87], v[170:173], v[202:205], v[84:87]
	v_mfma_f32_16x16x32_bf16 v[80:83], v[178:181], v[202:205], v[80:83]
	v_mfma_f32_16x16x32_bf16 v[68:71], v[170:173], v[210:213], v[68:71]
	v_mfma_f32_16x16x32_bf16 v[64:67], v[178:181], v[210:213], v[64:67]
	s_setprio 0
	s_setprio 1
	v_mfma_f32_16x16x32_bf16 v[60:63], v[144:147], v[220:223], v[60:63]
	v_mfma_f32_16x16x32_bf16 v[56:59], v[158:161], v[220:223], v[56:59]
	v_mfma_f32_16x16x32_bf16 v[44:47], v[144:147], v[228:231], v[44:47]
	v_mfma_f32_16x16x32_bf16 v[40:43], v[158:161], v[228:231], v[40:43]
	v_mfma_f32_16x16x32_bf16 v[28:31], v[144:147], v[236:239], v[28:31]
	v_mfma_f32_16x16x32_bf16 v[24:27], v[158:161], v[236:239], v[24:27]
	v_mfma_f32_16x16x32_bf16 v[12:15], v[144:147], v[244:247], v[12:15]
	v_mfma_f32_16x16x32_bf16 v[8:11], v[158:161], v[244:247], v[8:11]
	v_mfma_f32_16x16x32_bf16 v[60:63], v[154:157], v[224:227], v[60:63]
	v_mfma_f32_16x16x32_bf16 v[56:59], v[162:165], v[224:227], v[56:59]
	v_mfma_f32_16x16x32_bf16 v[44:47], v[154:157], v[232:235], v[44:47]
	v_mfma_f32_16x16x32_bf16 v[40:43], v[162:165], v[232:235], v[40:43]
	v_mfma_f32_16x16x32_bf16 v[28:31], v[154:157], v[240:243], v[28:31]
	v_mfma_f32_16x16x32_bf16 v[24:27], v[162:165], v[240:243], v[24:27]
	v_mfma_f32_16x16x32_bf16 v[12:15], v[154:157], v[248:251], v[12:15]
	v_mfma_f32_16x16x32_bf16 v[8:11], v[162:165], v[248:251], v[8:11]
	s_setprio 0
	s_setprio 1
	v_mfma_f32_16x16x32_bf16 v[52:55], v[166:169], v[220:223], v[52:55]
	v_mfma_f32_16x16x32_bf16 v[48:51], v[174:177], v[220:223], v[48:51]
	v_mfma_f32_16x16x32_bf16 v[36:39], v[166:169], v[228:231], v[36:39]
	v_mfma_f32_16x16x32_bf16 v[32:35], v[174:177], v[228:231], v[32:35]
	v_mfma_f32_16x16x32_bf16 v[20:23], v[166:169], v[236:239], v[20:23]
	v_mfma_f32_16x16x32_bf16 v[16:19], v[174:177], v[236:239], v[16:19]
	v_mfma_f32_16x16x32_bf16 v[4:7], v[166:169], v[244:247], v[4:7]
	v_mfma_f32_16x16x32_bf16 v[0:3], v[174:177], v[244:247], v[0:3]
	v_mfma_f32_16x16x32_bf16 v[52:55], v[170:173], v[224:227], v[52:55]
	v_mfma_f32_16x16x32_bf16 v[48:51], v[178:181], v[224:227], v[48:51]
	v_mfma_f32_16x16x32_bf16 v[36:39], v[170:173], v[232:235], v[36:39]
	v_mfma_f32_16x16x32_bf16 v[32:35], v[178:181], v[232:235], v[32:35]
	v_mfma_f32_16x16x32_bf16 v[20:23], v[170:173], v[240:243], v[20:23]
	v_mfma_f32_16x16x32_bf16 v[16:19], v[178:181], v[240:243], v[16:19]
	v_mfma_f32_16x16x32_bf16 v[4:7], v[170:173], v[248:251], v[4:7]
	v_mfma_f32_16x16x32_bf16 v[0:3], v[178:181], v[248:251], v[0:3]
	s_setprio 0
	s_waitcnt vmcnt(0)
	s_barrier
	s_add_i32 s49, s49, 2
	s_add_u32 s22, s22, 0x100
	s_addc_u32 s23, s23, 0
	s_add_u32 s47, s47, 0x100
	s_addc_u32 s48, s48, 0
	s_cmp_gt_u32 s49, 13
	s_cbranch_scc0 .LBB0_613
	s_branch .Lk64_done_glu
.Lk64_trail_glu:
	s_sub_u32 vcc_lo, s22, 0x40000
	s_subb_u32 vcc_hi, s23, 0
	s_add_i32 m0, s28, 0xa000
	s_nop 0
	global_load_lds_dwordx4 v130, vcc
	s_add_u32 vcc_lo, vcc_lo, 0x10000
	s_addc_u32 vcc_hi, vcc_hi, 0
	s_add_i32 m0, s28, 0x9000
	s_nop 0
	global_load_lds_dwordx4 v134, vcc
	s_add_u32 vcc_lo, vcc_lo, 0x30000
	s_addc_u32 vcc_hi, vcc_hi, 0
	s_add_i32 m0, s28, 0xe000
	s_nop 0
	global_load_lds_dwordx4 v130, vcc
	s_add_u32 vcc_lo, vcc_lo, 0x10000
	s_addc_u32 vcc_hi, vcc_hi, 0
	s_add_i32 m0, s28, 0xd000
	s_nop 0
	global_load_lds_dwordx4 v134, vcc
	s_add_u32 vcc_lo, s26, 0x0
	s_addc_u32 vcc_hi, s27, 0
	s_mov_b32 m0, s28
	s_nop 0
	global_load_lds_dwordx4 v134, vcc
	s_sub_u32 vcc_lo, vcc_lo, 0x10000
	s_subb_u32 vcc_hi, vcc_hi, 0
	s_sub_i32 m0, s28, 0x1000
	s_nop 0
	global_load_lds_dwordx4 v134, vcc
	s_add_u32 vcc_lo, vcc_lo, 0x50000
	s_addc_u32 vcc_hi, vcc_hi, 0
	s_add_i32 m0, s28, 0x4000
	s_nop 0
	global_load_lds_dwordx4 v134, vcc
	s_sub_u32 vcc_lo, vcc_lo, 0x10000
	s_subb_u32 vcc_hi, vcc_hi, 0
	s_add_i32 m0, s28, 0x3000
	s_nop 0
	global_load_lds_dwordx4 v134, vcc
	ds_read_b128 v[144:147], v151 offset:0
	ds_read_b128 v[154:157], v151 offset:1024
	ds_read_b128 v[158:161], v151 offset:2048
	ds_read_b128 v[162:165], v151 offset:3072
	ds_read_b128 v[166:169], v152 offset:0
	ds_read_b128 v[170:173], v152 offset:1024
	ds_read_b128 v[174:177], v152 offset:2048
	ds_read_b128 v[178:181], v152 offset:3072
	ds_read_b128 v[182:185], v153 offset:0
	ds_read_b128 v[186:189], v153 offset:1024
	ds_read_b128 v[190:193], v153 offset:2048
	ds_read_b128 v[194:197], v153 offset:3072
	ds_read_b128 v[198:201], v153 offset:4096
	ds_read_b128 v[202:205], v153 offset:5120
	ds_read_b128 v[206:209], v153 offset:6144
	ds_read_b128 v[210:213], v153 offset:7168
	ds_read_b128 v[220:223], v153 offset:16384
	ds_read_b128 v[224:227], v153 offset:17408
	ds_read_b128 v[228:231], v153 offset:18432
	ds_read_b128 v[232:235], v153 offset:19456
	ds_read_b128 v[236:239], v153 offset:20480
	ds_read_b128 v[240:243], v153 offset:21504
	ds_read_b128 v[244:247], v153 offset:22528
	ds_read_b128 v[248:251], v153 offset:23552
	s_nop 15
	s_nop 15
	s_waitcnt lgkmcnt(0)
	s_barrier
	s_setprio 1
	v_mfma_f32_16x16x32_bf16 v[124:127], v[144:147], v[182:185], v[124:127]
	v_mfma_f32_16x16x32_bf16 v[120:123], v[158:161], v[182:185], v[120:123]
	v_mfma_f32_16x16x32_bf16 v[108:111], v[144:147], v[190:193], v[108:111]
	v_mfma_f32_16x16x32_bf16 v[104:107], v[158:161], v[190:193], v[104:107]
	v_mfma_f32_16x16x32_bf16 v[92:95], v[144:147], v[198:201], v[92:95]
	v_mfma_f32_16x16x32_bf16 v[88:91], v[158:161], v[198:201], v[88:91]
	v_mfma_f32_16x16x32_bf16 v[76:79], v[144:147], v[206:209], v[76:79]
	v_mfma_f32_16x16x32_bf16 v[72:75], v[158:161], v[206:209], v[72:75]
	v_mfma_f32_16x16x32_bf16 v[124:127], v[154:157], v[186:189], v[124:127]
	v_mfma_f32_16x16x32_bf16 v[120:123], v[162:165], v[186:189], v[120:123]
	v_mfma_f32_16x16x32_bf16 v[108:111], v[154:157], v[194:197], v[108:111]
	v_mfma_f32_16x16x32_bf16 v[104:107], v[162:165], v[194:197], v[104:107]
	v_mfma_f32_16x16x32_bf16 v[92:95], v[154:157], v[202:205], v[92:95]
	v_mfma_f32_16x16x32_bf16 v[88:91], v[162:165], v[202:205], v[88:91]
	v_mfma_f32_16x16x32_bf16 v[76:79], v[154:157], v[210:213], v[76:79]
	v_mfma_f32_16x16x32_bf16 v[72:75], v[162:165], v[210:213], v[72:75]
	s_setprio 0
	s_setprio 1
	v_mfma_f32_16x16x32_bf16 v[116:119], v[166:169], v[182:185], v[116:119]
	v_mfma_f32_16x16x32_bf16 v[112:115], v[174:177], v[182:185], v[112:115]
	v_mfma_f32_16x16x32_bf16 v[100:103], v[166:169], v[190:193], v[100:103]
	v_mfma_f32_16x16x32_bf16 v[96:99], v[174:177], v[190:193], v[96:99]
	v_mfma_f32_16x16x32_bf16 v[84:87], v[166:169], v[198:201], v[84:87]
	v_mfma_f32_16x16x32_bf16 v[80:83], v[174:177], v[198:201], v[80:83]
	v_mfma_f32_16x16x32_bf16 v[68:71], v[166:169], v[206:209], v[68:71]
	v_mfma_f32_16x16x32_bf16 v[64:67], v[174:177], v[206:209], v[64:67]
	v_mfma_f32_16x16x32_bf16 v[116:119], v[170:173], v[186:189], v[116:119]
	v_mfma_f32_16x16x32_bf16 v[112:115], v[178:181], v[186:189], v[112:115]
	v_mfma_f32_16x16x32_bf16 v[100:103], v[170:173], v[194:197], v[100:103]
	v_mfma_f32_16x16x32_bf16 v[96:99], v[178:181], v[194:197], v[96:99]
	v_mfma_f32_16x16x32_bf16 v[84:87], v[170:173], v[202:205], v[84:87]
	v_mfma_f32_16x16x32_bf16 v[80:83], v[178:181], v[202:205], v[80:83]
	v_mfma_f32_16x16x32_bf16 v[68:71], v[170:173], v[210:213], v[68:71]
	v_mfma_f32_16x16x32_bf16 v[64:67], v[178:181], v[210:213], v[64:67]
	s_setprio 0
	s_setprio 1
	v_mfma_f32_16x16x32_bf16 v[60:63], v[144:147], v[220:223], v[60:63]
	v_mfma_f32_16x16x32_bf16 v[56:59], v[158:161], v[220:223], v[56:59]
	v_mfma_f32_16x16x32_bf16 v[44:47], v[144:147], v[228:231], v[44:47]
	v_mfma_f32_16x16x32_bf16 v[40:43], v[158:161], v[228:231], v[40:43]
	v_mfma_f32_16x16x32_bf16 v[28:31], v[144:147], v[236:239], v[28:31]
	v_mfma_f32_16x16x32_bf16 v[24:27], v[158:161], v[236:239], v[24:27]
	v_mfma_f32_16x16x32_bf16 v[12:15], v[144:147], v[244:247], v[12:15]
	v_mfma_f32_16x16x32_bf16 v[8:11], v[158:161], v[244:247], v[8:11]
	v_mfma_f32_16x16x32_bf16 v[60:63], v[154:157], v[224:227], v[60:63]
	v_mfma_f32_16x16x32_bf16 v[56:59], v[162:165], v[224:227], v[56:59]
	v_mfma_f32_16x16x32_bf16 v[44:47], v[154:157], v[232:235], v[44:47]
	v_mfma_f32_16x16x32_bf16 v[40:43], v[162:165], v[232:235], v[40:43]
	v_mfma_f32_16x16x32_bf16 v[28:31], v[154:157], v[240:243], v[28:31]
	v_mfma_f32_16x16x32_bf16 v[24:27], v[162:165], v[240:243], v[24:27]
	v_mfma_f32_16x16x32_bf16 v[12:15], v[154:157], v[248:251], v[12:15]
	v_mfma_f32_16x16x32_bf16 v[8:11], v[162:165], v[248:251], v[8:11]
	s_setprio 0
	s_setprio 1
	v_mfma_f32_16x16x32_bf16 v[52:55], v[166:169], v[220:223], v[52:55]
	v_mfma_f32_16x16x32_bf16 v[48:51], v[174:177], v[220:223], v[48:51]
	v_mfma_f32_16x16x32_bf16 v[36:39], v[166:169], v[228:231], v[36:39]
	v_mfma_f32_16x16x32_bf16 v[32:35], v[174:177], v[228:231], v[32:35]
	v_mfma_f32_16x16x32_bf16 v[20:23], v[166:169], v[236:239], v[20:23]
	v_mfma_f32_16x16x32_bf16 v[16:19], v[174:177], v[236:239], v[16:19]
	v_mfma_f32_16x16x32_bf16 v[4:7], v[166:169], v[244:247], v[4:7]
	v_mfma_f32_16x16x32_bf16 v[0:3], v[174:177], v[244:247], v[0:3]
	v_mfma_f32_16x16x32_bf16 v[52:55], v[170:173], v[224:227], v[52:55]
	v_mfma_f32_16x16x32_bf16 v[48:51], v[178:181], v[224:227], v[48:51]
	v_mfma_f32_16x16x32_bf16 v[36:39], v[170:173], v[232:235], v[36:39]
	v_mfma_f32_16x16x32_bf16 v[32:35], v[178:181], v[232:235], v[32:35]
	v_mfma_f32_16x16x32_bf16 v[20:23], v[170:173], v[240:243], v[20:23]
	v_mfma_f32_16x16x32_bf16 v[16:19], v[178:181], v[240:243], v[16:19]
	v_mfma_f32_16x16x32_bf16 v[4:7], v[170:173], v[248:251], v[4:7]
	v_mfma_f32_16x16x32_bf16 v[0:3], v[178:181], v[248:251], v[0:3]
	s_setprio 0
	s_waitcnt vmcnt(0)
	s_barrier
	s_add_u32 vcc_lo, s26, 0x0
	s_addc_u32 vcc_hi, s27, 0
	s_add_i32 m0, s28, 0x2000
	s_nop 0
	global_load_lds_dwordx4 v130, vcc
	s_add_u32 vcc_lo, vcc_lo, 0x10000
	s_addc_u32 vcc_hi, vcc_hi, 0
	s_add_i32 m0, s28, 0x1000
	s_nop 0
	global_load_lds_dwordx4 v134, vcc
	s_add_u32 vcc_lo, vcc_lo, 0x30000
	s_addc_u32 vcc_hi, vcc_hi, 0
	s_add_i32 m0, s28, 0x6000
	s_nop 0
	global_load_lds_dwordx4 v130, vcc
	s_add_u32 vcc_lo, vcc_lo, 0x10000
	s_addc_u32 vcc_hi, vcc_hi, 0
	s_add_i32 m0, s28, 0x5000
	s_nop 0
	global_load_lds_dwordx4 v134, vcc
	s_add_u32 vcc_lo, s26, 0x80
	s_addc_u32 vcc_hi, s27, 0
	s_add_i32 m0, s28, 0x8000
	s_nop 0
	global_load_lds_dwordx4 v134, vcc
	s_sub_u32 vcc_lo, vcc_lo, 0x10000
	s_subb_u32 vcc_hi, vcc_hi, 0
	s_add_i32 m0, s28, 0x7000
	s_nop 0
	global_load_lds_dwordx4 v134, vcc
	s_add_u32 vcc_lo, vcc_lo, 0x50000
	s_addc_u32 vcc_hi, vcc_hi, 0
	s_add_i32 m0, s28, 0xc000
	s_nop 0
	global_load_lds_dwordx4 v134, vcc
	s_sub_u32 vcc_lo, vcc_lo, 0x10000
	s_subb_u32 vcc_hi, vcc_hi, 0
	s_add_i32 m0, s28, 0xb000
	s_nop 0
	global_load_lds_dwordx4 v134, vcc
	ds_read_b128 v[144:147], v151 offset:32768
	ds_read_b128 v[154:157], v151 offset:33792
	ds_read_b128 v[158:161], v151 offset:34816
	ds_read_b128 v[162:165], v151 offset:35840
	ds_read_b128 v[166:169], v152 offset:32768
	ds_read_b128 v[170:173], v152 offset:33792
	ds_read_b128 v[174:177], v152 offset:34816
	ds_read_b128 v[178:181], v152 offset:35840
	ds_read_b128 v[182:185], v153 offset:32768
	ds_read_b128 v[186:189], v153 offset:33792
	ds_read_b128 v[190:193], v153 offset:34816
	ds_read_b128 v[194:197], v153 offset:35840
	ds_read_b128 v[198:201], v153 offset:36864
	ds_read_b128 v[202:205], v153 offset:37888
	ds_read_b128 v[206:209], v153 offset:38912
	ds_read_b128 v[210:213], v153 offset:39936
	ds_read_b128 v[220:223], v153 offset:49152
	ds_read_b128 v[224:227], v153 offset:50176
	ds_read_b128 v[228:231], v153 offset:51200
	ds_read_b128 v[232:235], v153 offset:52224
	ds_read_b128 v[236:239], v153 offset:53248
	ds_read_b128 v[240:243], v153 offset:54272
	ds_read_b128 v[244:247], v153 offset:55296
	ds_read_b128 v[248:251], v153 offset:56320
	s_nop 15
	s_nop 15
	s_waitcnt lgkmcnt(0)
	s_barrier
	s_setprio 1
	v_mfma_f32_16x16x32_bf16 v[124:127], v[144:147], v[182:185], v[124:127]
	v_mfma_f32_16x16x32_bf16 v[120:123], v[158:161], v[182:185], v[120:123]
	v_mfma_f32_16x16x32_bf16 v[108:111], v[144:147], v[190:193], v[108:111]
	v_mfma_f32_16x16x32_bf16 v[104:107], v[158:161], v[190:193], v[104:107]
	v_mfma_f32_16x16x32_bf16 v[92:95], v[144:147], v[198:201], v[92:95]
	v_mfma_f32_16x16x32_bf16 v[88:91], v[158:161], v[198:201], v[88:91]
	v_mfma_f32_16x16x32_bf16 v[76:79], v[144:147], v[206:209], v[76:79]
	v_mfma_f32_16x16x32_bf16 v[72:75], v[158:161], v[206:209], v[72:75]
	v_mfma_f32_16x16x32_bf16 v[124:127], v[154:157], v[186:189], v[124:127]
	v_mfma_f32_16x16x32_bf16 v[120:123], v[162:165], v[186:189], v[120:123]
	v_mfma_f32_16x16x32_bf16 v[108:111], v[154:157], v[194:197], v[108:111]
	v_mfma_f32_16x16x32_bf16 v[104:107], v[162:165], v[194:197], v[104:107]
	v_mfma_f32_16x16x32_bf16 v[92:95], v[154:157], v[202:205], v[92:95]
	v_mfma_f32_16x16x32_bf16 v[88:91], v[162:165], v[202:205], v[88:91]
	v_mfma_f32_16x16x32_bf16 v[76:79], v[154:157], v[210:213], v[76:79]
	v_mfma_f32_16x16x32_bf16 v[72:75], v[162:165], v[210:213], v[72:75]
	s_setprio 0
	s_setprio 1
	v_mfma_f32_16x16x32_bf16 v[116:119], v[166:169], v[182:185], v[116:119]
	v_mfma_f32_16x16x32_bf16 v[112:115], v[174:177], v[182:185], v[112:115]
	v_mfma_f32_16x16x32_bf16 v[100:103], v[166:169], v[190:193], v[100:103]
	v_mfma_f32_16x16x32_bf16 v[96:99], v[174:177], v[190:193], v[96:99]
	v_mfma_f32_16x16x32_bf16 v[84:87], v[166:169], v[198:201], v[84:87]
	v_mfma_f32_16x16x32_bf16 v[80:83], v[174:177], v[198:201], v[80:83]
	v_mfma_f32_16x16x32_bf16 v[68:71], v[166:169], v[206:209], v[68:71]
	v_mfma_f32_16x16x32_bf16 v[64:67], v[174:177], v[206:209], v[64:67]
	v_mfma_f32_16x16x32_bf16 v[116:119], v[170:173], v[186:189], v[116:119]
	v_mfma_f32_16x16x32_bf16 v[112:115], v[178:181], v[186:189], v[112:115]
	v_mfma_f32_16x16x32_bf16 v[100:103], v[170:173], v[194:197], v[100:103]
	v_mfma_f32_16x16x32_bf16 v[96:99], v[178:181], v[194:197], v[96:99]
	v_mfma_f32_16x16x32_bf16 v[84:87], v[170:173], v[202:205], v[84:87]
	v_mfma_f32_16x16x32_bf16 v[80:83], v[178:181], v[202:205], v[80:83]
	v_mfma_f32_16x16x32_bf16 v[68:71], v[170:173], v[210:213], v[68:71]
	v_mfma_f32_16x16x32_bf16 v[64:67], v[178:181], v[210:213], v[64:67]
	s_setprio 0
	s_setprio 1
	v_mfma_f32_16x16x32_bf16 v[60:63], v[144:147], v[220:223], v[60:63]
	v_mfma_f32_16x16x32_bf16 v[56:59], v[158:161], v[220:223], v[56:59]
	v_mfma_f32_16x16x32_bf16 v[44:47], v[144:147], v[228:231], v[44:47]
	v_mfma_f32_16x16x32_bf16 v[40:43], v[158:161], v[228:231], v[40:43]
	v_mfma_f32_16x16x32_bf16 v[28:31], v[144:147], v[236:239], v[28:31]
	v_mfma_f32_16x16x32_bf16 v[24:27], v[158:161], v[236:239], v[24:27]
	v_mfma_f32_16x16x32_bf16 v[12:15], v[144:147], v[244:247], v[12:15]
	v_mfma_f32_16x16x32_bf16 v[8:11], v[158:161], v[244:247], v[8:11]
	v_mfma_f32_16x16x32_bf16 v[60:63], v[154:157], v[224:227], v[60:63]
	v_mfma_f32_16x16x32_bf16 v[56:59], v[162:165], v[224:227], v[56:59]
	v_mfma_f32_16x16x32_bf16 v[44:47], v[154:157], v[232:235], v[44:47]
	v_mfma_f32_16x16x32_bf16 v[40:43], v[162:165], v[232:235], v[40:43]
	v_mfma_f32_16x16x32_bf16 v[28:31], v[154:157], v[240:243], v[28:31]
	v_mfma_f32_16x16x32_bf16 v[24:27], v[162:165], v[240:243], v[24:27]
	v_mfma_f32_16x16x32_bf16 v[12:15], v[154:157], v[248:251], v[12:15]
	v_mfma_f32_16x16x32_bf16 v[8:11], v[162:165], v[248:251], v[8:11]
	s_setprio 0
	s_setprio 1
	v_mfma_f32_16x16x32_bf16 v[52:55], v[166:169], v[220:223], v[52:55]
	v_mfma_f32_16x16x32_bf16 v[48:51], v[174:177], v[220:223], v[48:51]
	v_mfma_f32_16x16x32_bf16 v[36:39], v[166:169], v[228:231], v[36:39]
	v_mfma_f32_16x16x32_bf16 v[32:35], v[174:177], v[228:231], v[32:35]
	v_mfma_f32_16x16x32_bf16 v[20:23], v[166:169], v[236:239], v[20:23]
	v_mfma_f32_16x16x32_bf16 v[16:19], v[174:177], v[236:239], v[16:19]
	v_mfma_f32_16x16x32_bf16 v[4:7], v[166:169], v[244:247], v[4:7]
	v_mfma_f32_16x16x32_bf16 v[0:3], v[174:177], v[244:247], v[0:3]
	v_mfma_f32_16x16x32_bf16 v[52:55], v[170:173], v[224:227], v[52:55]
	v_mfma_f32_16x16x32_bf16 v[48:51], v[178:181], v[224:227], v[48:51]
	v_mfma_f32_16x16x32_bf16 v[36:39], v[170:173], v[232:235], v[36:39]
	v_mfma_f32_16x16x32_bf16 v[32:35], v[178:181], v[232:235], v[32:35]
	v_mfma_f32_16x16x32_bf16 v[20:23], v[170:173], v[240:243], v[20:23]
	v_mfma_f32_16x16x32_bf16 v[16:19], v[178:181], v[240:243], v[16:19]
	v_mfma_f32_16x16x32_bf16 v[4:7], v[170:173], v[248:251], v[4:7]
	v_mfma_f32_16x16x32_bf16 v[0:3], v[178:181], v[248:251], v[0:3]
	s_setprio 0
	s_waitcnt vmcnt(0)
	s_barrier
	s_add_i32 s49, s49, 2
	s_add_u32 s22, s22, 0x100
	s_addc_u32 s23, s23, 0
	s_add_u32 s47, s47, 0x100
	s_addc_u32 s48, s48, 0
	s_cmp_gt_u32 s49, 13
	s_cbranch_scc0 .LBB0_613
.Lk64_done_glu:
	s_and_b64 vcc, exec, s[6:7]
	s_cbranch_vccz .LBB0_616
	s_barrier

.LBB0_676:
	v_lshrrev_b32_e32 v16, 1, v14
	v_and_b32_e32 v16, 24, v16
	v_and_b32_e32 v15, 15, v14
	v_lshlrev_b32_e32 v17, 1, v16
	v_lshlrev_b32_e32 v14, 2, v14
	s_sext_i32_i8 s11, s4
	v_lshl_or_b32 v148, s7, 6, v15
	v_lshl_or_b32 v15, v15, 6, v17
	s_lshl_b32 s4, s7, 13
	v_and_b32_e32 v14, 32, v14
	v_bitop3_b32 v17, v15, s4, v14 bitop3:0xde
	s_lshl_b32 s4, s6, 5
	s_mov_b64 s[20:21], 0x80
	s_and_b32 s22, s4, 0x60
	s_add_i32 m0, s36, 0x18000
	v_lshl_add_u64 v[6:7], v[6:7], 0, s[20:21]
	s_lshl_b32 s4, s22, 7
	s_waitcnt vmcnt(0)
	s_barrier
	s_add_u32 vcc_lo, s12, 0x40080
	s_addc_u32 vcc_hi, s13, 0
	s_add_i32 m0, s36, 0xc000
	s_nop 0
	global_load_lds_dwordx4 v134, vcc
	s_add_i32 m0, s36, 0x18000
	s_nop 0
	global_load_lds_dwordx4 v[6:7], off
	v_lshl_add_u64 v[4:5], v[4:5], 0, s[20:21]
	s_add_i32 m0, s36, 0x1a000
	s_add_i32 s43, s36, 0x8000
	s_add_i32 s46, s36, 0xa000
	global_load_lds_dwordx4 v[4:5], off
	v_lshl_add_u64 v[0:1], v[0:1], 0, s[20:21]
	s_mov_b32 m0, s43
	s_add_u32 s6, s30, 0x40080
	global_load_lds_dwordx4 v[0:1], off
	v_lshl_add_u64 v[0:1], v[2:3], 0, s[20:21]
	s_mov_b32 m0, s46
	s_addc_u32 s7, s31, 0
	global_load_lds_dwordx4 v[0:1], off
	s_add_i32 m0, s36, 0x1c000
	v_lshl_add_u64 v[0:1], s[6:7], 0, v[132:133]
	global_load_lds_dwordx4 v[0:1], off
	v_lshl_add_u64 v[0:1], s[6:7], 0, v[128:129]
	s_add_i32 m0, s36, 0x1e000
	s_cmpk_lt_u32 s5, 0x100
	global_load_lds_dwordx4 v[0:1], off
	v_lshlrev_b32_e32 v0, 14, v12
	v_and_b32_e32 v0, 0xffff8000, v0
	v_lshl_add_u32 v0, v11, 11, v0
	v_and_b32_e32 v1, 1, v12
	v_lshl_or_b32 v0, v1, 6, v0
	v_lshl_add_u32 v136, v13, 1, v0
	v_lshlrev_b32_e32 v0, 14, v8
	v_and_b32_e32 v0, 0xffff8000, v0
	s_waitcnt vmcnt(6)
	v_lshl_add_u32 v0, v9, 11, v0
	v_and_b32_e32 v1, 1, v8
	v_bitop3_b32 v149, v15, s4, v14 bitop3:0xde
	s_cselect_b64 s[4:5], -1, 0
	v_lshl_or_b32 v0, v1, 6, v0
	s_add_i32 s47, 0, 0x10000
	s_add_i32 s48, 0, 0x14000
	v_or_b32_e32 v150, s22, v16
	v_mov_b32_e32 v137, v133
	v_lshl_add_u32 v138, v10, 1, v0
	v_mov_b32_e32 v139, v133
	v_mov_b64_e32 v[140:141], 0x100
	v_mov_b64_e32 v[142:143], 0xff
	v_add_u32_e32 v151, s47, v149
	v_add_u32_e32 v152, s48, v149
	v_add_u32_e32 v153, 0, v17
	s_mov_b64 s[6:7], 0x1000
	s_barrier
	s_branch .LBB0_679

.LBB0_686:
	s_add_u32 s30, s12, 0xfffc0080
	s_addc_u32 s31, s13, -1
	s_cmp_eq_u32 s56, 12
	s_cselect_b32 s35, s25, s31
	s_cselect_b32 s34, s49, s30
	s_cselect_b32 s31, s23, s55
	s_cselect_b32 s30, s51, s54
	s_and_b64 vcc, exec, s[4:5]
	s_cbranch_vccz .Lk64_trail_p4
	s_sub_u32 vcc_lo, s54, 0x80
	s_subb_u32 vcc_hi, s55, 0
	s_add_i32 m0, s36, 0x18000
	s_nop 0
	global_load_lds_dwordx4 v132, vcc
	s_add_i32 m0, s36, 0x1a000
	s_nop 0
	global_load_lds_dwordx4 v128, vcc
	s_add_u32 vcc_lo, vcc_lo, 0x10000
	s_addc_u32 vcc_hi, vcc_hi, 0
	s_add_i32 m0, s36, 0x19000
	s_nop 0
	global_load_lds_dwordx4 v132, vcc
	s_add_i32 m0, s36, 0x1b000
	s_nop 0
	global_load_lds_dwordx4 v128, vcc
	s_add_u32 vcc_lo, vcc_lo, 0x30000
	s_addc_u32 vcc_hi, vcc_hi, 0
	s_add_i32 m0, s36, 0x1c000
	s_nop 0
	global_load_lds_dwordx4 v132, vcc
	s_add_i32 m0, s36, 0x1e000
	s_nop 0
	global_load_lds_dwordx4 v128, vcc
	s_add_u32 vcc_lo, vcc_lo, 0x10000
	s_addc_u32 vcc_hi, vcc_hi, 0
	s_add_i32 m0, s36, 0x1d000
	s_nop 0
	global_load_lds_dwordx4 v132, vcc
	s_add_i32 m0, s36, 0x1f000
	s_nop 0
	global_load_lds_dwordx4 v128, vcc
	ds_read_b128 v[144:147], v151 offset:0
	ds_read_b128 v[154:157], v151 offset:1024
	ds_read_b128 v[158:161], v151 offset:2048
	ds_read_b128 v[162:165], v151 offset:3072
	ds_read_b128 v[166:169], v152 offset:0
	ds_read_b128 v[170:173], v152 offset:1024
	ds_read_b128 v[174:177], v152 offset:2048
	ds_read_b128 v[178:181], v152 offset:3072
	ds_read_b128 v[182:185], v153 offset:0
	ds_read_b128 v[186:189], v153 offset:1024
	ds_read_b128 v[190:193], v153 offset:2048
	ds_read_b128 v[194:197], v153 offset:3072
	ds_read_b128 v[198:201], v153 offset:4096
	ds_read_b128 v[202:205], v153 offset:5120
	ds_read_b128 v[206:209], v153 offset:6144
	ds_read_b128 v[210:213], v153 offset:7168
	ds_read_b128 v[220:223], v153 offset:16384
	ds_read_b128 v[224:227], v153 offset:17408
	ds_read_b128 v[228:231], v153 offset:18432
	ds_read_b128 v[232:235], v153 offset:19456
	ds_read_b128 v[236:239], v153 offset:20480
	ds_read_b128 v[240:243], v153 offset:21504
	ds_read_b128 v[244:247], v153 offset:22528
	ds_read_b128 v[248:251], v153 offset:23552
	s_nop 15
	s_nop 15
	s_waitcnt lgkmcnt(0)
	s_barrier
	s_setprio 1
	v_mfma_f32_16x16x32_bf16 v[124:127], v[144:147], v[182:185], v[124:127]
	v_mfma_f32_16x16x32_bf16 v[120:123], v[158:161], v[182:185], v[120:123]
	v_mfma_f32_16x16x32_bf16 v[108:111], v[144:147], v[190:193], v[108:111]
	v_mfma_f32_16x16x32_bf16 v[104:107], v[158:161], v[190:193], v[104:107]
	v_mfma_f32_16x16x32_bf16 v[92:95], v[144:147], v[198:201], v[92:95]
	v_mfma_f32_16x16x32_bf16 v[88:91], v[158:161], v[198:201], v[88:91]
	v_mfma_f32_16x16x32_bf16 v[76:79], v[144:147], v[206:209], v[76:79]
	v_mfma_f32_16x16x32_bf16 v[72:75], v[158:161], v[206:209], v[72:75]
	v_mfma_f32_16x16x32_bf16 v[124:127], v[154:157], v[186:189], v[124:127]
	v_mfma_f32_16x16x32_bf16 v[120:123], v[162:165], v[186:189], v[120:123]
	v_mfma_f32_16x16x32_bf16 v[108:111], v[154:157], v[194:197], v[108:111]
	v_mfma_f32_16x16x32_bf16 v[104:107], v[162:165], v[194:197], v[104:107]
	v_mfma_f32_16x16x32_bf16 v[92:95], v[154:157], v[202:205], v[92:95]
	v_mfma_f32_16x16x32_bf16 v[88:91], v[162:165], v[202:205], v[88:91]
	v_mfma_f32_16x16x32_bf16 v[76:79], v[154:157], v[210:213], v[76:79]
	v_mfma_f32_16x16x32_bf16 v[72:75], v[162:165], v[210:213], v[72:75]
	s_setprio 0
	s_setprio 1
	v_mfma_f32_16x16x32_bf16 v[116:119], v[166:169], v[182:185], v[116:119]
	v_mfma_f32_16x16x32_bf16 v[112:115], v[174:177], v[182:185], v[112:115]
	v_mfma_f32_16x16x32_bf16 v[100:103], v[166:169], v[190:193], v[100:103]
	v_mfma_f32_16x16x32_bf16 v[96:99], v[174:177], v[190:193], v[96:99]
	v_mfma_f32_16x16x32_bf16 v[84:87], v[166:169], v[198:201], v[84:87]
	v_mfma_f32_16x16x32_bf16 v[80:83], v[174:177], v[198:201], v[80:83]
	v_mfma_f32_16x16x32_bf16 v[68:71], v[166:169], v[206:209], v[68:71]
	v_mfma_f32_16x16x32_bf16 v[64:67], v[174:177], v[206:209], v[64:67]
	v_mfma_f32_16x16x32_bf16 v[116:119], v[170:173], v[186:189], v[116:119]
	v_mfma_f32_16x16x32_bf16 v[112:115], v[178:181], v[186:189], v[112:115]
	v_mfma_f32_16x16x32_bf16 v[100:103], v[170:173], v[194:197], v[100:103]
	v_mfma_f32_16x16x32_bf16 v[96:99], v[178:181], v[194:197], v[96:99]
	v_mfma_f32_16x16x32_bf16 v[84:87], v[170:173], v[202:205], v[84:87]
	v_mfma_f32_16x16x32_bf16 v[80:83], v[178:181], v[202:205], v[80:83]
	v_mfma_f32_16x16x32_bf16 v[68:71], v[170:173], v[210:213], v[68:71]
	v_mfma_f32_16x16x32_bf16 v[64:67], v[178:181], v[210:213], v[64:67]
	s_setprio 0
	s_setprio 1
	v_mfma_f32_16x16x32_bf16 v[60:63], v[144:147], v[220:223], v[60:63]
	v_mfma_f32_16x16x32_bf16 v[56:59], v[158:161], v[220:223], v[56:59]
	v_mfma_f32_16x16x32_bf16 v[44:47], v[144:147], v[228:231], v[44:47]
	v_mfma_f32_16x16x32_bf16 v[40:43], v[158:161], v[228:231], v[40:43]
	v_mfma_f32_16x16x32_bf16 v[28:31], v[144:147], v[236:239], v[28:31]
	v_mfma_f32_16x16x32_bf16 v[24:27], v[158:161], v[236:239], v[24:27]
	v_mfma_f32_16x16x32_bf16 v[12:15], v[144:147], v[244:247], v[12:15]
	v_mfma_f32_16x16x32_bf16 v[8:11], v[158:161], v[244:247], v[8:11]
	v_mfma_f32_16x16x32_bf16 v[60:63], v[154:157], v[224:227], v[60:63]
	v_mfma_f32_16x16x32_bf16 v[56:59], v[162:165], v[224:227], v[56:59]
	v_mfma_f32_16x16x32_bf16 v[44:47], v[154:157], v[232:235], v[44:47]
	v_mfma_f32_16x16x32_bf16 v[40:43], v[162:165], v[232:235], v[40:43]
	v_mfma_f32_16x16x32_bf16 v[28:31], v[154:157], v[240:243], v[28:31]
	v_mfma_f32_16x16x32_bf16 v[24:27], v[162:165], v[240:243], v[24:27]
	v_mfma_f32_16x16x32_bf16 v[12:15], v[154:157], v[248:251], v[12:15]
	v_mfma_f32_16x16x32_bf16 v[8:11], v[162:165], v[248:251], v[8:11]
	s_setprio 0
	s_setprio 1
	v_mfma_f32_16x16x32_bf16 v[52:55], v[166:169], v[220:223], v[52:55]
	v_mfma_f32_16x16x32_bf16 v[48:51], v[174:177], v[220:223], v[48:51]
	v_mfma_f32_16x16x32_bf16 v[36:39], v[166:169], v[228:231], v[36:39]
	v_mfma_f32_16x16x32_bf16 v[32:35], v[174:177], v[228:231], v[32:35]
	v_mfma_f32_16x16x32_bf16 v[20:23], v[166:169], v[236:239], v[20:23]
	v_mfma_f32_16x16x32_bf16 v[16:19], v[174:177], v[236:239], v[16:19]
	v_mfma_f32_16x16x32_bf16 v[4:7], v[166:169], v[244:247], v[4:7]
	v_mfma_f32_16x16x32_bf16 v[0:3], v[174:177], v[244:247], v[0:3]
	v_mfma_f32_16x16x32_bf16 v[52:55], v[170:173], v[224:227], v[52:55]
	v_mfma_f32_16x16x32_bf16 v[48:51], v[178:181], v[224:227], v[48:51]
	v_mfma_f32_16x16x32_bf16 v[36:39], v[170:173], v[232:235], v[36:39]
	v_mfma_f32_16x16x32_bf16 v[32:35], v[178:181], v[232:235], v[32:35]
	v_mfma_f32_16x16x32_bf16 v[20:23], v[170:173], v[240:243], v[20:23]
	v_mfma_f32_16x16x32_bf16 v[16:19], v[178:181], v[240:243], v[16:19]
	v_mfma_f32_16x16x32_bf16 v[4:7], v[170:173], v[248:251], v[4:7]
	v_mfma_f32_16x16x32_bf16 v[0:3], v[178:181], v[248:251], v[0:3]
	s_setprio 0
	s_waitcnt vmcnt(0)
	s_barrier
	s_add_u32 vcc_lo, s30, 0x0
	s_addc_u32 vcc_hi, s31, 0
	s_add_i32 m0, s36, 0x10000
	s_nop 0
	global_load_lds_dwordx4 v132, vcc
	s_add_i32 m0, s36, 0x12000
	s_nop 0
	global_load_lds_dwordx4 v128, vcc
	s_add_u32 vcc_lo, vcc_lo, 0x10000
	s_addc_u32 vcc_hi, vcc_hi, 0
	s_add_i32 m0, s36, 0x11000
	s_nop 0
	global_load_lds_dwordx4 v132, vcc
	s_add_i32 m0, s36, 0x13000
	s_nop 0
	global_load_lds_dwordx4 v128, vcc
	s_add_u32 vcc_lo, vcc_lo, 0x30000
	s_addc_u32 vcc_hi, vcc_hi, 0
	s_add_i32 m0, s36, 0x14000
	s_nop 0
	global_load_lds_dwordx4 v132, vcc
	s_add_i32 m0, s36, 0x16000
	s_nop 0
	global_load_lds_dwordx4 v128, vcc
	s_add_u32 vcc_lo, vcc_lo, 0x10000
	s_addc_u32 vcc_hi, vcc_hi, 0
	s_add_i32 m0, s36, 0x15000
	s_nop 0
	global_load_lds_dwordx4 v132, vcc
	s_add_i32 m0, s36, 0x17000
	s_nop 0
	global_load_lds_dwordx4 v128, vcc
	ds_read_b128 v[144:147], v151 offset:32768
	ds_read_b128 v[154:157], v151 offset:33792
	ds_read_b128 v[158:161], v151 offset:34816
	ds_read_b128 v[162:165], v151 offset:35840
	ds_read_b128 v[166:169], v152 offset:32768
	ds_read_b128 v[170:173], v152 offset:33792
	ds_read_b128 v[174:177], v152 offset:34816
	ds_read_b128 v[178:181], v152 offset:35840
	ds_read_b128 v[182:185], v153 offset:32768
	ds_read_b128 v[186:189], v153 offset:33792
	ds_read_b128 v[190:193], v153 offset:34816
	ds_read_b128 v[194:197], v153 offset:35840
	ds_read_b128 v[198:201], v153 offset:36864
	ds_read_b128 v[202:205], v153 offset:37888
	ds_read_b128 v[206:209], v153 offset:38912
	ds_read_b128 v[210:213], v153 offset:39936
	ds_read_b128 v[220:223], v153 offset:49152
	ds_read_b128 v[224:227], v153 offset:50176
	ds_read_b128 v[228:231], v153 offset:51200
	ds_read_b128 v[232:235], v153 offset:52224
	ds_read_b128 v[236:239], v153 offset:53248
	ds_read_b128 v[240:243], v153 offset:54272
	ds_read_b128 v[244:247], v153 offset:55296
	ds_read_b128 v[248:251], v153 offset:56320
	s_nop 15
	s_nop 15
	s_waitcnt lgkmcnt(0)
	s_barrier
	s_setprio 1
	v_mfma_f32_16x16x32_bf16 v[124:127], v[144:147], v[182:185], v[124:127]
	v_mfma_f32_16x16x32_bf16 v[120:123], v[158:161], v[182:185], v[120:123]
	v_mfma_f32_16x16x32_bf16 v[108:111], v[144:147], v[190:193], v[108:111]
	v_mfma_f32_16x16x32_bf16 v[104:107], v[158:161], v[190:193], v[104:107]
	v_mfma_f32_16x16x32_bf16 v[92:95], v[144:147], v[198:201], v[92:95]
	v_mfma_f32_16x16x32_bf16 v[88:91], v[158:161], v[198:201], v[88:91]
	v_mfma_f32_16x16x32_bf16 v[76:79], v[144:147], v[206:209], v[76:79]
	v_mfma_f32_16x16x32_bf16 v[72:75], v[158:161], v[206:209], v[72:75]
	v_mfma_f32_16x16x32_bf16 v[124:127], v[154:157], v[186:189], v[124:127]
	v_mfma_f32_16x16x32_bf16 v[120:123], v[162:165], v[186:189], v[120:123]
	v_mfma_f32_16x16x32_bf16 v[108:111], v[154:157], v[194:197], v[108:111]
	v_mfma_f32_16x16x32_bf16 v[104:107], v[162:165], v[194:197], v[104:107]
	v_mfma_f32_16x16x32_bf16 v[92:95], v[154:157], v[202:205], v[92:95]
	v_mfma_f32_16x16x32_bf16 v[88:91], v[162:165], v[202:205], v[88:91]
	v_mfma_f32_16x16x32_bf16 v[76:79], v[154:157], v[210:213], v[76:79]
	v_mfma_f32_16x16x32_bf16 v[72:75], v[162:165], v[210:213], v[72:75]
	s_setprio 0
	s_setprio 1
	v_mfma_f32_16x16x32_bf16 v[116:119], v[166:169], v[182:185], v[116:119]
	v_mfma_f32_16x16x32_bf16 v[112:115], v[174:177], v[182:185], v[112:115]
	v_mfma_f32_16x16x32_bf16 v[100:103], v[166:169], v[190:193], v[100:103]
	v_mfma_f32_16x16x32_bf16 v[96:99], v[174:177], v[190:193], v[96:99]
	v_mfma_f32_16x16x32_bf16 v[84:87], v[166:169], v[198:201], v[84:87]
	v_mfma_f32_16x16x32_bf16 v[80:83], v[174:177], v[198:201], v[80:83]
	v_mfma_f32_16x16x32_bf16 v[68:71], v[166:169], v[206:209], v[68:71]
	v_mfma_f32_16x16x32_bf16 v[64:67], v[174:177], v[206:209], v[64:67]
	v_mfma_f32_16x16x32_bf16 v[116:119], v[170:173], v[186:189], v[116:119]
	v_mfma_f32_16x16x32_bf16 v[112:115], v[178:181], v[186:189], v[112:115]
	v_mfma_f32_16x16x32_bf16 v[100:103], v[170:173], v[194:197], v[100:103]
	v_mfma_f32_16x16x32_bf16 v[96:99], v[178:181], v[194:197], v[96:99]
	v_mfma_f32_16x16x32_bf16 v[84:87], v[170:173], v[202:205], v[84:87]
	v_mfma_f32_16x16x32_bf16 v[80:83], v[178:181], v[202:205], v[80:83]
	v_mfma_f32_16x16x32_bf16 v[68:71], v[170:173], v[210:213], v[68:71]
	v_mfma_f32_16x16x32_bf16 v[64:67], v[178:181], v[210:213], v[64:67]
	s_setprio 0
	s_setprio 1
	v_mfma_f32_16x16x32_bf16 v[60:63], v[144:147], v[220:223], v[60:63]
	v_mfma_f32_16x16x32_bf16 v[56:59], v[158:161], v[220:223], v[56:59]
	v_mfma_f32_16x16x32_bf16 v[44:47], v[144:147], v[228:231], v[44:47]
	v_mfma_f32_16x16x32_bf16 v[40:43], v[158:161], v[228:231], v[40:43]
	v_mfma_f32_16x16x32_bf16 v[28:31], v[144:147], v[236:239], v[28:31]
	v_mfma_f32_16x16x32_bf16 v[24:27], v[158:161], v[236:239], v[24:27]
	v_mfma_f32_16x16x32_bf16 v[12:15], v[144:147], v[244:247], v[12:15]
	v_mfma_f32_16x16x32_bf16 v[8:11], v[158:161], v[244:247], v[8:11]
	v_mfma_f32_16x16x32_bf16 v[60:63], v[154:157], v[224:227], v[60:63]
	v_mfma_f32_16x16x32_bf16 v[56:59], v[162:165], v[224:227], v[56:59]
	v_mfma_f32_16x16x32_bf16 v[44:47], v[154:157], v[232:235], v[44:47]
	v_mfma_f32_16x16x32_bf16 v[40:43], v[162:165], v[232:235], v[40:43]
	v_mfma_f32_16x16x32_bf16 v[28:31], v[154:157], v[240:243], v[28:31]
	v_mfma_f32_16x16x32_bf16 v[24:27], v[162:165], v[240:243], v[24:27]
	v_mfma_f32_16x16x32_bf16 v[12:15], v[154:157], v[248:251], v[12:15]
	v_mfma_f32_16x16x32_bf16 v[8:11], v[162:165], v[248:251], v[8:11]
	s_setprio 0
	s_setprio 1
	v_mfma_f32_16x16x32_bf16 v[52:55], v[166:169], v[220:223], v[52:55]
	v_mfma_f32_16x16x32_bf16 v[48:51], v[174:177], v[220:223], v[48:51]
	v_mfma_f32_16x16x32_bf16 v[36:39], v[166:169], v[228:231], v[36:39]
	v_mfma_f32_16x16x32_bf16 v[32:35], v[174:177], v[228:231], v[32:35]
	v_mfma_f32_16x16x32_bf16 v[20:23], v[166:169], v[236:239], v[20:23]
	v_mfma_f32_16x16x32_bf16 v[16:19], v[174:177], v[236:239], v[16:19]
	v_mfma_f32_16x16x32_bf16 v[4:7], v[166:169], v[244:247], v[4:7]
	v_mfma_f32_16x16x32_bf16 v[0:3], v[174:177], v[244:247], v[0:3]
	v_mfma_f32_16x16x32_bf16 v[52:55], v[170:173], v[224:227], v[52:55]
	v_mfma_f32_16x16x32_bf16 v[48:51], v[178:181], v[224:227], v[48:51]
	v_mfma_f32_16x16x32_bf16 v[36:39], v[170:173], v[232:235], v[36:39]
	v_mfma_f32_16x16x32_bf16 v[32:35], v[178:181], v[232:235], v[32:35]
	v_mfma_f32_16x16x32_bf16 v[20:23], v[170:173], v[240:243], v[20:23]
	v_mfma_f32_16x16x32_bf16 v[16:19], v[178:181], v[240:243], v[16:19]
	v_mfma_f32_16x16x32_bf16 v[4:7], v[170:173], v[248:251], v[4:7]
	v_mfma_f32_16x16x32_bf16 v[0:3], v[178:181], v[248:251], v[0:3]
	s_setprio 0
	s_waitcnt vmcnt(0)
	s_barrier
	s_add_i32 s56, s56, 2
	s_add_u32 s12, s12, 0x100
	s_addc_u32 s13, s13, 0
	s_add_u32 s54, s54, 0x100
	s_addc_u32 s55, s55, 0
	s_cmp_gt_u32 s56, 13
	s_cbranch_scc0 .LBB0_686
	s_branch .Lk64_done_p4
.Lk64_trail_p4:
	s_sub_u32 vcc_lo, s12, 0x40000
	s_subb_u32 vcc_hi, s13, 0
	s_add_i32 m0, s36, 0xa000
	s_nop 0
	global_load_lds_dwordx4 v130, vcc
	s_add_u32 vcc_lo, vcc_lo, 0x10000
	s_addc_u32 vcc_hi, vcc_hi, 0
	s_add_i32 m0, s36, 0x9000
	s_nop 0
	global_load_lds_dwordx4 v134, vcc
	s_add_u32 vcc_lo, vcc_lo, 0x30000
	s_addc_u32 vcc_hi, vcc_hi, 0
	s_add_i32 m0, s36, 0xe000
	s_nop 0
	global_load_lds_dwordx4 v130, vcc
	s_add_u32 vcc_lo, vcc_lo, 0x10000
	s_addc_u32 vcc_hi, vcc_hi, 0
	s_add_i32 m0, s36, 0xd000
	s_nop 0
	global_load_lds_dwordx4 v134, vcc
	s_add_u32 vcc_lo, s34, 0x0
	s_addc_u32 vcc_hi, s35, 0
	s_mov_b32 m0, s36
	s_nop 0
	global_load_lds_dwordx4 v134, vcc
	s_sub_u32 vcc_lo, vcc_lo, 0x10000
	s_subb_u32 vcc_hi, vcc_hi, 0
	s_sub_i32 m0, s36, 0x1000
	s_nop 0
	global_load_lds_dwordx4 v134, vcc
	s_add_u32 vcc_lo, vcc_lo, 0x50000
	s_addc_u32 vcc_hi, vcc_hi, 0
	s_add_i32 m0, s36, 0x4000
	s_nop 0
	global_load_lds_dwordx4 v134, vcc
	s_sub_u32 vcc_lo, vcc_lo, 0x10000
	s_subb_u32 vcc_hi, vcc_hi, 0
	s_add_i32 m0, s36, 0x3000
	s_nop 0
	global_load_lds_dwordx4 v134, vcc
	ds_read_b128 v[144:147], v151 offset:0
	ds_read_b128 v[154:157], v151 offset:1024
	ds_read_b128 v[158:161], v151 offset:2048
	ds_read_b128 v[162:165], v151 offset:3072
	ds_read_b128 v[166:169], v152 offset:0
	ds_read_b128 v[170:173], v152 offset:1024
	ds_read_b128 v[174:177], v152 offset:2048
	ds_read_b128 v[178:181], v152 offset:3072
	ds_read_b128 v[182:185], v153 offset:0
	ds_read_b128 v[186:189], v153 offset:1024
	ds_read_b128 v[190:193], v153 offset:2048
	ds_read_b128 v[194:197], v153 offset:3072
	ds_read_b128 v[198:201], v153 offset:4096
	ds_read_b128 v[202:205], v153 offset:5120
	ds_read_b128 v[206:209], v153 offset:6144
	ds_read_b128 v[210:213], v153 offset:7168
	ds_read_b128 v[220:223], v153 offset:16384
	ds_read_b128 v[224:227], v153 offset:17408
	ds_read_b128 v[228:231], v153 offset:18432
	ds_read_b128 v[232:235], v153 offset:19456
	ds_read_b128 v[236:239], v153 offset:20480
	ds_read_b128 v[240:243], v153 offset:21504
	ds_read_b128 v[244:247], v153 offset:22528
	ds_read_b128 v[248:251], v153 offset:23552
	s_nop 15
	s_nop 15
	s_waitcnt lgkmcnt(0)
	s_barrier
	s_setprio 1
	v_mfma_f32_16x16x32_bf16 v[124:127], v[144:147], v[182:185], v[124:127]
	v_mfma_f32_16x16x32_bf16 v[120:123], v[158:161], v[182:185], v[120:123]
	v_mfma_f32_16x16x32_bf16 v[108:111], v[144:147], v[190:193], v[108:111]
	v_mfma_f32_16x16x32_bf16 v[104:107], v[158:161], v[190:193], v[104:107]
	v_mfma_f32_16x16x32_bf16 v[92:95], v[144:147], v[198:201], v[92:95]
	v_mfma_f32_16x16x32_bf16 v[88:91], v[158:161], v[198:201], v[88:91]
	v_mfma_f32_16x16x32_bf16 v[76:79], v[144:147], v[206:209], v[76:79]
	v_mfma_f32_16x16x32_bf16 v[72:75], v[158:161], v[206:209], v[72:75]
	v_mfma_f32_16x16x32_bf16 v[124:127], v[154:157], v[186:189], v[124:127]
	v_mfma_f32_16x16x32_bf16 v[120:123], v[162:165], v[186:189], v[120:123]
	v_mfma_f32_16x16x32_bf16 v[108:111], v[154:157], v[194:197], v[108:111]
	v_mfma_f32_16x16x32_bf16 v[104:107], v[162:165], v[194:197], v[104:107]
	v_mfma_f32_16x16x32_bf16 v[92:95], v[154:157], v[202:205], v[92:95]
	v_mfma_f32_16x16x32_bf16 v[88:91], v[162:165], v[202:205], v[88:91]
	v_mfma_f32_16x16x32_bf16 v[76:79], v[154:157], v[210:213], v[76:79]
	v_mfma_f32_16x16x32_bf16 v[72:75], v[162:165], v[210:213], v[72:75]
	s_setprio 0
	s_setprio 1
	v_mfma_f32_16x16x32_bf16 v[116:119], v[166:169], v[182:185], v[116:119]
	v_mfma_f32_16x16x32_bf16 v[112:115], v[174:177], v[182:185], v[112:115]
	v_mfma_f32_16x16x32_bf16 v[100:103], v[166:169], v[190:193], v[100:103]
	v_mfma_f32_16x16x32_bf16 v[96:99], v[174:177], v[190:193], v[96:99]
	v_mfma_f32_16x16x32_bf16 v[84:87], v[166:169], v[198:201], v[84:87]
	v_mfma_f32_16x16x32_bf16 v[80:83], v[174:177], v[198:201], v[80:83]
	v_mfma_f32_16x16x32_bf16 v[68:71], v[166:169], v[206:209], v[68:71]
	v_mfma_f32_16x16x32_bf16 v[64:67], v[174:177], v[206:209], v[64:67]
	v_mfma_f32_16x16x32_bf16 v[116:119], v[170:173], v[186:189], v[116:119]
	v_mfma_f32_16x16x32_bf16 v[112:115], v[178:181], v[186:189], v[112:115]
	v_mfma_f32_16x16x32_bf16 v[100:103], v[170:173], v[194:197], v[100:103]
	v_mfma_f32_16x16x32_bf16 v[96:99], v[178:181], v[194:197], v[96:99]
	v_mfma_f32_16x16x32_bf16 v[84:87], v[170:173], v[202:205], v[84:87]
	v_mfma_f32_16x16x32_bf16 v[80:83], v[178:181], v[202:205], v[80:83]
	v_mfma_f32_16x16x32_bf16 v[68:71], v[170:173], v[210:213], v[68:71]
	v_mfma_f32_16x16x32_bf16 v[64:67], v[178:181], v[210:213], v[64:67]
	s_setprio 0
	s_setprio 1
	v_mfma_f32_16x16x32_bf16 v[60:63], v[144:147], v[220:223], v[60:63]
	v_mfma_f32_16x16x32_bf16 v[56:59], v[158:161], v[220:223], v[56:59]
	v_mfma_f32_16x16x32_bf16 v[44:47], v[144:147], v[228:231], v[44:47]
	v_mfma_f32_16x16x32_bf16 v[40:43], v[158:161], v[228:231], v[40:43]
	v_mfma_f32_16x16x32_bf16 v[28:31], v[144:147], v[236:239], v[28:31]
	v_mfma_f32_16x16x32_bf16 v[24:27], v[158:161], v[236:239], v[24:27]
	v_mfma_f32_16x16x32_bf16 v[12:15], v[144:147], v[244:247], v[12:15]
	v_mfma_f32_16x16x32_bf16 v[8:11], v[158:161], v[244:247], v[8:11]
	v_mfma_f32_16x16x32_bf16 v[60:63], v[154:157], v[224:227], v[60:63]
	v_mfma_f32_16x16x32_bf16 v[56:59], v[162:165], v[224:227], v[56:59]
	v_mfma_f32_16x16x32_bf16 v[44:47], v[154:157], v[232:235], v[44:47]
	v_mfma_f32_16x16x32_bf16 v[40:43], v[162:165], v[232:235], v[40:43]
	v_mfma_f32_16x16x32_bf16 v[28:31], v[154:157], v[240:243], v[28:31]
	v_mfma_f32_16x16x32_bf16 v[24:27], v[162:165], v[240:243], v[24:27]
	v_mfma_f32_16x16x32_bf16 v[12:15], v[154:157], v[248:251], v[12:15]
	v_mfma_f32_16x16x32_bf16 v[8:11], v[162:165], v[248:251], v[8:11]
	s_setprio 0
	s_setprio 1
	v_mfma_f32_16x16x32_bf16 v[52:55], v[166:169], v[220:223], v[52:55]
	v_mfma_f32_16x16x32_bf16 v[48:51], v[174:177], v[220:223], v[48:51]
	v_mfma_f32_16x16x32_bf16 v[36:39], v[166:169], v[228:231], v[36:39]
	v_mfma_f32_16x16x32_bf16 v[32:35], v[174:177], v[228:231], v[32:35]
	v_mfma_f32_16x16x32_bf16 v[20:23], v[166:169], v[236:239], v[20:23]
	v_mfma_f32_16x16x32_bf16 v[16:19], v[174:177], v[236:239], v[16:19]
	v_mfma_f32_16x16x32_bf16 v[4:7], v[166:169], v[244:247], v[4:7]
	v_mfma_f32_16x16x32_bf16 v[0:3], v[174:177], v[244:247], v[0:3]
	v_mfma_f32_16x16x32_bf16 v[52:55], v[170:173], v[224:227], v[52:55]
	v_mfma_f32_16x16x32_bf16 v[48:51], v[178:181], v[224:227], v[48:51]
	v_mfma_f32_16x16x32_bf16 v[36:39], v[170:173], v[232:235], v[36:39]
	v_mfma_f32_16x16x32_bf16 v[32:35], v[178:181], v[232:235], v[32:35]
	v_mfma_f32_16x16x32_bf16 v[20:23], v[170:173], v[240:243], v[20:23]
	v_mfma_f32_16x16x32_bf16 v[16:19], v[178:181], v[240:243], v[16:19]
	v_mfma_f32_16x16x32_bf16 v[4:7], v[170:173], v[248:251], v[4:7]
	v_mfma_f32_16x16x32_bf16 v[0:3], v[178:181], v[248:251], v[0:3]
	s_setprio 0
	s_waitcnt vmcnt(0)
	s_barrier
	s_add_u32 vcc_lo, s34, 0x0
	s_addc_u32 vcc_hi, s35, 0
	s_add_i32 m0, s36, 0x2000
	s_nop 0
	global_load_lds_dwordx4 v130, vcc
	s_add_u32 vcc_lo, vcc_lo, 0x10000
	s_addc_u32 vcc_hi, vcc_hi, 0
	s_add_i32 m0, s36, 0x1000
	s_nop 0
	global_load_lds_dwordx4 v134, vcc
	s_add_u32 vcc_lo, vcc_lo, 0x30000
	s_addc_u32 vcc_hi, vcc_hi, 0
	s_add_i32 m0, s36, 0x6000
	s_nop 0
	global_load_lds_dwordx4 v130, vcc
	s_add_u32 vcc_lo, vcc_lo, 0x10000
	s_addc_u32 vcc_hi, vcc_hi, 0
	s_add_i32 m0, s36, 0x5000
	s_nop 0
	global_load_lds_dwordx4 v134, vcc
	s_add_u32 vcc_lo, s34, 0x80
	s_addc_u32 vcc_hi, s35, 0
	s_add_i32 m0, s36, 0x8000
	s_nop 0
	global_load_lds_dwordx4 v134, vcc
	s_sub_u32 vcc_lo, vcc_lo, 0x10000
	s_subb_u32 vcc_hi, vcc_hi, 0
	s_add_i32 m0, s36, 0x7000
	s_nop 0
	global_load_lds_dwordx4 v134, vcc
	s_add_u32 vcc_lo, vcc_lo, 0x50000
	s_addc_u32 vcc_hi, vcc_hi, 0
	s_add_i32 m0, s36, 0xc000
	s_nop 0
	global_load_lds_dwordx4 v134, vcc
	s_sub_u32 vcc_lo, vcc_lo, 0x10000
	s_subb_u32 vcc_hi, vcc_hi, 0
	s_add_i32 m0, s36, 0xb000
	s_nop 0
	global_load_lds_dwordx4 v134, vcc
	ds_read_b128 v[144:147], v151 offset:32768
	ds_read_b128 v[154:157], v151 offset:33792
	ds_read_b128 v[158:161], v151 offset:34816
	ds_read_b128 v[162:165], v151 offset:35840
	ds_read_b128 v[166:169], v152 offset:32768
	ds_read_b128 v[170:173], v152 offset:33792
	ds_read_b128 v[174:177], v152 offset:34816
	ds_read_b128 v[178:181], v152 offset:35840
	ds_read_b128 v[182:185], v153 offset:32768
	ds_read_b128 v[186:189], v153 offset:33792
	ds_read_b128 v[190:193], v153 offset:34816
	ds_read_b128 v[194:197], v153 offset:35840
	ds_read_b128 v[198:201], v153 offset:36864
	ds_read_b128 v[202:205], v153 offset:37888
	ds_read_b128 v[206:209], v153 offset:38912
	ds_read_b128 v[210:213], v153 offset:39936
	ds_read_b128 v[220:223], v153 offset:49152
	ds_read_b128 v[224:227], v153 offset:50176
	ds_read_b128 v[228:231], v153 offset:51200
	ds_read_b128 v[232:235], v153 offset:52224
	ds_read_b128 v[236:239], v153 offset:53248
	ds_read_b128 v[240:243], v153 offset:54272
	ds_read_b128 v[244:247], v153 offset:55296
	ds_read_b128 v[248:251], v153 offset:56320
	s_nop 15
	s_nop 15
	s_waitcnt lgkmcnt(0)
	s_barrier
	s_setprio 1
	v_mfma_f32_16x16x32_bf16 v[124:127], v[144:147], v[182:185], v[124:127]
	v_mfma_f32_16x16x32_bf16 v[120:123], v[158:161], v[182:185], v[120:123]
	v_mfma_f32_16x16x32_bf16 v[108:111], v[144:147], v[190:193], v[108:111]
	v_mfma_f32_16x16x32_bf16 v[104:107], v[158:161], v[190:193], v[104:107]
	v_mfma_f32_16x16x32_bf16 v[92:95], v[144:147], v[198:201], v[92:95]
	v_mfma_f32_16x16x32_bf16 v[88:91], v[158:161], v[198:201], v[88:91]
	v_mfma_f32_16x16x32_bf16 v[76:79], v[144:147], v[206:209], v[76:79]
	v_mfma_f32_16x16x32_bf16 v[72:75], v[158:161], v[206:209], v[72:75]
	v_mfma_f32_16x16x32_bf16 v[124:127], v[154:157], v[186:189], v[124:127]
	v_mfma_f32_16x16x32_bf16 v[120:123], v[162:165], v[186:189], v[120:123]
	v_mfma_f32_16x16x32_bf16 v[108:111], v[154:157], v[194:197], v[108:111]
	v_mfma_f32_16x16x32_bf16 v[104:107], v[162:165], v[194:197], v[104:107]
	v_mfma_f32_16x16x32_bf16 v[92:95], v[154:157], v[202:205], v[92:95]
	v_mfma_f32_16x16x32_bf16 v[88:91], v[162:165], v[202:205], v[88:91]
	v_mfma_f32_16x16x32_bf16 v[76:79], v[154:157], v[210:213], v[76:79]
	v_mfma_f32_16x16x32_bf16 v[72:75], v[162:165], v[210:213], v[72:75]
	s_setprio 0
	s_setprio 1
	v_mfma_f32_16x16x32_bf16 v[116:119], v[166:169], v[182:185], v[116:119]
	v_mfma_f32_16x16x32_bf16 v[112:115], v[174:177], v[182:185], v[112:115]
	v_mfma_f32_16x16x32_bf16 v[100:103], v[166:169], v[190:193], v[100:103]
	v_mfma_f32_16x16x32_bf16 v[96:99], v[174:177], v[190:193], v[96:99]
	v_mfma_f32_16x16x32_bf16 v[84:87], v[166:169], v[198:201], v[84:87]
	v_mfma_f32_16x16x32_bf16 v[80:83], v[174:177], v[198:201], v[80:83]
	v_mfma_f32_16x16x32_bf16 v[68:71], v[166:169], v[206:209], v[68:71]
	v_mfma_f32_16x16x32_bf16 v[64:67], v[174:177], v[206:209], v[64:67]
	v_mfma_f32_16x16x32_bf16 v[116:119], v[170:173], v[186:189], v[116:119]
	v_mfma_f32_16x16x32_bf16 v[112:115], v[178:181], v[186:189], v[112:115]
	v_mfma_f32_16x16x32_bf16 v[100:103], v[170:173], v[194:197], v[100:103]
	v_mfma_f32_16x16x32_bf16 v[96:99], v[178:181], v[194:197], v[96:99]
	v_mfma_f32_16x16x32_bf16 v[84:87], v[170:173], v[202:205], v[84:87]
	v_mfma_f32_16x16x32_bf16 v[80:83], v[178:181], v[202:205], v[80:83]
	v_mfma_f32_16x16x32_bf16 v[68:71], v[170:173], v[210:213], v[68:71]
	v_mfma_f32_16x16x32_bf16 v[64:67], v[178:181], v[210:213], v[64:67]
	s_setprio 0
	s_setprio 1
	v_mfma_f32_16x16x32_bf16 v[60:63], v[144:147], v[220:223], v[60:63]
	v_mfma_f32_16x16x32_bf16 v[56:59], v[158:161], v[220:223], v[56:59]
	v_mfma_f32_16x16x32_bf16 v[44:47], v[144:147], v[228:231], v[44:47]
	v_mfma_f32_16x16x32_bf16 v[40:43], v[158:161], v[228:231], v[40:43]
	v_mfma_f32_16x16x32_bf16 v[28:31], v[144:147], v[236:239], v[28:31]
	v_mfma_f32_16x16x32_bf16 v[24:27], v[158:161], v[236:239], v[24:27]
	v_mfma_f32_16x16x32_bf16 v[12:15], v[144:147], v[244:247], v[12:15]
	v_mfma_f32_16x16x32_bf16 v[8:11], v[158:161], v[244:247], v[8:11]
	v_mfma_f32_16x16x32_bf16 v[60:63], v[154:157], v[224:227], v[60:63]
	v_mfma_f32_16x16x32_bf16 v[56:59], v[162:165], v[224:227], v[56:59]
	v_mfma_f32_16x16x32_bf16 v[44:47], v[154:157], v[232:235], v[44:47]
	v_mfma_f32_16x16x32_bf16 v[40:43], v[162:165], v[232:235], v[40:43]
	v_mfma_f32_16x16x32_bf16 v[28:31], v[154:157], v[240:243], v[28:31]
	v_mfma_f32_16x16x32_bf16 v[24:27], v[162:165], v[240:243], v[24:27]
	v_mfma_f32_16x16x32_bf16 v[12:15], v[154:157], v[248:251], v[12:15]
	v_mfma_f32_16x16x32_bf16 v[8:11], v[162:165], v[248:251], v[8:11]
	s_setprio 0
	s_setprio 1
	v_mfma_f32_16x16x32_bf16 v[52:55], v[166:169], v[220:223], v[52:55]
	v_mfma_f32_16x16x32_bf16 v[48:51], v[174:177], v[220:223], v[48:51]
	v_mfma_f32_16x16x32_bf16 v[36:39], v[166:169], v[228:231], v[36:39]
	v_mfma_f32_16x16x32_bf16 v[32:35], v[174:177], v[228:231], v[32:35]
	v_mfma_f32_16x16x32_bf16 v[20:23], v[166:169], v[236:239], v[20:23]
	v_mfma_f32_16x16x32_bf16 v[16:19], v[174:177], v[236:239], v[16:19]
	v_mfma_f32_16x16x32_bf16 v[4:7], v[166:169], v[244:247], v[4:7]
	v_mfma_f32_16x16x32_bf16 v[0:3], v[174:177], v[244:247], v[0:3]
	v_mfma_f32_16x16x32_bf16 v[52:55], v[170:173], v[224:227], v[52:55]
	v_mfma_f32_16x16x32_bf16 v[48:51], v[178:181], v[224:227], v[48:51]
	v_mfma_f32_16x16x32_bf16 v[36:39], v[170:173], v[232:235], v[36:39]
	v_mfma_f32_16x16x32_bf16 v[32:35], v[178:181], v[232:235], v[32:35]
	v_mfma_f32_16x16x32_bf16 v[20:23], v[170:173], v[240:243], v[20:23]
	v_mfma_f32_16x16x32_bf16 v[16:19], v[178:181], v[240:243], v[16:19]
	v_mfma_f32_16x16x32_bf16 v[4:7], v[170:173], v[248:251], v[4:7]
	v_mfma_f32_16x16x32_bf16 v[0:3], v[178:181], v[248:251], v[0:3]
	s_setprio 0
	s_waitcnt vmcnt(0)
	s_barrier
	s_add_i32 s56, s56, 2
	s_add_u32 s12, s12, 0x100
	s_addc_u32 s13, s13, 0
	s_add_u32 s54, s54, 0x100
	s_addc_u32 s55, s55, 0
	s_cmp_gt_u32 s56, 13
	s_cbranch_scc0 .LBB0_686
.Lk64_done_p4:
	s_and_b64 vcc, exec, s[4:5]
	s_cbranch_vccz .LBB0_689
	s_barrier

.LBB0_751:
	v_bfe_u32 v16, v9, 4, 2
	v_and_b32_e32 v15, 15, v9
	v_lshlrev_b32_e32 v17, 4, v16
	v_lshlrev_b32_e32 v9, 2, v9
	v_lshl_or_b32 v150, s0, 6, v15
	v_lshl_or_b32 v15, v15, 6, v17
	s_lshl_b32 s0, s0, 13
	v_and_b32_e32 v9, 32, v9
	v_bitop3_b32 v17, v15, s0, v9 bitop3:0xde
	s_lshl_b32 s0, s1, 5
	s_mov_b64 s[6:7], 0x80
	s_and_b32 s12, s0, 0x60
	s_add_i32 m0, s44, 0x18000
	v_lshl_add_u64 v[6:7], v[6:7], 0, s[6:7]
	s_lshl_b32 s0, s12, 7
	s_waitcnt vmcnt(0)
	s_barrier
	s_add_u32 vcc_lo, s34, 0x80080
	s_addc_u32 vcc_hi, s35, 0
	s_add_i32 m0, s44, 0xc000
	s_nop 0
	global_load_lds_dwordx4 v128, vcc
	s_add_i32 m0, s44, 0x18000
	s_nop 0
	global_load_lds_dwordx4 v[6:7], off
	v_lshl_add_u64 v[4:5], v[4:5], 0, s[6:7]
	s_add_i32 m0, s44, 0x1a000
	s_add_i32 s49, s44, 0x8000
	s_add_i32 s51, s44, 0xa000
	v_bitop3_b32 v151, v15, s0, v9 bitop3:0xde
	global_load_lds_dwordx4 v[4:5], off
	v_lshl_add_u64 v[0:1], v[0:1], 0, s[6:7]
	s_mov_b32 m0, s49
	s_add_u32 s0, s36, 0x80080
	global_load_lds_dwordx4 v[0:1], off
	v_lshl_add_u64 v[0:1], v[2:3], 0, s[6:7]
	s_mov_b32 m0, s51
	s_addc_u32 s1, s37, 0
	global_load_lds_dwordx4 v[0:1], off
	s_add_i32 m0, s44, 0x1c000
	v_lshl_add_u64 v[0:1], s[0:1], 0, v[130:131]
	global_load_lds_dwordx4 v[0:1], off
	v_lshl_add_u64 v[0:1], s[0:1], 0, v[134:135]
	s_add_i32 m0, s44, 0x1e000
	s_cmpk_lt_u32 s10, 0x100
	global_load_lds_dwordx4 v[0:1], off
	v_lshlrev_b32_e32 v0, 15, v8
	v_and_b32_e32 v0, 0xffff0000, v0
	v_lshl_add_u32 v0, v10, 12, v0
	v_and_b32_e32 v1, 1, v8
	v_lshl_or_b32 v0, v1, 6, v0
	v_lshl_add_u32 v136, v11, 1, v0
	v_lshlrev_b32_e32 v0, 15, v12
	v_and_b32_e32 v0, 0xffff0000, v0
	v_lshl_add_u32 v0, v13, 12, v0
	v_and_b32_e32 v1, 1, v12
	s_waitcnt vmcnt(6)
	v_lshl_or_b32 v0, v1, 6, v0
	s_cselect_b64 s[10:11], -1, 0
	v_lshl_add_u32 v138, v14, 1, v0
	s_add_i32 s54, 0, 0x10000
	s_add_i32 s55, 0, 0x14000
	v_mbcnt_lo_u32_b32 v0, -1, 0
	v_cmp_eq_u32_e64 s[0:1], 0, v16
	v_lshl_or_b32 v152, v16, 3, s12
	v_mov_b32_e32 v137, v131
	v_mov_b32_e32 v139, v131
	v_mov_b64_e32 v[140:141], 0x100
	v_mov_b64_e32 v[142:143], 0xff
	v_add_u32_e32 v153, s54, v151
	v_add_u32_e32 v154, s55, v151
	v_add_u32_e32 v155, 0, v17
	v_mbcnt_hi_u32_b32 v156, -1, v0
	s_barrier
	s_branch .LBB0_754

.LBB0_761:
	s_add_u32 s36, s34, 0xfff80080
	s_addc_u32 s37, s35, -1
	s_cmp_eq_u32 s58, 28
	s_cselect_b32 s43, s23, s37
	s_cselect_b32 s42, s29, s36
	s_cselect_b32 s37, s13, s57
	s_cselect_b32 s36, s31, s56
	s_and_b64 vcc, exec, s[10:11]
	s_cbranch_vccz .Lk64_trail_p5
	s_sub_u32 vcc_lo, s56, 0x80
	s_subb_u32 vcc_hi, s57, 0
	s_add_i32 m0, s44, 0x18000
	s_nop 0
	global_load_lds_dwordx4 v130, vcc
	s_add_i32 m0, s44, 0x1a000
	s_nop 0
	global_load_lds_dwordx4 v134, vcc
	s_add_u32 vcc_lo, vcc_lo, 0x20000
	s_addc_u32 vcc_hi, vcc_hi, 0
	s_add_i32 m0, s44, 0x19000
	s_nop 0
	global_load_lds_dwordx4 v130, vcc
	s_add_i32 m0, s44, 0x1b000
	s_nop 0
	global_load_lds_dwordx4 v134, vcc
	s_add_u32 vcc_lo, vcc_lo, 0x60000
	s_addc_u32 vcc_hi, vcc_hi, 0
	s_add_i32 m0, s44, 0x1c000
	s_nop 0
	global_load_lds_dwordx4 v130, vcc
	s_add_i32 m0, s44, 0x1e000
	s_nop 0
	global_load_lds_dwordx4 v134, vcc
	s_add_u32 vcc_lo, vcc_lo, 0x20000
	s_addc_u32 vcc_hi, vcc_hi, 0
	s_add_i32 m0, s44, 0x1d000
	s_nop 0
	global_load_lds_dwordx4 v130, vcc
	s_add_i32 m0, s44, 0x1f000
	s_nop 0
	global_load_lds_dwordx4 v134, vcc
	ds_read_b128 v[144:147], v153 offset:0
	ds_read_b128 v[158:161], v153 offset:1024
	ds_read_b128 v[162:165], v153 offset:2048
	ds_read_b128 v[166:169], v153 offset:3072
	ds_read_b128 v[170:173], v154 offset:0
	ds_read_b128 v[174:177], v154 offset:1024
	ds_read_b128 v[178:181], v154 offset:2048
	ds_read_b128 v[182:185], v154 offset:3072
	ds_read_b128 v[186:189], v155 offset:0
	ds_read_b128 v[190:193], v155 offset:1024
	ds_read_b128 v[194:197], v155 offset:2048
	ds_read_b128 v[198:201], v155 offset:3072
	ds_read_b128 v[202:205], v155 offset:4096
	ds_read_b128 v[206:209], v155 offset:5120
	ds_read_b128 v[210:213], v155 offset:6144
	ds_read_b128 v[214:217], v155 offset:7168
	ds_read_b128 v[220:223], v155 offset:16384
	ds_read_b128 v[224:227], v155 offset:17408
	ds_read_b128 v[228:231], v155 offset:18432
	ds_read_b128 v[232:235], v155 offset:19456
	ds_read_b128 v[236:239], v155 offset:20480
	ds_read_b128 v[240:243], v155 offset:21504
	ds_read_b128 v[244:247], v155 offset:22528
	ds_read_b128 v[248:251], v155 offset:23552
	s_nop 15
	s_nop 15
	s_waitcnt lgkmcnt(0)
	s_barrier
	s_setprio 1
	v_mfma_f32_16x16x32_bf16 v[124:127], v[144:147], v[186:189], v[124:127]
	v_mfma_f32_16x16x32_bf16 v[120:123], v[162:165], v[186:189], v[120:123]
	v_mfma_f32_16x16x32_bf16 v[108:111], v[144:147], v[194:197], v[108:111]
	v_mfma_f32_16x16x32_bf16 v[104:107], v[162:165], v[194:197], v[104:107]
	v_mfma_f32_16x16x32_bf16 v[92:95], v[144:147], v[202:205], v[92:95]
	v_mfma_f32_16x16x32_bf16 v[88:91], v[162:165], v[202:205], v[88:91]
	v_mfma_f32_16x16x32_bf16 v[76:79], v[144:147], v[210:213], v[76:79]
	v_mfma_f32_16x16x32_bf16 v[72:75], v[162:165], v[210:213], v[72:75]
	v_mfma_f32_16x16x32_bf16 v[124:127], v[158:161], v[190:193], v[124:127]
	v_mfma_f32_16x16x32_bf16 v[120:123], v[166:169], v[190:193], v[120:123]
	v_mfma_f32_16x16x32_bf16 v[108:111], v[158:161], v[198:201], v[108:111]
	v_mfma_f32_16x16x32_bf16 v[104:107], v[166:169], v[198:201], v[104:107]
	v_mfma_f32_16x16x32_bf16 v[92:95], v[158:161], v[206:209], v[92:95]
	v_mfma_f32_16x16x32_bf16 v[88:91], v[166:169], v[206:209], v[88:91]
	v_mfma_f32_16x16x32_bf16 v[76:79], v[158:161], v[214:217], v[76:79]
	v_mfma_f32_16x16x32_bf16 v[72:75], v[166:169], v[214:217], v[72:75]
	s_setprio 0
	s_setprio 1
	v_mfma_f32_16x16x32_bf16 v[116:119], v[170:173], v[186:189], v[116:119]
	v_mfma_f32_16x16x32_bf16 v[112:115], v[178:181], v[186:189], v[112:115]
	v_mfma_f32_16x16x32_bf16 v[100:103], v[170:173], v[194:197], v[100:103]
	v_mfma_f32_16x16x32_bf16 v[96:99], v[178:181], v[194:197], v[96:99]
	v_mfma_f32_16x16x32_bf16 v[84:87], v[170:173], v[202:205], v[84:87]
	v_mfma_f32_16x16x32_bf16 v[80:83], v[178:181], v[202:205], v[80:83]
	v_mfma_f32_16x16x32_bf16 v[68:71], v[170:173], v[210:213], v[68:71]
	v_mfma_f32_16x16x32_bf16 v[64:67], v[178:181], v[210:213], v[64:67]
	v_mfma_f32_16x16x32_bf16 v[116:119], v[174:177], v[190:193], v[116:119]
	v_mfma_f32_16x16x32_bf16 v[112:115], v[182:185], v[190:193], v[112:115]
	v_mfma_f32_16x16x32_bf16 v[100:103], v[174:177], v[198:201], v[100:103]
	v_mfma_f32_16x16x32_bf16 v[96:99], v[182:185], v[198:201], v[96:99]
	v_mfma_f32_16x16x32_bf16 v[84:87], v[174:177], v[206:209], v[84:87]
	v_mfma_f32_16x16x32_bf16 v[80:83], v[182:185], v[206:209], v[80:83]
	v_mfma_f32_16x16x32_bf16 v[68:71], v[174:177], v[214:217], v[68:71]
	v_mfma_f32_16x16x32_bf16 v[64:67], v[182:185], v[214:217], v[64:67]
	s_setprio 0
	s_setprio 1
	v_mfma_f32_16x16x32_bf16 v[60:63], v[144:147], v[220:223], v[60:63]
	v_mfma_f32_16x16x32_bf16 v[56:59], v[162:165], v[220:223], v[56:59]
	v_mfma_f32_16x16x32_bf16 v[44:47], v[144:147], v[228:231], v[44:47]
	v_mfma_f32_16x16x32_bf16 v[40:43], v[162:165], v[228:231], v[40:43]
	v_mfma_f32_16x16x32_bf16 v[28:31], v[144:147], v[236:239], v[28:31]
	v_mfma_f32_16x16x32_bf16 v[24:27], v[162:165], v[236:239], v[24:27]
	v_mfma_f32_16x16x32_bf16 v[12:15], v[144:147], v[244:247], v[12:15]
	v_mfma_f32_16x16x32_bf16 v[8:11], v[162:165], v[244:247], v[8:11]
	v_mfma_f32_16x16x32_bf16 v[60:63], v[158:161], v[224:227], v[60:63]
	v_mfma_f32_16x16x32_bf16 v[56:59], v[166:169], v[224:227], v[56:59]
	v_mfma_f32_16x16x32_bf16 v[44:47], v[158:161], v[232:235], v[44:47]
	v_mfma_f32_16x16x32_bf16 v[40:43], v[166:169], v[232:235], v[40:43]
	v_mfma_f32_16x16x32_bf16 v[28:31], v[158:161], v[240:243], v[28:31]
	v_mfma_f32_16x16x32_bf16 v[24:27], v[166:169], v[240:243], v[24:27]
	v_mfma_f32_16x16x32_bf16 v[12:15], v[158:161], v[248:251], v[12:15]
	v_mfma_f32_16x16x32_bf16 v[8:11], v[166:169], v[248:251], v[8:11]
	s_setprio 0
	s_setprio 1
	v_mfma_f32_16x16x32_bf16 v[52:55], v[170:173], v[220:223], v[52:55]
	v_mfma_f32_16x16x32_bf16 v[48:51], v[178:181], v[220:223], v[48:51]
	v_mfma_f32_16x16x32_bf16 v[36:39], v[170:173], v[228:231], v[36:39]
	v_mfma_f32_16x16x32_bf16 v[32:35], v[178:181], v[228:231], v[32:35]
	v_mfma_f32_16x16x32_bf16 v[20:23], v[170:173], v[236:239], v[20:23]
	v_mfma_f32_16x16x32_bf16 v[16:19], v[178:181], v[236:239], v[16:19]
	v_mfma_f32_16x16x32_bf16 v[4:7], v[170:173], v[244:247], v[4:7]
	v_mfma_f32_16x16x32_bf16 v[0:3], v[178:181], v[244:247], v[0:3]
	v_mfma_f32_16x16x32_bf16 v[52:55], v[174:177], v[224:227], v[52:55]
	v_mfma_f32_16x16x32_bf16 v[48:51], v[182:185], v[224:227], v[48:51]
	v_mfma_f32_16x16x32_bf16 v[36:39], v[174:177], v[232:235], v[36:39]
	v_mfma_f32_16x16x32_bf16 v[32:35], v[182:185], v[232:235], v[32:35]
	v_mfma_f32_16x16x32_bf16 v[20:23], v[174:177], v[240:243], v[20:23]
	v_mfma_f32_16x16x32_bf16 v[16:19], v[182:185], v[240:243], v[16:19]
	v_mfma_f32_16x16x32_bf16 v[4:7], v[174:177], v[248:251], v[4:7]
	v_mfma_f32_16x16x32_bf16 v[0:3], v[182:185], v[248:251], v[0:3]
	s_setprio 0
	s_waitcnt vmcnt(0)
	s_barrier
	s_add_u32 vcc_lo, s36, 0x0
	s_addc_u32 vcc_hi, s37, 0
	s_add_i32 m0, s44, 0x10000
	s_nop 0
	global_load_lds_dwordx4 v130, vcc
	s_add_i32 m0, s44, 0x12000
	s_nop 0
	global_load_lds_dwordx4 v134, vcc
	s_add_u32 vcc_lo, vcc_lo, 0x20000
	s_addc_u32 vcc_hi, vcc_hi, 0
	s_add_i32 m0, s44, 0x11000
	s_nop 0
	global_load_lds_dwordx4 v130, vcc
	s_add_i32 m0, s44, 0x13000
	s_nop 0
	global_load_lds_dwordx4 v134, vcc
	s_add_u32 vcc_lo, vcc_lo, 0x60000
	s_addc_u32 vcc_hi, vcc_hi, 0
	s_add_i32 m0, s44, 0x14000
	s_nop 0
	global_load_lds_dwordx4 v130, vcc
	s_add_i32 m0, s44, 0x16000
	s_nop 0
	global_load_lds_dwordx4 v134, vcc
	s_add_u32 vcc_lo, vcc_lo, 0x20000
	s_addc_u32 vcc_hi, vcc_hi, 0
	s_add_i32 m0, s44, 0x15000
	s_nop 0
	global_load_lds_dwordx4 v130, vcc
	s_add_i32 m0, s44, 0x17000
	s_nop 0
	global_load_lds_dwordx4 v134, vcc
	ds_read_b128 v[144:147], v153 offset:32768
	ds_read_b128 v[158:161], v153 offset:33792
	ds_read_b128 v[162:165], v153 offset:34816
	ds_read_b128 v[166:169], v153 offset:35840
	ds_read_b128 v[170:173], v154 offset:32768
	ds_read_b128 v[174:177], v154 offset:33792
	ds_read_b128 v[178:181], v154 offset:34816
	ds_read_b128 v[182:185], v154 offset:35840
	ds_read_b128 v[186:189], v155 offset:32768
	ds_read_b128 v[190:193], v155 offset:33792
	ds_read_b128 v[194:197], v155 offset:34816
	ds_read_b128 v[198:201], v155 offset:35840
	ds_read_b128 v[202:205], v155 offset:36864
	ds_read_b128 v[206:209], v155 offset:37888
	ds_read_b128 v[210:213], v155 offset:38912
	ds_read_b128 v[214:217], v155 offset:39936
	ds_read_b128 v[220:223], v155 offset:49152
	ds_read_b128 v[224:227], v155 offset:50176
	ds_read_b128 v[228:231], v155 offset:51200
	ds_read_b128 v[232:235], v155 offset:52224
	ds_read_b128 v[236:239], v155 offset:53248
	ds_read_b128 v[240:243], v155 offset:54272
	ds_read_b128 v[244:247], v155 offset:55296
	ds_read_b128 v[248:251], v155 offset:56320
	s_nop 15
	s_nop 15
	s_waitcnt lgkmcnt(0)
	s_barrier
	s_setprio 1
	v_mfma_f32_16x16x32_bf16 v[124:127], v[144:147], v[186:189], v[124:127]
	v_mfma_f32_16x16x32_bf16 v[120:123], v[162:165], v[186:189], v[120:123]
	v_mfma_f32_16x16x32_bf16 v[108:111], v[144:147], v[194:197], v[108:111]
	v_mfma_f32_16x16x32_bf16 v[104:107], v[162:165], v[194:197], v[104:107]
	v_mfma_f32_16x16x32_bf16 v[92:95], v[144:147], v[202:205], v[92:95]
	v_mfma_f32_16x16x32_bf16 v[88:91], v[162:165], v[202:205], v[88:91]
	v_mfma_f32_16x16x32_bf16 v[76:79], v[144:147], v[210:213], v[76:79]
	v_mfma_f32_16x16x32_bf16 v[72:75], v[162:165], v[210:213], v[72:75]
	v_mfma_f32_16x16x32_bf16 v[124:127], v[158:161], v[190:193], v[124:127]
	v_mfma_f32_16x16x32_bf16 v[120:123], v[166:169], v[190:193], v[120:123]
	v_mfma_f32_16x16x32_bf16 v[108:111], v[158:161], v[198:201], v[108:111]
	v_mfma_f32_16x16x32_bf16 v[104:107], v[166:169], v[198:201], v[104:107]
	v_mfma_f32_16x16x32_bf16 v[92:95], v[158:161], v[206:209], v[92:95]
	v_mfma_f32_16x16x32_bf16 v[88:91], v[166:169], v[206:209], v[88:91]
	v_mfma_f32_16x16x32_bf16 v[76:79], v[158:161], v[214:217], v[76:79]
	v_mfma_f32_16x16x32_bf16 v[72:75], v[166:169], v[214:217], v[72:75]
	s_setprio 0
	s_setprio 1
	v_mfma_f32_16x16x32_bf16 v[116:119], v[170:173], v[186:189], v[116:119]
	v_mfma_f32_16x16x32_bf16 v[112:115], v[178:181], v[186:189], v[112:115]
	v_mfma_f32_16x16x32_bf16 v[100:103], v[170:173], v[194:197], v[100:103]
	v_mfma_f32_16x16x32_bf16 v[96:99], v[178:181], v[194:197], v[96:99]
	v_mfma_f32_16x16x32_bf16 v[84:87], v[170:173], v[202:205], v[84:87]
	v_mfma_f32_16x16x32_bf16 v[80:83], v[178:181], v[202:205], v[80:83]
	v_mfma_f32_16x16x32_bf16 v[68:71], v[170:173], v[210:213], v[68:71]
	v_mfma_f32_16x16x32_bf16 v[64:67], v[178:181], v[210:213], v[64:67]
	v_mfma_f32_16x16x32_bf16 v[116:119], v[174:177], v[190:193], v[116:119]
	v_mfma_f32_16x16x32_bf16 v[112:115], v[182:185], v[190:193], v[112:115]
	v_mfma_f32_16x16x32_bf16 v[100:103], v[174:177], v[198:201], v[100:103]
	v_mfma_f32_16x16x32_bf16 v[96:99], v[182:185], v[198:201], v[96:99]
	v_mfma_f32_16x16x32_bf16 v[84:87], v[174:177], v[206:209], v[84:87]
	v_mfma_f32_16x16x32_bf16 v[80:83], v[182:185], v[206:209], v[80:83]
	v_mfma_f32_16x16x32_bf16 v[68:71], v[174:177], v[214:217], v[68:71]
	v_mfma_f32_16x16x32_bf16 v[64:67], v[182:185], v[214:217], v[64:67]
	s_setprio 0
	s_setprio 1
	v_mfma_f32_16x16x32_bf16 v[60:63], v[144:147], v[220:223], v[60:63]
	v_mfma_f32_16x16x32_bf16 v[56:59], v[162:165], v[220:223], v[56:59]
	v_mfma_f32_16x16x32_bf16 v[44:47], v[144:147], v[228:231], v[44:47]
	v_mfma_f32_16x16x32_bf16 v[40:43], v[162:165], v[228:231], v[40:43]
	v_mfma_f32_16x16x32_bf16 v[28:31], v[144:147], v[236:239], v[28:31]
	v_mfma_f32_16x16x32_bf16 v[24:27], v[162:165], v[236:239], v[24:27]
	v_mfma_f32_16x16x32_bf16 v[12:15], v[144:147], v[244:247], v[12:15]
	v_mfma_f32_16x16x32_bf16 v[8:11], v[162:165], v[244:247], v[8:11]
	v_mfma_f32_16x16x32_bf16 v[60:63], v[158:161], v[224:227], v[60:63]
	v_mfma_f32_16x16x32_bf16 v[56:59], v[166:169], v[224:227], v[56:59]
	v_mfma_f32_16x16x32_bf16 v[44:47], v[158:161], v[232:235], v[44:47]
	v_mfma_f32_16x16x32_bf16 v[40:43], v[166:169], v[232:235], v[40:43]
	v_mfma_f32_16x16x32_bf16 v[28:31], v[158:161], v[240:243], v[28:31]
	v_mfma_f32_16x16x32_bf16 v[24:27], v[166:169], v[240:243], v[24:27]
	v_mfma_f32_16x16x32_bf16 v[12:15], v[158:161], v[248:251], v[12:15]
	v_mfma_f32_16x16x32_bf16 v[8:11], v[166:169], v[248:251], v[8:11]
	s_setprio 0
	s_setprio 1
	v_mfma_f32_16x16x32_bf16 v[52:55], v[170:173], v[220:223], v[52:55]
	v_mfma_f32_16x16x32_bf16 v[48:51], v[178:181], v[220:223], v[48:51]
	v_mfma_f32_16x16x32_bf16 v[36:39], v[170:173], v[228:231], v[36:39]
	v_mfma_f32_16x16x32_bf16 v[32:35], v[178:181], v[228:231], v[32:35]
	v_mfma_f32_16x16x32_bf16 v[20:23], v[170:173], v[236:239], v[20:23]
	v_mfma_f32_16x16x32_bf16 v[16:19], v[178:181], v[236:239], v[16:19]
	v_mfma_f32_16x16x32_bf16 v[4:7], v[170:173], v[244:247], v[4:7]
	v_mfma_f32_16x16x32_bf16 v[0:3], v[178:181], v[244:247], v[0:3]
	v_mfma_f32_16x16x32_bf16 v[52:55], v[174:177], v[224:227], v[52:55]
	v_mfma_f32_16x16x32_bf16 v[48:51], v[182:185], v[224:227], v[48:51]
	v_mfma_f32_16x16x32_bf16 v[36:39], v[174:177], v[232:235], v[36:39]
	v_mfma_f32_16x16x32_bf16 v[32:35], v[182:185], v[232:235], v[32:35]
	v_mfma_f32_16x16x32_bf16 v[20:23], v[174:177], v[240:243], v[20:23]
	v_mfma_f32_16x16x32_bf16 v[16:19], v[182:185], v[240:243], v[16:19]
	v_mfma_f32_16x16x32_bf16 v[4:7], v[174:177], v[248:251], v[4:7]
	v_mfma_f32_16x16x32_bf16 v[0:3], v[182:185], v[248:251], v[0:3]
	s_setprio 0
	s_waitcnt vmcnt(0)
	s_barrier
	s_add_i32 s58, s58, 2
	s_add_u32 s34, s34, 0x100
	s_addc_u32 s35, s35, 0
	s_add_u32 s56, s56, 0x100
	s_addc_u32 s57, s57, 0
	s_cmp_gt_u32 s58, 29
	s_cbranch_scc0 .LBB0_761
	s_branch .Lk64_done_p5
.Lk64_trail_p5:
	s_sub_u32 vcc_lo, s34, 0x80000
	s_subb_u32 vcc_hi, s35, 0
	s_add_i32 m0, s44, 0xa000
	s_nop 0
	global_load_lds_dwordx4 v132, vcc
	s_add_u32 vcc_lo, vcc_lo, 0x20000
	s_addc_u32 vcc_hi, vcc_hi, 0
	s_add_i32 m0, s44, 0x9000
	s_nop 0
	global_load_lds_dwordx4 v128, vcc
	s_add_u32 vcc_lo, vcc_lo, 0x60000
	s_addc_u32 vcc_hi, vcc_hi, 0
	s_add_i32 m0, s44, 0xe000
	s_nop 0
	global_load_lds_dwordx4 v132, vcc
	s_add_u32 vcc_lo, vcc_lo, 0x20000
	s_addc_u32 vcc_hi, vcc_hi, 0
	s_add_i32 m0, s44, 0xd000
	s_nop 0
	global_load_lds_dwordx4 v128, vcc
	s_add_u32 vcc_lo, s42, 0x0
	s_addc_u32 vcc_hi, s43, 0
	s_mov_b32 m0, s44
	s_nop 0
	global_load_lds_dwordx4 v128, vcc
	s_sub_u32 vcc_lo, vcc_lo, 0x20000
	s_subb_u32 vcc_hi, vcc_hi, 0
	s_sub_i32 m0, s44, 0x1000
	s_nop 0
	global_load_lds_dwordx4 v128, vcc
	s_add_u32 vcc_lo, vcc_lo, 0xa0000
	s_addc_u32 vcc_hi, vcc_hi, 0
	s_add_i32 m0, s44, 0x4000
	s_nop 0
	global_load_lds_dwordx4 v128, vcc
	s_sub_u32 vcc_lo, vcc_lo, 0x20000
	s_subb_u32 vcc_hi, vcc_hi, 0
	s_add_i32 m0, s44, 0x3000
	s_nop 0
	global_load_lds_dwordx4 v128, vcc
	ds_read_b128 v[144:147], v153 offset:0
	ds_read_b128 v[158:161], v153 offset:1024
	ds_read_b128 v[162:165], v153 offset:2048
	ds_read_b128 v[166:169], v153 offset:3072
	ds_read_b128 v[170:173], v154 offset:0
	ds_read_b128 v[174:177], v154 offset:1024
	ds_read_b128 v[178:181], v154 offset:2048
	ds_read_b128 v[182:185], v154 offset:3072
	ds_read_b128 v[186:189], v155 offset:0
	ds_read_b128 v[190:193], v155 offset:1024
	ds_read_b128 v[194:197], v155 offset:2048
	ds_read_b128 v[198:201], v155 offset:3072
	ds_read_b128 v[202:205], v155 offset:4096
	ds_read_b128 v[206:209], v155 offset:5120
	ds_read_b128 v[210:213], v155 offset:6144
	ds_read_b128 v[214:217], v155 offset:7168
	ds_read_b128 v[220:223], v155 offset:16384
	ds_read_b128 v[224:227], v155 offset:17408
	ds_read_b128 v[228:231], v155 offset:18432
	ds_read_b128 v[232:235], v155 offset:19456
	ds_read_b128 v[236:239], v155 offset:20480
	ds_read_b128 v[240:243], v155 offset:21504
	ds_read_b128 v[244:247], v155 offset:22528
	ds_read_b128 v[248:251], v155 offset:23552
	s_nop 15
	s_nop 15
	s_waitcnt lgkmcnt(0)
	s_barrier
	s_setprio 1
	v_mfma_f32_16x16x32_bf16 v[124:127], v[144:147], v[186:189], v[124:127]
	v_mfma_f32_16x16x32_bf16 v[120:123], v[162:165], v[186:189], v[120:123]
	v_mfma_f32_16x16x32_bf16 v[108:111], v[144:147], v[194:197], v[108:111]
	v_mfma_f32_16x16x32_bf16 v[104:107], v[162:165], v[194:197], v[104:107]
	v_mfma_f32_16x16x32_bf16 v[92:95], v[144:147], v[202:205], v[92:95]
	v_mfma_f32_16x16x32_bf16 v[88:91], v[162:165], v[202:205], v[88:91]
	v_mfma_f32_16x16x32_bf16 v[76:79], v[144:147], v[210:213], v[76:79]
	v_mfma_f32_16x16x32_bf16 v[72:75], v[162:165], v[210:213], v[72:75]
	v_mfma_f32_16x16x32_bf16 v[124:127], v[158:161], v[190:193], v[124:127]
	v_mfma_f32_16x16x32_bf16 v[120:123], v[166:169], v[190:193], v[120:123]
	v_mfma_f32_16x16x32_bf16 v[108:111], v[158:161], v[198:201], v[108:111]
	v_mfma_f32_16x16x32_bf16 v[104:107], v[166:169], v[198:201], v[104:107]
	v_mfma_f32_16x16x32_bf16 v[92:95], v[158:161], v[206:209], v[92:95]
	v_mfma_f32_16x16x32_bf16 v[88:91], v[166:169], v[206:209], v[88:91]
	v_mfma_f32_16x16x32_bf16 v[76:79], v[158:161], v[214:217], v[76:79]
	v_mfma_f32_16x16x32_bf16 v[72:75], v[166:169], v[214:217], v[72:75]
	s_setprio 0
	s_setprio 1
	v_mfma_f32_16x16x32_bf16 v[116:119], v[170:173], v[186:189], v[116:119]
	v_mfma_f32_16x16x32_bf16 v[112:115], v[178:181], v[186:189], v[112:115]
	v_mfma_f32_16x16x32_bf16 v[100:103], v[170:173], v[194:197], v[100:103]
	v_mfma_f32_16x16x32_bf16 v[96:99], v[178:181], v[194:197], v[96:99]
	v_mfma_f32_16x16x32_bf16 v[84:87], v[170:173], v[202:205], v[84:87]
	v_mfma_f32_16x16x32_bf16 v[80:83], v[178:181], v[202:205], v[80:83]
	v_mfma_f32_16x16x32_bf16 v[68:71], v[170:173], v[210:213], v[68:71]
	v_mfma_f32_16x16x32_bf16 v[64:67], v[178:181], v[210:213], v[64:67]
	v_mfma_f32_16x16x32_bf16 v[116:119], v[174:177], v[190:193], v[116:119]
	v_mfma_f32_16x16x32_bf16 v[112:115], v[182:185], v[190:193], v[112:115]
	v_mfma_f32_16x16x32_bf16 v[100:103], v[174:177], v[198:201], v[100:103]
	v_mfma_f32_16x16x32_bf16 v[96:99], v[182:185], v[198:201], v[96:99]
	v_mfma_f32_16x16x32_bf16 v[84:87], v[174:177], v[206:209], v[84:87]
	v_mfma_f32_16x16x32_bf16 v[80:83], v[182:185], v[206:209], v[80:83]
	v_mfma_f32_16x16x32_bf16 v[68:71], v[174:177], v[214:217], v[68:71]
	v_mfma_f32_16x16x32_bf16 v[64:67], v[182:185], v[214:217], v[64:67]
	s_setprio 0
	s_setprio 1
	v_mfma_f32_16x16x32_bf16 v[60:63], v[144:147], v[220:223], v[60:63]
	v_mfma_f32_16x16x32_bf16 v[56:59], v[162:165], v[220:223], v[56:59]
	v_mfma_f32_16x16x32_bf16 v[44:47], v[144:147], v[228:231], v[44:47]
	v_mfma_f32_16x16x32_bf16 v[40:43], v[162:165], v[228:231], v[40:43]
	v_mfma_f32_16x16x32_bf16 v[28:31], v[144:147], v[236:239], v[28:31]
	v_mfma_f32_16x16x32_bf16 v[24:27], v[162:165], v[236:239], v[24:27]
	v_mfma_f32_16x16x32_bf16 v[12:15], v[144:147], v[244:247], v[12:15]
	v_mfma_f32_16x16x32_bf16 v[8:11], v[162:165], v[244:247], v[8:11]
	v_mfma_f32_16x16x32_bf16 v[60:63], v[158:161], v[224:227], v[60:63]
	v_mfma_f32_16x16x32_bf16 v[56:59], v[166:169], v[224:227], v[56:59]
	v_mfma_f32_16x16x32_bf16 v[44:47], v[158:161], v[232:235], v[44:47]
	v_mfma_f32_16x16x32_bf16 v[40:43], v[166:169], v[232:235], v[40:43]
	v_mfma_f32_16x16x32_bf16 v[28:31], v[158:161], v[240:243], v[28:31]
	v_mfma_f32_16x16x32_bf16 v[24:27], v[166:169], v[240:243], v[24:27]
	v_mfma_f32_16x16x32_bf16 v[12:15], v[158:161], v[248:251], v[12:15]
	v_mfma_f32_16x16x32_bf16 v[8:11], v[166:169], v[248:251], v[8:11]
	s_setprio 0
	s_setprio 1
	v_mfma_f32_16x16x32_bf16 v[52:55], v[170:173], v[220:223], v[52:55]
	v_mfma_f32_16x16x32_bf16 v[48:51], v[178:181], v[220:223], v[48:51]
	v_mfma_f32_16x16x32_bf16 v[36:39], v[170:173], v[228:231], v[36:39]
	v_mfma_f32_16x16x32_bf16 v[32:35], v[178:181], v[228:231], v[32:35]
	v_mfma_f32_16x16x32_bf16 v[20:23], v[170:173], v[236:239], v[20:23]
	v_mfma_f32_16x16x32_bf16 v[16:19], v[178:181], v[236:239], v[16:19]
	v_mfma_f32_16x16x32_bf16 v[4:7], v[170:173], v[244:247], v[4:7]
	v_mfma_f32_16x16x32_bf16 v[0:3], v[178:181], v[244:247], v[0:3]
	v_mfma_f32_16x16x32_bf16 v[52:55], v[174:177], v[224:227], v[52:55]
	v_mfma_f32_16x16x32_bf16 v[48:51], v[182:185], v[224:227], v[48:51]
	v_mfma_f32_16x16x32_bf16 v[36:39], v[174:177], v[232:235], v[36:39]
	v_mfma_f32_16x16x32_bf16 v[32:35], v[182:185], v[232:235], v[32:35]
	v_mfma_f32_16x16x32_bf16 v[20:23], v[174:177], v[240:243], v[20:23]
	v_mfma_f32_16x16x32_bf16 v[16:19], v[182:185], v[240:243], v[16:19]
	v_mfma_f32_16x16x32_bf16 v[4:7], v[174:177], v[248:251], v[4:7]
	v_mfma_f32_16x16x32_bf16 v[0:3], v[182:185], v[248:251], v[0:3]
	s_setprio 0
	s_waitcnt vmcnt(0)
	s_barrier
	s_add_u32 vcc_lo, s42, 0x0
	s_addc_u32 vcc_hi, s43, 0
	s_add_i32 m0, s44, 0x2000
	s_nop 0
	global_load_lds_dwordx4 v132, vcc
	s_add_u32 vcc_lo, vcc_lo, 0x20000
	s_addc_u32 vcc_hi, vcc_hi, 0
	s_add_i32 m0, s44, 0x1000
	s_nop 0
	global_load_lds_dwordx4 v128, vcc
	s_add_u32 vcc_lo, vcc_lo, 0x60000
	s_addc_u32 vcc_hi, vcc_hi, 0
	s_add_i32 m0, s44, 0x6000
	s_nop 0
	global_load_lds_dwordx4 v132, vcc
	s_add_u32 vcc_lo, vcc_lo, 0x20000
	s_addc_u32 vcc_hi, vcc_hi, 0
	s_add_i32 m0, s44, 0x5000
	s_nop 0
	global_load_lds_dwordx4 v128, vcc
	s_add_u32 vcc_lo, s42, 0x80
	s_addc_u32 vcc_hi, s43, 0
	s_add_i32 m0, s44, 0x8000
	s_nop 0
	global_load_lds_dwordx4 v128, vcc
	s_sub_u32 vcc_lo, vcc_lo, 0x20000
	s_subb_u32 vcc_hi, vcc_hi, 0
	s_add_i32 m0, s44, 0x7000
	s_nop 0
	global_load_lds_dwordx4 v128, vcc
	s_add_u32 vcc_lo, vcc_lo, 0xa0000
	s_addc_u32 vcc_hi, vcc_hi, 0
	s_add_i32 m0, s44, 0xc000
	s_nop 0
	global_load_lds_dwordx4 v128, vcc
	s_sub_u32 vcc_lo, vcc_lo, 0x20000
	s_subb_u32 vcc_hi, vcc_hi, 0
	s_add_i32 m0, s44, 0xb000
	s_nop 0
	global_load_lds_dwordx4 v128, vcc
	ds_read_b128 v[144:147], v153 offset:32768
	ds_read_b128 v[158:161], v153 offset:33792
	ds_read_b128 v[162:165], v153 offset:34816
	ds_read_b128 v[166:169], v153 offset:35840
	ds_read_b128 v[170:173], v154 offset:32768
	ds_read_b128 v[174:177], v154 offset:33792
	ds_read_b128 v[178:181], v154 offset:34816
	ds_read_b128 v[182:185], v154 offset:35840
	ds_read_b128 v[186:189], v155 offset:32768
	ds_read_b128 v[190:193], v155 offset:33792
	ds_read_b128 v[194:197], v155 offset:34816
	ds_read_b128 v[198:201], v155 offset:35840
	ds_read_b128 v[202:205], v155 offset:36864
	ds_read_b128 v[206:209], v155 offset:37888
	ds_read_b128 v[210:213], v155 offset:38912
	ds_read_b128 v[214:217], v155 offset:39936
	ds_read_b128 v[220:223], v155 offset:49152
	ds_read_b128 v[224:227], v155 offset:50176
	ds_read_b128 v[228:231], v155 offset:51200
	ds_read_b128 v[232:235], v155 offset:52224
	ds_read_b128 v[236:239], v155 offset:53248
	ds_read_b128 v[240:243], v155 offset:54272
	ds_read_b128 v[244:247], v155 offset:55296
	ds_read_b128 v[248:251], v155 offset:56320
	s_nop 15
	s_nop 15
	s_waitcnt lgkmcnt(0)
	s_barrier
	s_setprio 1
	v_mfma_f32_16x16x32_bf16 v[124:127], v[144:147], v[186:189], v[124:127]
	v_mfma_f32_16x16x32_bf16 v[120:123], v[162:165], v[186:189], v[120:123]
	v_mfma_f32_16x16x32_bf16 v[108:111], v[144:147], v[194:197], v[108:111]
	v_mfma_f32_16x16x32_bf16 v[104:107], v[162:165], v[194:197], v[104:107]
	v_mfma_f32_16x16x32_bf16 v[92:95], v[144:147], v[202:205], v[92:95]
	v_mfma_f32_16x16x32_bf16 v[88:91], v[162:165], v[202:205], v[88:91]
	v_mfma_f32_16x16x32_bf16 v[76:79], v[144:147], v[210:213], v[76:79]
	v_mfma_f32_16x16x32_bf16 v[72:75], v[162:165], v[210:213], v[72:75]
	v_mfma_f32_16x16x32_bf16 v[124:127], v[158:161], v[190:193], v[124:127]
	v_mfma_f32_16x16x32_bf16 v[120:123], v[166:169], v[190:193], v[120:123]
	v_mfma_f32_16x16x32_bf16 v[108:111], v[158:161], v[198:201], v[108:111]
	v_mfma_f32_16x16x32_bf16 v[104:107], v[166:169], v[198:201], v[104:107]
	v_mfma_f32_16x16x32_bf16 v[92:95], v[158:161], v[206:209], v[92:95]
	v_mfma_f32_16x16x32_bf16 v[88:91], v[166:169], v[206:209], v[88:91]
	v_mfma_f32_16x16x32_bf16 v[76:79], v[158:161], v[214:217], v[76:79]
	v_mfma_f32_16x16x32_bf16 v[72:75], v[166:169], v[214:217], v[72:75]
	s_setprio 0
	s_setprio 1
	v_mfma_f32_16x16x32_bf16 v[116:119], v[170:173], v[186:189], v[116:119]
	v_mfma_f32_16x16x32_bf16 v[112:115], v[178:181], v[186:189], v[112:115]
	v_mfma_f32_16x16x32_bf16 v[100:103], v[170:173], v[194:197], v[100:103]
	v_mfma_f32_16x16x32_bf16 v[96:99], v[178:181], v[194:197], v[96:99]
	v_mfma_f32_16x16x32_bf16 v[84:87], v[170:173], v[202:205], v[84:87]
	v_mfma_f32_16x16x32_bf16 v[80:83], v[178:181], v[202:205], v[80:83]
	v_mfma_f32_16x16x32_bf16 v[68:71], v[170:173], v[210:213], v[68:71]
	v_mfma_f32_16x16x32_bf16 v[64:67], v[178:181], v[210:213], v[64:67]
	v_mfma_f32_16x16x32_bf16 v[116:119], v[174:177], v[190:193], v[116:119]
	v_mfma_f32_16x16x32_bf16 v[112:115], v[182:185], v[190:193], v[112:115]
	v_mfma_f32_16x16x32_bf16 v[100:103], v[174:177], v[198:201], v[100:103]
	v_mfma_f32_16x16x32_bf16 v[96:99], v[182:185], v[198:201], v[96:99]
	v_mfma_f32_16x16x32_bf16 v[84:87], v[174:177], v[206:209], v[84:87]
	v_mfma_f32_16x16x32_bf16 v[80:83], v[182:185], v[206:209], v[80:83]
	v_mfma_f32_16x16x32_bf16 v[68:71], v[174:177], v[214:217], v[68:71]
	v_mfma_f32_16x16x32_bf16 v[64:67], v[182:185], v[214:217], v[64:67]
	s_setprio 0
	s_setprio 1
	v_mfma_f32_16x16x32_bf16 v[60:63], v[144:147], v[220:223], v[60:63]
	v_mfma_f32_16x16x32_bf16 v[56:59], v[162:165], v[220:223], v[56:59]
	v_mfma_f32_16x16x32_bf16 v[44:47], v[144:147], v[228:231], v[44:47]
	v_mfma_f32_16x16x32_bf16 v[40:43], v[162:165], v[228:231], v[40:43]
	v_mfma_f32_16x16x32_bf16 v[28:31], v[144:147], v[236:239], v[28:31]
	v_mfma_f32_16x16x32_bf16 v[24:27], v[162:165], v[236:239], v[24:27]
	v_mfma_f32_16x16x32_bf16 v[12:15], v[144:147], v[244:247], v[12:15]
	v_mfma_f32_16x16x32_bf16 v[8:11], v[162:165], v[244:247], v[8:11]
	v_mfma_f32_16x16x32_bf16 v[60:63], v[158:161], v[224:227], v[60:63]
	v_mfma_f32_16x16x32_bf16 v[56:59], v[166:169], v[224:227], v[56:59]
	v_mfma_f32_16x16x32_bf16 v[44:47], v[158:161], v[232:235], v[44:47]
	v_mfma_f32_16x16x32_bf16 v[40:43], v[166:169], v[232:235], v[40:43]
	v_mfma_f32_16x16x32_bf16 v[28:31], v[158:161], v[240:243], v[28:31]
	v_mfma_f32_16x16x32_bf16 v[24:27], v[166:169], v[240:243], v[24:27]
	v_mfma_f32_16x16x32_bf16 v[12:15], v[158:161], v[248:251], v[12:15]
	v_mfma_f32_16x16x32_bf16 v[8:11], v[166:169], v[248:251], v[8:11]
	s_setprio 0
	s_setprio 1
	v_mfma_f32_16x16x32_bf16 v[52:55], v[170:173], v[220:223], v[52:55]
	v_mfma_f32_16x16x32_bf16 v[48:51], v[178:181], v[220:223], v[48:51]
	v_mfma_f32_16x16x32_bf16 v[36:39], v[170:173], v[228:231], v[36:39]
	v_mfma_f32_16x16x32_bf16 v[32:35], v[178:181], v[228:231], v[32:35]
	v_mfma_f32_16x16x32_bf16 v[20:23], v[170:173], v[236:239], v[20:23]
	v_mfma_f32_16x16x32_bf16 v[16:19], v[178:181], v[236:239], v[16:19]
	v_mfma_f32_16x16x32_bf16 v[4:7], v[170:173], v[244:247], v[4:7]
	v_mfma_f32_16x16x32_bf16 v[0:3], v[178:181], v[244:247], v[0:3]
	v_mfma_f32_16x16x32_bf16 v[52:55], v[174:177], v[224:227], v[52:55]
	v_mfma_f32_16x16x32_bf16 v[48:51], v[182:185], v[224:227], v[48:51]
	v_mfma_f32_16x16x32_bf16 v[36:39], v[174:177], v[232:235], v[36:39]
	v_mfma_f32_16x16x32_bf16 v[32:35], v[182:185], v[232:235], v[32:35]
	v_mfma_f32_16x16x32_bf16 v[20:23], v[174:177], v[240:243], v[20:23]
	v_mfma_f32_16x16x32_bf16 v[16:19], v[182:185], v[240:243], v[16:19]
	v_mfma_f32_16x16x32_bf16 v[4:7], v[174:177], v[248:251], v[4:7]
	v_mfma_f32_16x16x32_bf16 v[0:3], v[182:185], v[248:251], v[0:3]
	s_setprio 0
	s_waitcnt vmcnt(0)
	s_barrier
	s_add_i32 s58, s58, 2
	s_add_u32 s34, s34, 0x100
	s_addc_u32 s35, s35, 0
	s_add_u32 s56, s56, 0x100
	s_addc_u32 s57, s57, 0
	s_cmp_gt_u32 s58, 29
	s_cbranch_scc0 .LBB0_761
.Lk64_done_p5:
	s_and_b64 vcc, exec, s[10:11]
	s_cbranch_vccz .LBB0_764
	s_barrier

.LBB0_840:
	s_lshl_b32 s6, s6, 5
	s_and_b32 s25, s6, 0x60
	s_mov_b64 s[6:7], 0x80
	s_add_i32 m0, s37, 0x18000
	v_lshl_add_u64 v[6:7], v[6:7], 0, s[6:7]
	s_lshl_b32 s24, s17, 13
	s_lshl_b32 s26, s25, 7
	s_waitcnt vmcnt(0)
	s_barrier
	s_add_u32 vcc_lo, s12, 0x80080
	s_addc_u32 vcc_hi, s13, 0
	s_add_i32 m0, s37, 0xc000
	s_nop 0
	global_load_lds_dwordx4 v150, vcc
	s_add_i32 m0, s37, 0x18000
	s_nop 0
	global_load_lds_dwordx4 v[6:7], off
	v_lshl_add_u64 v[4:5], v[4:5], 0, s[6:7]
	s_add_i32 m0, s37, 0x1a000
	s_add_i32 s45, s37, 0x8000
	s_add_i32 s46, s37, 0xa000
	global_load_lds_dwordx4 v[4:5], off
	v_lshl_add_u64 v[0:1], v[0:1], 0, s[6:7]
	s_mov_b32 m0, s45
	s_add_u32 s22, s30, 0x80080
	global_load_lds_dwordx4 v[0:1], off
	v_lshl_add_u64 v[0:1], v[2:3], 0, s[6:7]
	s_mov_b32 m0, s46
	s_addc_u32 s23, s31, 0
	global_load_lds_dwordx4 v[0:1], off
	s_add_i32 m0, s37, 0x1c000
	v_lshl_add_u64 v[0:1], s[22:23], 0, v[148:149]
	global_load_lds_dwordx4 v[0:1], off
	v_lshl_add_u64 v[0:1], s[22:23], 0, v[144:145]
	s_add_i32 m0, s37, 0x1e000
	s_cmpk_lt_u32 s16, 0x100
	global_load_lds_dwordx4 v[0:1], off
	v_lshrrev_b32_e32 v0, 1, v9
	v_and_b32_e32 v0, 24, v0
	v_and_b32_e32 v1, 15, v9
	v_lshlrev_b32_e32 v2, 1, v0
	v_lshl_or_b32 v166, s17, 6, v1
	v_lshl_or_b32 v1, v1, 6, v2
	v_lshlrev_b32_e32 v2, 2, v9
	v_and_b32_e32 v2, 32, v2
	v_bitop3_b32 v3, v1, s24, v2 bitop3:0xde
	v_bitop3_b32 v167, v1, s26, v2 bitop3:0xde
	v_lshlrev_b32_e32 v1, 15, v13
	v_and_b32_e32 v1, 0xffff0000, v1
	v_lshl_add_u32 v1, v12, 12, v1
	v_and_b32_e32 v2, 1, v13
	v_lshl_or_b32 v1, v2, 6, v1
	v_lshl_add_u32 v154, v14, 1, v1
	v_lshlrev_b32_e32 v1, 15, v8
	v_and_b32_e32 v1, 0xffff0000, v1
	s_waitcnt vmcnt(6)
	v_lshl_add_u32 v1, v10, 12, v1
	v_and_b32_e32 v2, 1, v8
	s_cselect_b64 s[16:17], -1, 0
	v_lshl_or_b32 v1, v2, 6, v1
	s_add_i32 s47, 0, 0x10000
	s_add_i32 s48, 0, 0x14000
	s_sext_i32_i16 s11, s0
	v_or_b32_e32 v168, s25, v0
	v_mov_b32_e32 v155, v153
	v_lshl_add_u32 v156, v11, 1, v1
	v_mov_b32_e32 v157, v153
	v_mov_b64_e32 v[158:159], 0x580
	v_mov_b64_e32 v[160:161], 0x57f
	v_add_u32_e32 v169, s47, v167
	v_add_u32_e32 v170, s48, v167
	v_add_u32_e32 v171, 0, v3
	v_mov_b32_e32 v172, 0x358637bd
	s_movk_i32 s49, 0x2c00
	s_lshl_b32 s0, s25, 1
	v_lshlrev_b32_e32 v152, 1, v0
	s_mov_b32 s51, s1
	s_barrier
	s_branch .LBB0_843

.LBB0_846:
	s_add_u32 s30, s12, 0xfff80080
	s_addc_u32 s31, s13, -1
	s_cmp_eq_u32 s56, 28
	s_cselect_b32 s35, s25, s31
	s_cselect_b32 s34, s52, s30
	s_cselect_b32 s31, s23, s55
	s_cselect_b32 s30, s53, s54
	s_and_b64 vcc, exec, s[16:17]
	s_cbranch_vccz .Lk64_trail_p6
	s_sub_u32 vcc_lo, s54, 0x80
	s_subb_u32 vcc_hi, s55, 0
	s_add_i32 m0, s37, 0x18000
	s_nop 0
	global_load_lds_dwordx4 v148, vcc
	s_add_i32 m0, s37, 0x1a000
	s_nop 0
	global_load_lds_dwordx4 v144, vcc
	s_add_u32 vcc_lo, vcc_lo, 0x20000
	s_addc_u32 vcc_hi, vcc_hi, 0
	s_add_i32 m0, s37, 0x19000
	s_nop 0
	global_load_lds_dwordx4 v148, vcc
	s_add_i32 m0, s37, 0x1b000
	s_nop 0
	global_load_lds_dwordx4 v144, vcc
	s_add_u32 vcc_lo, vcc_lo, 0x60000
	s_addc_u32 vcc_hi, vcc_hi, 0
	s_add_i32 m0, s37, 0x1c000
	s_nop 0
	global_load_lds_dwordx4 v148, vcc
	s_add_i32 m0, s37, 0x1e000
	s_nop 0
	global_load_lds_dwordx4 v144, vcc
	s_add_u32 vcc_lo, vcc_lo, 0x20000
	s_addc_u32 vcc_hi, vcc_hi, 0
	s_add_i32 m0, s37, 0x1d000
	s_nop 0
	global_load_lds_dwordx4 v148, vcc
	s_add_i32 m0, s37, 0x1f000
	s_nop 0
	global_load_lds_dwordx4 v144, vcc
	ds_read_b128 v[32:35], v169 offset:0
	ds_read_b128 v[36:39], v169 offset:1024
	ds_read_b128 v[40:43], v169 offset:2048
	ds_read_b128 v[44:47], v169 offset:3072
	ds_read_b128 v[162:165], v170 offset:0
	ds_read_b128 v[174:177], v170 offset:1024
	ds_read_b128 v[178:181], v170 offset:2048
	ds_read_b128 v[182:185], v170 offset:3072
	ds_read_b128 v[186:189], v171 offset:0
	ds_read_b128 v[190:193], v171 offset:1024
	ds_read_b128 v[194:197], v171 offset:2048
	ds_read_b128 v[198:201], v171 offset:3072
	ds_read_b128 v[202:205], v171 offset:4096
	ds_read_b128 v[206:209], v171 offset:5120
	ds_read_b128 v[210:213], v171 offset:6144
	ds_read_b128 v[214:217], v171 offset:7168
	ds_read_b128 v[220:223], v171 offset:16384
	ds_read_b128 v[224:227], v171 offset:17408
	ds_read_b128 v[228:231], v171 offset:18432
	ds_read_b128 v[232:235], v171 offset:19456
	ds_read_b128 v[236:239], v171 offset:20480
	ds_read_b128 v[240:243], v171 offset:21504
	ds_read_b128 v[244:247], v171 offset:22528
	ds_read_b128 v[248:251], v171 offset:23552
	s_nop 15
	s_nop 15
	s_waitcnt lgkmcnt(0)
	s_barrier
	s_setprio 1
	v_mfma_f32_16x16x32_bf16 v[140:143], v[32:35], v[186:189], v[140:143]
	v_mfma_f32_16x16x32_bf16 v[136:139], v[40:43], v[186:189], v[136:139]
	v_mfma_f32_16x16x32_bf16 v[124:127], v[32:35], v[194:197], v[124:127]
	v_mfma_f32_16x16x32_bf16 v[120:123], v[40:43], v[194:197], v[120:123]
	v_mfma_f32_16x16x32_bf16 v[108:111], v[32:35], v[202:205], v[108:111]
	v_mfma_f32_16x16x32_bf16 v[104:107], v[40:43], v[202:205], v[104:107]
	v_mfma_f32_16x16x32_bf16 v[92:95], v[32:35], v[210:213], v[92:95]
	v_mfma_f32_16x16x32_bf16 v[88:91], v[40:43], v[210:213], v[88:91]
	v_mfma_f32_16x16x32_bf16 v[140:143], v[36:39], v[190:193], v[140:143]
	v_mfma_f32_16x16x32_bf16 v[136:139], v[44:47], v[190:193], v[136:139]
	v_mfma_f32_16x16x32_bf16 v[124:127], v[36:39], v[198:201], v[124:127]
	v_mfma_f32_16x16x32_bf16 v[120:123], v[44:47], v[198:201], v[120:123]
	v_mfma_f32_16x16x32_bf16 v[108:111], v[36:39], v[206:209], v[108:111]
	v_mfma_f32_16x16x32_bf16 v[104:107], v[44:47], v[206:209], v[104:107]
	v_mfma_f32_16x16x32_bf16 v[92:95], v[36:39], v[214:217], v[92:95]
	v_mfma_f32_16x16x32_bf16 v[88:91], v[44:47], v[214:217], v[88:91]
	s_setprio 0
	s_setprio 1
	v_mfma_f32_16x16x32_bf16 v[132:135], v[162:165], v[186:189], v[132:135]
	v_mfma_f32_16x16x32_bf16 v[128:131], v[178:181], v[186:189], v[128:131]
	v_mfma_f32_16x16x32_bf16 v[116:119], v[162:165], v[194:197], v[116:119]
	v_mfma_f32_16x16x32_bf16 v[112:115], v[178:181], v[194:197], v[112:115]
	v_mfma_f32_16x16x32_bf16 v[100:103], v[162:165], v[202:205], v[100:103]
	v_mfma_f32_16x16x32_bf16 v[96:99], v[178:181], v[202:205], v[96:99]
	v_mfma_f32_16x16x32_bf16 v[84:87], v[162:165], v[210:213], v[84:87]
	v_mfma_f32_16x16x32_bf16 v[80:83], v[178:181], v[210:213], v[80:83]
	v_mfma_f32_16x16x32_bf16 v[132:135], v[174:177], v[190:193], v[132:135]
	v_mfma_f32_16x16x32_bf16 v[128:131], v[182:185], v[190:193], v[128:131]
	v_mfma_f32_16x16x32_bf16 v[116:119], v[174:177], v[198:201], v[116:119]
	v_mfma_f32_16x16x32_bf16 v[112:115], v[182:185], v[198:201], v[112:115]
	v_mfma_f32_16x16x32_bf16 v[100:103], v[174:177], v[206:209], v[100:103]
	v_mfma_f32_16x16x32_bf16 v[96:99], v[182:185], v[206:209], v[96:99]
	v_mfma_f32_16x16x32_bf16 v[84:87], v[174:177], v[214:217], v[84:87]
	v_mfma_f32_16x16x32_bf16 v[80:83], v[182:185], v[214:217], v[80:83]
	s_setprio 0
	s_setprio 1
	v_mfma_f32_16x16x32_bf16 v[76:79], v[32:35], v[220:223], v[76:79]
	v_mfma_f32_16x16x32_bf16 v[72:75], v[40:43], v[220:223], v[72:75]
	v_mfma_f32_16x16x32_bf16 v[60:63], v[32:35], v[228:231], v[60:63]
	v_mfma_f32_16x16x32_bf16 v[56:59], v[40:43], v[228:231], v[56:59]
	v_mfma_f32_16x16x32_bf16 v[28:31], v[32:35], v[236:239], v[28:31]
	v_mfma_f32_16x16x32_bf16 v[24:27], v[40:43], v[236:239], v[24:27]
	v_mfma_f32_16x16x32_bf16 v[12:15], v[32:35], v[244:247], v[12:15]
	v_mfma_f32_16x16x32_bf16 v[8:11], v[40:43], v[244:247], v[8:11]
	v_mfma_f32_16x16x32_bf16 v[76:79], v[36:39], v[224:227], v[76:79]
	v_mfma_f32_16x16x32_bf16 v[72:75], v[44:47], v[224:227], v[72:75]
	v_mfma_f32_16x16x32_bf16 v[60:63], v[36:39], v[232:235], v[60:63]
	v_mfma_f32_16x16x32_bf16 v[56:59], v[44:47], v[232:235], v[56:59]
	v_mfma_f32_16x16x32_bf16 v[28:31], v[36:39], v[240:243], v[28:31]
	v_mfma_f32_16x16x32_bf16 v[24:27], v[44:47], v[240:243], v[24:27]
	v_mfma_f32_16x16x32_bf16 v[12:15], v[36:39], v[248:251], v[12:15]
	v_mfma_f32_16x16x32_bf16 v[8:11], v[44:47], v[248:251], v[8:11]
	s_setprio 0
	s_setprio 1
	v_mfma_f32_16x16x32_bf16 v[68:71], v[162:165], v[220:223], v[68:71]
	v_mfma_f32_16x16x32_bf16 v[64:67], v[178:181], v[220:223], v[64:67]
	v_mfma_f32_16x16x32_bf16 v[52:55], v[162:165], v[228:231], v[52:55]
	v_mfma_f32_16x16x32_bf16 v[48:51], v[178:181], v[228:231], v[48:51]
	v_mfma_f32_16x16x32_bf16 v[20:23], v[162:165], v[236:239], v[20:23]
	v_mfma_f32_16x16x32_bf16 v[16:19], v[178:181], v[236:239], v[16:19]
	v_mfma_f32_16x16x32_bf16 v[4:7], v[162:165], v[244:247], v[4:7]
	v_mfma_f32_16x16x32_bf16 v[0:3], v[178:181], v[244:247], v[0:3]
	v_mfma_f32_16x16x32_bf16 v[68:71], v[174:177], v[224:227], v[68:71]
	v_mfma_f32_16x16x32_bf16 v[64:67], v[182:185], v[224:227], v[64:67]
	v_mfma_f32_16x16x32_bf16 v[52:55], v[174:177], v[232:235], v[52:55]
	v_mfma_f32_16x16x32_bf16 v[48:51], v[182:185], v[232:235], v[48:51]
	v_mfma_f32_16x16x32_bf16 v[20:23], v[174:177], v[240:243], v[20:23]
	v_mfma_f32_16x16x32_bf16 v[16:19], v[182:185], v[240:243], v[16:19]
	v_mfma_f32_16x16x32_bf16 v[4:7], v[174:177], v[248:251], v[4:7]
	v_mfma_f32_16x16x32_bf16 v[0:3], v[182:185], v[248:251], v[0:3]
	s_setprio 0
	s_waitcnt vmcnt(0)
	s_barrier
	s_add_u32 vcc_lo, s30, 0x0
	s_addc_u32 vcc_hi, s31, 0
	s_add_i32 m0, s37, 0x10000
	s_nop 0
	global_load_lds_dwordx4 v148, vcc
	s_add_i32 m0, s37, 0x12000
	s_nop 0
	global_load_lds_dwordx4 v144, vcc
	s_add_u32 vcc_lo, vcc_lo, 0x20000
	s_addc_u32 vcc_hi, vcc_hi, 0
	s_add_i32 m0, s37, 0x11000
	s_nop 0
	global_load_lds_dwordx4 v148, vcc
	s_add_i32 m0, s37, 0x13000
	s_nop 0
	global_load_lds_dwordx4 v144, vcc
	s_add_u32 vcc_lo, vcc_lo, 0x60000
	s_addc_u32 vcc_hi, vcc_hi, 0
	s_add_i32 m0, s37, 0x14000
	s_nop 0
	global_load_lds_dwordx4 v148, vcc
	s_add_i32 m0, s37, 0x16000
	s_nop 0
	global_load_lds_dwordx4 v144, vcc
	s_add_u32 vcc_lo, vcc_lo, 0x20000
	s_addc_u32 vcc_hi, vcc_hi, 0
	s_add_i32 m0, s37, 0x15000
	s_nop 0
	global_load_lds_dwordx4 v148, vcc
	s_add_i32 m0, s37, 0x17000
	s_nop 0
	global_load_lds_dwordx4 v144, vcc
	ds_read_b128 v[32:35], v169 offset:32768
	ds_read_b128 v[36:39], v169 offset:33792
	ds_read_b128 v[40:43], v169 offset:34816
	ds_read_b128 v[44:47], v169 offset:35840
	ds_read_b128 v[162:165], v170 offset:32768
	ds_read_b128 v[174:177], v170 offset:33792
	ds_read_b128 v[178:181], v170 offset:34816
	ds_read_b128 v[182:185], v170 offset:35840
	ds_read_b128 v[186:189], v171 offset:32768
	ds_read_b128 v[190:193], v171 offset:33792
	ds_read_b128 v[194:197], v171 offset:34816
	ds_read_b128 v[198:201], v171 offset:35840
	ds_read_b128 v[202:205], v171 offset:36864
	ds_read_b128 v[206:209], v171 offset:37888
	ds_read_b128 v[210:213], v171 offset:38912
	ds_read_b128 v[214:217], v171 offset:39936
	ds_read_b128 v[220:223], v171 offset:49152
	ds_read_b128 v[224:227], v171 offset:50176
	ds_read_b128 v[228:231], v171 offset:51200
	ds_read_b128 v[232:235], v171 offset:52224
	ds_read_b128 v[236:239], v171 offset:53248
	ds_read_b128 v[240:243], v171 offset:54272
	ds_read_b128 v[244:247], v171 offset:55296
	ds_read_b128 v[248:251], v171 offset:56320
	s_nop 15
	s_nop 15
	s_waitcnt lgkmcnt(0)
	s_barrier
	s_setprio 1
	v_mfma_f32_16x16x32_bf16 v[140:143], v[32:35], v[186:189], v[140:143]
	v_mfma_f32_16x16x32_bf16 v[136:139], v[40:43], v[186:189], v[136:139]
	v_mfma_f32_16x16x32_bf16 v[124:127], v[32:35], v[194:197], v[124:127]
	v_mfma_f32_16x16x32_bf16 v[120:123], v[40:43], v[194:197], v[120:123]
	v_mfma_f32_16x16x32_bf16 v[108:111], v[32:35], v[202:205], v[108:111]
	v_mfma_f32_16x16x32_bf16 v[104:107], v[40:43], v[202:205], v[104:107]
	v_mfma_f32_16x16x32_bf16 v[92:95], v[32:35], v[210:213], v[92:95]
	v_mfma_f32_16x16x32_bf16 v[88:91], v[40:43], v[210:213], v[88:91]
	v_mfma_f32_16x16x32_bf16 v[140:143], v[36:39], v[190:193], v[140:143]
	v_mfma_f32_16x16x32_bf16 v[136:139], v[44:47], v[190:193], v[136:139]
	v_mfma_f32_16x16x32_bf16 v[124:127], v[36:39], v[198:201], v[124:127]
	v_mfma_f32_16x16x32_bf16 v[120:123], v[44:47], v[198:201], v[120:123]
	v_mfma_f32_16x16x32_bf16 v[108:111], v[36:39], v[206:209], v[108:111]
	v_mfma_f32_16x16x32_bf16 v[104:107], v[44:47], v[206:209], v[104:107]
	v_mfma_f32_16x16x32_bf16 v[92:95], v[36:39], v[214:217], v[92:95]
	v_mfma_f32_16x16x32_bf16 v[88:91], v[44:47], v[214:217], v[88:91]
	s_setprio 0
	s_setprio 1
	v_mfma_f32_16x16x32_bf16 v[132:135], v[162:165], v[186:189], v[132:135]
	v_mfma_f32_16x16x32_bf16 v[128:131], v[178:181], v[186:189], v[128:131]
	v_mfma_f32_16x16x32_bf16 v[116:119], v[162:165], v[194:197], v[116:119]
	v_mfma_f32_16x16x32_bf16 v[112:115], v[178:181], v[194:197], v[112:115]
	v_mfma_f32_16x16x32_bf16 v[100:103], v[162:165], v[202:205], v[100:103]
	v_mfma_f32_16x16x32_bf16 v[96:99], v[178:181], v[202:205], v[96:99]
	v_mfma_f32_16x16x32_bf16 v[84:87], v[162:165], v[210:213], v[84:87]
	v_mfma_f32_16x16x32_bf16 v[80:83], v[178:181], v[210:213], v[80:83]
	v_mfma_f32_16x16x32_bf16 v[132:135], v[174:177], v[190:193], v[132:135]
	v_mfma_f32_16x16x32_bf16 v[128:131], v[182:185], v[190:193], v[128:131]
	v_mfma_f32_16x16x32_bf16 v[116:119], v[174:177], v[198:201], v[116:119]
	v_mfma_f32_16x16x32_bf16 v[112:115], v[182:185], v[198:201], v[112:115]
	v_mfma_f32_16x16x32_bf16 v[100:103], v[174:177], v[206:209], v[100:103]
	v_mfma_f32_16x16x32_bf16 v[96:99], v[182:185], v[206:209], v[96:99]
	v_mfma_f32_16x16x32_bf16 v[84:87], v[174:177], v[214:217], v[84:87]
	v_mfma_f32_16x16x32_bf16 v[80:83], v[182:185], v[214:217], v[80:83]
	s_setprio 0
	s_setprio 1
	v_mfma_f32_16x16x32_bf16 v[76:79], v[32:35], v[220:223], v[76:79]
	v_mfma_f32_16x16x32_bf16 v[72:75], v[40:43], v[220:223], v[72:75]
	v_mfma_f32_16x16x32_bf16 v[60:63], v[32:35], v[228:231], v[60:63]
	v_mfma_f32_16x16x32_bf16 v[56:59], v[40:43], v[228:231], v[56:59]
	v_mfma_f32_16x16x32_bf16 v[28:31], v[32:35], v[236:239], v[28:31]
	v_mfma_f32_16x16x32_bf16 v[24:27], v[40:43], v[236:239], v[24:27]
	v_mfma_f32_16x16x32_bf16 v[12:15], v[32:35], v[244:247], v[12:15]
	v_mfma_f32_16x16x32_bf16 v[8:11], v[40:43], v[244:247], v[8:11]
	v_mfma_f32_16x16x32_bf16 v[76:79], v[36:39], v[224:227], v[76:79]
	v_mfma_f32_16x16x32_bf16 v[72:75], v[44:47], v[224:227], v[72:75]
	v_mfma_f32_16x16x32_bf16 v[60:63], v[36:39], v[232:235], v[60:63]
	v_mfma_f32_16x16x32_bf16 v[56:59], v[44:47], v[232:235], v[56:59]
	v_mfma_f32_16x16x32_bf16 v[28:31], v[36:39], v[240:243], v[28:31]
	v_mfma_f32_16x16x32_bf16 v[24:27], v[44:47], v[240:243], v[24:27]
	v_mfma_f32_16x16x32_bf16 v[12:15], v[36:39], v[248:251], v[12:15]
	v_mfma_f32_16x16x32_bf16 v[8:11], v[44:47], v[248:251], v[8:11]
	s_setprio 0
	s_setprio 1
	v_mfma_f32_16x16x32_bf16 v[68:71], v[162:165], v[220:223], v[68:71]
	v_mfma_f32_16x16x32_bf16 v[64:67], v[178:181], v[220:223], v[64:67]
	v_mfma_f32_16x16x32_bf16 v[52:55], v[162:165], v[228:231], v[52:55]
	v_mfma_f32_16x16x32_bf16 v[48:51], v[178:181], v[228:231], v[48:51]
	v_mfma_f32_16x16x32_bf16 v[20:23], v[162:165], v[236:239], v[20:23]
	v_mfma_f32_16x16x32_bf16 v[16:19], v[178:181], v[236:239], v[16:19]
	v_mfma_f32_16x16x32_bf16 v[4:7], v[162:165], v[244:247], v[4:7]
	v_mfma_f32_16x16x32_bf16 v[0:3], v[178:181], v[244:247], v[0:3]
	v_mfma_f32_16x16x32_bf16 v[68:71], v[174:177], v[224:227], v[68:71]
	v_mfma_f32_16x16x32_bf16 v[64:67], v[182:185], v[224:227], v[64:67]
	v_mfma_f32_16x16x32_bf16 v[52:55], v[174:177], v[232:235], v[52:55]
	v_mfma_f32_16x16x32_bf16 v[48:51], v[182:185], v[232:235], v[48:51]
	v_mfma_f32_16x16x32_bf16 v[20:23], v[174:177], v[240:243], v[20:23]
	v_mfma_f32_16x16x32_bf16 v[16:19], v[182:185], v[240:243], v[16:19]
	v_mfma_f32_16x16x32_bf16 v[4:7], v[174:177], v[248:251], v[4:7]
	v_mfma_f32_16x16x32_bf16 v[0:3], v[182:185], v[248:251], v[0:3]
	s_setprio 0
	s_waitcnt vmcnt(0)
	s_barrier
	s_add_i32 s56, s56, 2
	s_add_u32 s12, s12, 0x100
	s_addc_u32 s13, s13, 0
	s_add_u32 s54, s54, 0x100
	s_addc_u32 s55, s55, 0
	s_cmp_gt_u32 s56, 29
	s_cbranch_scc0 .LBB0_846
	s_branch .Lk64_done_p6
.Lk64_trail_p6:
	s_sub_u32 vcc_lo, s12, 0x80000
	s_subb_u32 vcc_hi, s13, 0
	s_add_i32 m0, s37, 0xa000
	s_nop 0
	global_load_lds_dwordx4 v146, vcc
	s_add_u32 vcc_lo, vcc_lo, 0x20000
	s_addc_u32 vcc_hi, vcc_hi, 0
	s_add_i32 m0, s37, 0x9000
	s_nop 0
	global_load_lds_dwordx4 v150, vcc
	s_add_u32 vcc_lo, vcc_lo, 0x60000
	s_addc_u32 vcc_hi, vcc_hi, 0
	s_add_i32 m0, s37, 0xe000
	s_nop 0
	global_load_lds_dwordx4 v146, vcc
	s_add_u32 vcc_lo, vcc_lo, 0x20000
	s_addc_u32 vcc_hi, vcc_hi, 0
	s_add_i32 m0, s37, 0xd000
	s_nop 0
	global_load_lds_dwordx4 v150, vcc
	s_add_u32 vcc_lo, s34, 0x0
	s_addc_u32 vcc_hi, s35, 0
	s_mov_b32 m0, s37
	s_nop 0
	global_load_lds_dwordx4 v150, vcc
	s_sub_u32 vcc_lo, vcc_lo, 0x20000
	s_subb_u32 vcc_hi, vcc_hi, 0
	s_sub_i32 m0, s37, 0x1000
	s_nop 0
	global_load_lds_dwordx4 v150, vcc
	s_add_u32 vcc_lo, vcc_lo, 0xa0000
	s_addc_u32 vcc_hi, vcc_hi, 0
	s_add_i32 m0, s37, 0x4000
	s_nop 0
	global_load_lds_dwordx4 v150, vcc
	s_sub_u32 vcc_lo, vcc_lo, 0x20000
	s_subb_u32 vcc_hi, vcc_hi, 0
	s_add_i32 m0, s37, 0x3000
	s_nop 0
	global_load_lds_dwordx4 v150, vcc
	ds_read_b128 v[32:35], v169 offset:0
	ds_read_b128 v[36:39], v169 offset:1024
	ds_read_b128 v[40:43], v169 offset:2048
	ds_read_b128 v[44:47], v169 offset:3072
	ds_read_b128 v[162:165], v170 offset:0
	ds_read_b128 v[174:177], v170 offset:1024
	ds_read_b128 v[178:181], v170 offset:2048
	ds_read_b128 v[182:185], v170 offset:3072
	ds_read_b128 v[186:189], v171 offset:0
	ds_read_b128 v[190:193], v171 offset:1024
	ds_read_b128 v[194:197], v171 offset:2048
	ds_read_b128 v[198:201], v171 offset:3072
	ds_read_b128 v[202:205], v171 offset:4096
	ds_read_b128 v[206:209], v171 offset:5120
	ds_read_b128 v[210:213], v171 offset:6144
	ds_read_b128 v[214:217], v171 offset:7168
	ds_read_b128 v[220:223], v171 offset:16384
	ds_read_b128 v[224:227], v171 offset:17408
	ds_read_b128 v[228:231], v171 offset:18432
	ds_read_b128 v[232:235], v171 offset:19456
	ds_read_b128 v[236:239], v171 offset:20480
	ds_read_b128 v[240:243], v171 offset:21504
	ds_read_b128 v[244:247], v171 offset:22528
	ds_read_b128 v[248:251], v171 offset:23552
	s_nop 15
	s_nop 15
	s_waitcnt lgkmcnt(0)
	s_barrier
	s_setprio 1
	v_mfma_f32_16x16x32_bf16 v[140:143], v[32:35], v[186:189], v[140:143]
	v_mfma_f32_16x16x32_bf16 v[136:139], v[40:43], v[186:189], v[136:139]
	v_mfma_f32_16x16x32_bf16 v[124:127], v[32:35], v[194:197], v[124:127]
	v_mfma_f32_16x16x32_bf16 v[120:123], v[40:43], v[194:197], v[120:123]
	v_mfma_f32_16x16x32_bf16 v[108:111], v[32:35], v[202:205], v[108:111]
	v_mfma_f32_16x16x32_bf16 v[104:107], v[40:43], v[202:205], v[104:107]
	v_mfma_f32_16x16x32_bf16 v[92:95], v[32:35], v[210:213], v[92:95]
	v_mfma_f32_16x16x32_bf16 v[88:91], v[40:43], v[210:213], v[88:91]
	v_mfma_f32_16x16x32_bf16 v[140:143], v[36:39], v[190:193], v[140:143]
	v_mfma_f32_16x16x32_bf16 v[136:139], v[44:47], v[190:193], v[136:139]
	v_mfma_f32_16x16x32_bf16 v[124:127], v[36:39], v[198:201], v[124:127]
	v_mfma_f32_16x16x32_bf16 v[120:123], v[44:47], v[198:201], v[120:123]
	v_mfma_f32_16x16x32_bf16 v[108:111], v[36:39], v[206:209], v[108:111]
	v_mfma_f32_16x16x32_bf16 v[104:107], v[44:47], v[206:209], v[104:107]
	v_mfma_f32_16x16x32_bf16 v[92:95], v[36:39], v[214:217], v[92:95]
	v_mfma_f32_16x16x32_bf16 v[88:91], v[44:47], v[214:217], v[88:91]
	s_setprio 0
	s_setprio 1
	v_mfma_f32_16x16x32_bf16 v[132:135], v[162:165], v[186:189], v[132:135]
	v_mfma_f32_16x16x32_bf16 v[128:131], v[178:181], v[186:189], v[128:131]
	v_mfma_f32_16x16x32_bf16 v[116:119], v[162:165], v[194:197], v[116:119]
	v_mfma_f32_16x16x32_bf16 v[112:115], v[178:181], v[194:197], v[112:115]
	v_mfma_f32_16x16x32_bf16 v[100:103], v[162:165], v[202:205], v[100:103]
	v_mfma_f32_16x16x32_bf16 v[96:99], v[178:181], v[202:205], v[96:99]
	v_mfma_f32_16x16x32_bf16 v[84:87], v[162:165], v[210:213], v[84:87]
	v_mfma_f32_16x16x32_bf16 v[80:83], v[178:181], v[210:213], v[80:83]
	v_mfma_f32_16x16x32_bf16 v[132:135], v[174:177], v[190:193], v[132:135]
	v_mfma_f32_16x16x32_bf16 v[128:131], v[182:185], v[190:193], v[128:131]
	v_mfma_f32_16x16x32_bf16 v[116:119], v[174:177], v[198:201], v[116:119]
	v_mfma_f32_16x16x32_bf16 v[112:115], v[182:185], v[198:201], v[112:115]
	v_mfma_f32_16x16x32_bf16 v[100:103], v[174:177], v[206:209], v[100:103]
	v_mfma_f32_16x16x32_bf16 v[96:99], v[182:185], v[206:209], v[96:99]
	v_mfma_f32_16x16x32_bf16 v[84:87], v[174:177], v[214:217], v[84:87]
	v_mfma_f32_16x16x32_bf16 v[80:83], v[182:185], v[214:217], v[80:83]
	s_setprio 0
	s_setprio 1
	v_mfma_f32_16x16x32_bf16 v[76:79], v[32:35], v[220:223], v[76:79]
	v_mfma_f32_16x16x32_bf16 v[72:75], v[40:43], v[220:223], v[72:75]
	v_mfma_f32_16x16x32_bf16 v[60:63], v[32:35], v[228:231], v[60:63]
	v_mfma_f32_16x16x32_bf16 v[56:59], v[40:43], v[228:231], v[56:59]
	v_mfma_f32_16x16x32_bf16 v[28:31], v[32:35], v[236:239], v[28:31]
	v_mfma_f32_16x16x32_bf16 v[24:27], v[40:43], v[236:239], v[24:27]
	v_mfma_f32_16x16x32_bf16 v[12:15], v[32:35], v[244:247], v[12:15]
	v_mfma_f32_16x16x32_bf16 v[8:11], v[40:43], v[244:247], v[8:11]
	v_mfma_f32_16x16x32_bf16 v[76:79], v[36:39], v[224:227], v[76:79]
	v_mfma_f32_16x16x32_bf16 v[72:75], v[44:47], v[224:227], v[72:75]
	v_mfma_f32_16x16x32_bf16 v[60:63], v[36:39], v[232:235], v[60:63]
	v_mfma_f32_16x16x32_bf16 v[56:59], v[44:47], v[232:235], v[56:59]
	v_mfma_f32_16x16x32_bf16 v[28:31], v[36:39], v[240:243], v[28:31]
	v_mfma_f32_16x16x32_bf16 v[24:27], v[44:47], v[240:243], v[24:27]
	v_mfma_f32_16x16x32_bf16 v[12:15], v[36:39], v[248:251], v[12:15]
	v_mfma_f32_16x16x32_bf16 v[8:11], v[44:47], v[248:251], v[8:11]
	s_setprio 0
	s_setprio 1
	v_mfma_f32_16x16x32_bf16 v[68:71], v[162:165], v[220:223], v[68:71]
	v_mfma_f32_16x16x32_bf16 v[64:67], v[178:181], v[220:223], v[64:67]
	v_mfma_f32_16x16x32_bf16 v[52:55], v[162:165], v[228:231], v[52:55]
	v_mfma_f32_16x16x32_bf16 v[48:51], v[178:181], v[228:231], v[48:51]
	v_mfma_f32_16x16x32_bf16 v[20:23], v[162:165], v[236:239], v[20:23]
	v_mfma_f32_16x16x32_bf16 v[16:19], v[178:181], v[236:239], v[16:19]
	v_mfma_f32_16x16x32_bf16 v[4:7], v[162:165], v[244:247], v[4:7]
	v_mfma_f32_16x16x32_bf16 v[0:3], v[178:181], v[244:247], v[0:3]
	v_mfma_f32_16x16x32_bf16 v[68:71], v[174:177], v[224:227], v[68:71]
	v_mfma_f32_16x16x32_bf16 v[64:67], v[182:185], v[224:227], v[64:67]
	v_mfma_f32_16x16x32_bf16 v[52:55], v[174:177], v[232:235], v[52:55]
	v_mfma_f32_16x16x32_bf16 v[48:51], v[182:185], v[232:235], v[48:51]
	v_mfma_f32_16x16x32_bf16 v[20:23], v[174:177], v[240:243], v[20:23]
	v_mfma_f32_16x16x32_bf16 v[16:19], v[182:185], v[240:243], v[16:19]
	v_mfma_f32_16x16x32_bf16 v[4:7], v[174:177], v[248:251], v[4:7]
	v_mfma_f32_16x16x32_bf16 v[0:3], v[182:185], v[248:251], v[0:3]
	s_setprio 0
	s_waitcnt vmcnt(0)
	s_barrier
	s_add_u32 vcc_lo, s34, 0x0
	s_addc_u32 vcc_hi, s35, 0
	s_add_i32 m0, s37, 0x2000
	s_nop 0
	global_load_lds_dwordx4 v146, vcc
	s_add_u32 vcc_lo, vcc_lo, 0x20000
	s_addc_u32 vcc_hi, vcc_hi, 0
	s_add_i32 m0, s37, 0x1000
	s_nop 0
	global_load_lds_dwordx4 v150, vcc
	s_add_u32 vcc_lo, vcc_lo, 0x60000
	s_addc_u32 vcc_hi, vcc_hi, 0
	s_add_i32 m0, s37, 0x6000
	s_nop 0
	global_load_lds_dwordx4 v146, vcc
	s_add_u32 vcc_lo, vcc_lo, 0x20000
	s_addc_u32 vcc_hi, vcc_hi, 0
	s_add_i32 m0, s37, 0x5000
	s_nop 0
	global_load_lds_dwordx4 v150, vcc
	s_add_u32 vcc_lo, s34, 0x80
	s_addc_u32 vcc_hi, s35, 0
	s_add_i32 m0, s37, 0x8000
	s_nop 0
	global_load_lds_dwordx4 v150, vcc
	s_sub_u32 vcc_lo, vcc_lo, 0x20000
	s_subb_u32 vcc_hi, vcc_hi, 0
	s_add_i32 m0, s37, 0x7000
	s_nop 0
	global_load_lds_dwordx4 v150, vcc
	s_add_u32 vcc_lo, vcc_lo, 0xa0000
	s_addc_u32 vcc_hi, vcc_hi, 0
	s_add_i32 m0, s37, 0xc000
	s_nop 0
	global_load_lds_dwordx4 v150, vcc
	s_sub_u32 vcc_lo, vcc_lo, 0x20000
	s_subb_u32 vcc_hi, vcc_hi, 0
	s_add_i32 m0, s37, 0xb000
	s_nop 0
	global_load_lds_dwordx4 v150, vcc
	ds_read_b128 v[32:35], v169 offset:32768
	ds_read_b128 v[36:39], v169 offset:33792
	ds_read_b128 v[40:43], v169 offset:34816
	ds_read_b128 v[44:47], v169 offset:35840
	ds_read_b128 v[162:165], v170 offset:32768
	ds_read_b128 v[174:177], v170 offset:33792
	ds_read_b128 v[178:181], v170 offset:34816
	ds_read_b128 v[182:185], v170 offset:35840
	ds_read_b128 v[186:189], v171 offset:32768
	ds_read_b128 v[190:193], v171 offset:33792
	ds_read_b128 v[194:197], v171 offset:34816
	ds_read_b128 v[198:201], v171 offset:35840
	ds_read_b128 v[202:205], v171 offset:36864
	ds_read_b128 v[206:209], v171 offset:37888
	ds_read_b128 v[210:213], v171 offset:38912
	ds_read_b128 v[214:217], v171 offset:39936
	ds_read_b128 v[220:223], v171 offset:49152
	ds_read_b128 v[224:227], v171 offset:50176
	ds_read_b128 v[228:231], v171 offset:51200
	ds_read_b128 v[232:235], v171 offset:52224
	ds_read_b128 v[236:239], v171 offset:53248
	ds_read_b128 v[240:243], v171 offset:54272
	ds_read_b128 v[244:247], v171 offset:55296
	ds_read_b128 v[248:251], v171 offset:56320
	s_nop 15
	s_nop 15
	s_waitcnt lgkmcnt(0)
	s_barrier
	s_setprio 1
	v_mfma_f32_16x16x32_bf16 v[140:143], v[32:35], v[186:189], v[140:143]
	v_mfma_f32_16x16x32_bf16 v[136:139], v[40:43], v[186:189], v[136:139]
	v_mfma_f32_16x16x32_bf16 v[124:127], v[32:35], v[194:197], v[124:127]
	v_mfma_f32_16x16x32_bf16 v[120:123], v[40:43], v[194:197], v[120:123]
	v_mfma_f32_16x16x32_bf16 v[108:111], v[32:35], v[202:205], v[108:111]
	v_mfma_f32_16x16x32_bf16 v[104:107], v[40:43], v[202:205], v[104:107]
	v_mfma_f32_16x16x32_bf16 v[92:95], v[32:35], v[210:213], v[92:95]
	v_mfma_f32_16x16x32_bf16 v[88:91], v[40:43], v[210:213], v[88:91]
	v_mfma_f32_16x16x32_bf16 v[140:143], v[36:39], v[190:193], v[140:143]
	v_mfma_f32_16x16x32_bf16 v[136:139], v[44:47], v[190:193], v[136:139]
	v_mfma_f32_16x16x32_bf16 v[124:127], v[36:39], v[198:201], v[124:127]
	v_mfma_f32_16x16x32_bf16 v[120:123], v[44:47], v[198:201], v[120:123]
	v_mfma_f32_16x16x32_bf16 v[108:111], v[36:39], v[206:209], v[108:111]
	v_mfma_f32_16x16x32_bf16 v[104:107], v[44:47], v[206:209], v[104:107]
	v_mfma_f32_16x16x32_bf16 v[92:95], v[36:39], v[214:217], v[92:95]
	v_mfma_f32_16x16x32_bf16 v[88:91], v[44:47], v[214:217], v[88:91]
	s_setprio 0
	s_setprio 1
	v_mfma_f32_16x16x32_bf16 v[132:135], v[162:165], v[186:189], v[132:135]
	v_mfma_f32_16x16x32_bf16 v[128:131], v[178:181], v[186:189], v[128:131]
	v_mfma_f32_16x16x32_bf16 v[116:119], v[162:165], v[194:197], v[116:119]
	v_mfma_f32_16x16x32_bf16 v[112:115], v[178:181], v[194:197], v[112:115]
	v_mfma_f32_16x16x32_bf16 v[100:103], v[162:165], v[202:205], v[100:103]
	v_mfma_f32_16x16x32_bf16 v[96:99], v[178:181], v[202:205], v[96:99]
	v_mfma_f32_16x16x32_bf16 v[84:87], v[162:165], v[210:213], v[84:87]
	v_mfma_f32_16x16x32_bf16 v[80:83], v[178:181], v[210:213], v[80:83]
	v_mfma_f32_16x16x32_bf16 v[132:135], v[174:177], v[190:193], v[132:135]
	v_mfma_f32_16x16x32_bf16 v[128:131], v[182:185], v[190:193], v[128:131]
	v_mfma_f32_16x16x32_bf16 v[116:119], v[174:177], v[198:201], v[116:119]
	v_mfma_f32_16x16x32_bf16 v[112:115], v[182:185], v[198:201], v[112:115]
	v_mfma_f32_16x16x32_bf16 v[100:103], v[174:177], v[206:209], v[100:103]
	v_mfma_f32_16x16x32_bf16 v[96:99], v[182:185], v[206:209], v[96:99]
	v_mfma_f32_16x16x32_bf16 v[84:87], v[174:177], v[214:217], v[84:87]
	v_mfma_f32_16x16x32_bf16 v[80:83], v[182:185], v[214:217], v[80:83]
	s_setprio 0
	s_setprio 1
	v_mfma_f32_16x16x32_bf16 v[76:79], v[32:35], v[220:223], v[76:79]
	v_mfma_f32_16x16x32_bf16 v[72:75], v[40:43], v[220:223], v[72:75]
	v_mfma_f32_16x16x32_bf16 v[60:63], v[32:35], v[228:231], v[60:63]
	v_mfma_f32_16x16x32_bf16 v[56:59], v[40:43], v[228:231], v[56:59]
	v_mfma_f32_16x16x32_bf16 v[28:31], v[32:35], v[236:239], v[28:31]
	v_mfma_f32_16x16x32_bf16 v[24:27], v[40:43], v[236:239], v[24:27]
	v_mfma_f32_16x16x32_bf16 v[12:15], v[32:35], v[244:247], v[12:15]
	v_mfma_f32_16x16x32_bf16 v[8:11], v[40:43], v[244:247], v[8:11]
	v_mfma_f32_16x16x32_bf16 v[76:79], v[36:39], v[224:227], v[76:79]
	v_mfma_f32_16x16x32_bf16 v[72:75], v[44:47], v[224:227], v[72:75]
	v_mfma_f32_16x16x32_bf16 v[60:63], v[36:39], v[232:235], v[60:63]
	v_mfma_f32_16x16x32_bf16 v[56:59], v[44:47], v[232:235], v[56:59]
	v_mfma_f32_16x16x32_bf16 v[28:31], v[36:39], v[240:243], v[28:31]
	v_mfma_f32_16x16x32_bf16 v[24:27], v[44:47], v[240:243], v[24:27]
	v_mfma_f32_16x16x32_bf16 v[12:15], v[36:39], v[248:251], v[12:15]
	v_mfma_f32_16x16x32_bf16 v[8:11], v[44:47], v[248:251], v[8:11]
	s_setprio 0
	s_setprio 1
	v_mfma_f32_16x16x32_bf16 v[68:71], v[162:165], v[220:223], v[68:71]
	v_mfma_f32_16x16x32_bf16 v[64:67], v[178:181], v[220:223], v[64:67]
	v_mfma_f32_16x16x32_bf16 v[52:55], v[162:165], v[228:231], v[52:55]
	v_mfma_f32_16x16x32_bf16 v[48:51], v[178:181], v[228:231], v[48:51]
	v_mfma_f32_16x16x32_bf16 v[20:23], v[162:165], v[236:239], v[20:23]
	v_mfma_f32_16x16x32_bf16 v[16:19], v[178:181], v[236:239], v[16:19]
	v_mfma_f32_16x16x32_bf16 v[4:7], v[162:165], v[244:247], v[4:7]
	v_mfma_f32_16x16x32_bf16 v[0:3], v[178:181], v[244:247], v[0:3]
	v_mfma_f32_16x16x32_bf16 v[68:71], v[174:177], v[224:227], v[68:71]
	v_mfma_f32_16x16x32_bf16 v[64:67], v[182:185], v[224:227], v[64:67]
	v_mfma_f32_16x16x32_bf16 v[52:55], v[174:177], v[232:235], v[52:55]
	v_mfma_f32_16x16x32_bf16 v[48:51], v[182:185], v[232:235], v[48:51]
	v_mfma_f32_16x16x32_bf16 v[20:23], v[174:177], v[240:243], v[20:23]
	v_mfma_f32_16x16x32_bf16 v[16:19], v[182:185], v[240:243], v[16:19]
	v_mfma_f32_16x16x32_bf16 v[4:7], v[174:177], v[248:251], v[4:7]
	v_mfma_f32_16x16x32_bf16 v[0:3], v[182:185], v[248:251], v[0:3]
	s_setprio 0
	s_waitcnt vmcnt(0)
	s_barrier
	s_add_i32 s56, s56, 2
	s_add_u32 s12, s12, 0x100
	s_addc_u32 s13, s13, 0
	s_add_u32 s54, s54, 0x100
	s_addc_u32 s55, s55, 0
	s_cmp_gt_u32 s56, 29
	s_cbranch_scc0 .LBB0_846

.LBB0_926:
	s_add_u32 s6, s92, 0x30000
	s_addc_u32 s7, s93, 0
	v_and_b32_e32 v17, 63, v252
	v_bfe_u32 v18, v13, 4, 2
	s_add_u32 s37, s92, 0x88b80
	v_cmp_eq_u32_e64 s[0:1], 0, v17
	v_and_b32_e32 v17, 15, v13
	v_lshlrev_b32_e32 v19, 4, v18
	v_lshlrev_b32_e32 v13, 2, v13
	s_addc_u32 s42, s93, 0
	v_lshl_or_b32 v182, s10, 6, v17
	v_lshl_or_b32 v17, v17, 6, v19
	s_lshl_b32 s10, s10, 13
	v_and_b32_e32 v13, 32, v13
	v_bitop3_b32 v19, v17, s10, v13 bitop3:0xde
	s_lshl_b32 s10, s11, 5
	s_and_b32 s28, s10, 0x60
	s_lshl_b32 s10, s28, 7
	v_bitop3_b32 v183, v17, s10, v13 bitop3:0xde
	s_mov_b64 s[10:11], 0x80
	s_add_i32 m0, s30, 0x18000
	v_lshl_add_u64 v[6:7], v[6:7], 0, s[10:11]
	s_waitcnt vmcnt(0)
	s_barrier
	s_add_u32 vcc_lo, s22, 0x160080
	s_addc_u32 vcc_hi, s23, 0
	s_add_i32 m0, s30, 0xc000
	s_nop 0
	global_load_lds_dwordx4 v128, vcc
	s_add_i32 m0, s30, 0x18000
	s_nop 0
	global_load_lds_dwordx4 v[6:7], off
	v_lshl_add_u64 v[2:3], v[2:3], 0, s[10:11]
	s_add_i32 m0, s30, 0x1a000
	s_add_i32 s43, s30, 0x8000
	s_add_i32 s48, s30, 0xa000
	global_load_lds_dwordx4 v[2:3], off
	v_lshl_add_u64 v[0:1], v[0:1], 0, s[10:11]
	s_mov_b32 m0, s43
	s_add_u32 s26, s24, 0x160080
	global_load_lds_dwordx4 v[0:1], off
	v_lshl_add_u64 v[0:1], v[4:5], 0, s[10:11]
	s_mov_b32 m0, s48
	s_addc_u32 s27, s25, 0
	global_load_lds_dwordx4 v[0:1], off
	s_add_i32 m0, s30, 0x1c000
	v_lshl_add_u64 v[0:1], s[26:27], 0, v[130:131]
	global_load_lds_dwordx4 v[0:1], off
	v_lshl_add_u64 v[0:1], s[26:27], 0, v[134:135]
	s_add_i32 m0, s30, 0x1e000
	s_mov_b64 s[20:21], 0x160080
	global_load_lds_dwordx4 v[0:1], off
	v_lshrrev_b32_e32 v1, 1, v8
	v_mul_lo_u32 v0, v9, s18
	v_mad_u64_u32 v[0:1], s[26:27], v1, s19, v[0:1]
	v_or_b32_e32 v0, v0, v10
	v_add_lshl_u32 v0, v0, v11, 1
	v_mov_b32_e32 v1, v131
	v_lshl_add_u64 v[136:137], v[0:1], 0, s[20:21]
	v_lshrrev_b32_e32 v1, 1, v12
	v_mul_lo_u32 v0, v14, s18
	v_mad_u64_u32 v[0:1], s[18:19], v1, s19, v[0:1]
	v_or_b32_e32 v0, v0, v15
	s_waitcnt vmcnt(6)
	s_cmpk_lt_u32 s12, 0x100
	v_add_lshl_u32 v0, v0, v16, 1
	v_mov_b32_e32 v1, v131
	s_cselect_b64 s[12:13], -1, 0
	v_lshl_add_u64 v[138:139], v[0:1], 0, s[20:21]
	s_add_i32 s49, 0, 0x10000
	s_add_i32 s51, 0, 0x14000
	v_mbcnt_lo_u32_b32 v0, -1, 0
	v_cmp_gt_u32_e64 s[38:39], 64, v252
	v_cmp_eq_u32_e64 s[40:41], 0, v18
	v_lshl_or_b32 v184, v18, 3, s28
	v_mov_b64_e32 v[140:141], 0x100
	v_mov_b64_e32 v[142:143], 0xff
	v_add_u32_e32 v185, s49, v183
	v_add_u32_e32 v186, s51, v183
	v_add_u32_e32 v187, 0, v19
	v_mbcnt_hi_u32_b32 v188, -1, v0
	v_mov_b32_e32 v189, 0x358637bd
	s_barrier
	s_branch .LBB0_929

.LBB0_940:
	s_add_u32 s24, s22, 0x100
	s_addc_u32 s25, s23, 0
	s_cmpk_eq_i32 s56, 0x54
	s_cselect_b32 s29, s19, s25
	s_cselect_b32 s28, s18, s24
	s_cselect_b32 s27, s21, s47
	s_cselect_b32 s26, s20, s46
	s_and_b64 vcc, exec, s[12:13]
	s_cbranch_vccz .Lk64_trail_p7
	s_sub_u32 vcc_lo, s46, 0x80
	s_subb_u32 vcc_hi, s47, 0
	s_add_i32 m0, s30, 0x18000
	s_nop 0
	global_load_lds_dwordx4 v130, vcc
	s_add_i32 m0, s30, 0x1a000
	s_nop 0
	global_load_lds_dwordx4 v134, vcc
	s_add_u32 vcc_lo, vcc_lo, 0x58000
	s_addc_u32 vcc_hi, vcc_hi, 0
	s_add_i32 m0, s30, 0x19000
	s_nop 0
	global_load_lds_dwordx4 v130, vcc
	s_add_i32 m0, s30, 0x1b000
	s_nop 0
	global_load_lds_dwordx4 v134, vcc
	s_add_u32 vcc_lo, vcc_lo, 0x108000
	s_addc_u32 vcc_hi, vcc_hi, 0
	s_add_i32 m0, s30, 0x1c000
	s_nop 0
	global_load_lds_dwordx4 v130, vcc
	s_add_i32 m0, s30, 0x1e000
	s_nop 0
	global_load_lds_dwordx4 v134, vcc
	s_add_u32 vcc_lo, vcc_lo, 0x58000
	s_addc_u32 vcc_hi, vcc_hi, 0
	s_add_i32 m0, s30, 0x1d000
	s_nop 0
	global_load_lds_dwordx4 v130, vcc
	s_add_i32 m0, s30, 0x1f000
	s_nop 0
	global_load_lds_dwordx4 v134, vcc
	ds_read_b128 v[144:147], v185 offset:0
	ds_read_b128 v[148:151], v185 offset:1024
	ds_read_b128 v[152:155], v185 offset:2048
	ds_read_b128 v[156:159], v185 offset:3072
	ds_read_b128 v[160:163], v186 offset:0
	ds_read_b128 v[164:167], v186 offset:1024
	ds_read_b128 v[168:171], v186 offset:2048
	ds_read_b128 v[172:175], v186 offset:3072
	ds_read_b128 v[176:179], v187 offset:0
	ds_read_b128 v[190:193], v187 offset:1024
	ds_read_b128 v[194:197], v187 offset:2048
	ds_read_b128 v[198:201], v187 offset:3072
	ds_read_b128 v[202:205], v187 offset:4096
	ds_read_b128 v[206:209], v187 offset:5120
	ds_read_b128 v[210:213], v187 offset:6144
	ds_read_b128 v[214:217], v187 offset:7168
	ds_read_b128 v[220:223], v187 offset:16384
	ds_read_b128 v[224:227], v187 offset:17408
	ds_read_b128 v[228:231], v187 offset:18432
	ds_read_b128 v[232:235], v187 offset:19456
	ds_read_b128 v[236:239], v187 offset:20480
	ds_read_b128 v[240:243], v187 offset:21504
	ds_read_b128 v[244:247], v187 offset:22528
	ds_read_b128 v[248:251], v187 offset:23552
	s_nop 15
	s_nop 15
	s_waitcnt lgkmcnt(0)
	s_barrier
	s_setprio 1
	v_mfma_f32_16x16x32_bf16 v[72:75], v[144:147], v[176:179], v[72:75]
	v_mfma_f32_16x16x32_bf16 v[76:79], v[152:155], v[176:179], v[76:79]
	v_mfma_f32_16x16x32_bf16 v[96:99], v[144:147], v[194:197], v[96:99]
	v_mfma_f32_16x16x32_bf16 v[100:103], v[152:155], v[194:197], v[100:103]
	v_mfma_f32_16x16x32_bf16 v[120:123], v[144:147], v[202:205], v[120:123]
	v_mfma_f32_16x16x32_bf16 v[124:127], v[152:155], v[202:205], v[124:127]
	v_mfma_f32_16x16x32_bf16 v[92:95], v[144:147], v[210:213], v[92:95]
	v_mfma_f32_16x16x32_bf16 v[84:87], v[152:155], v[210:213], v[84:87]
	v_mfma_f32_16x16x32_bf16 v[72:75], v[148:151], v[190:193], v[72:75]
	v_mfma_f32_16x16x32_bf16 v[76:79], v[156:159], v[190:193], v[76:79]
	v_mfma_f32_16x16x32_bf16 v[96:99], v[148:151], v[198:201], v[96:99]
	v_mfma_f32_16x16x32_bf16 v[100:103], v[156:159], v[198:201], v[100:103]
	v_mfma_f32_16x16x32_bf16 v[120:123], v[148:151], v[206:209], v[120:123]
	v_mfma_f32_16x16x32_bf16 v[124:127], v[156:159], v[206:209], v[124:127]
	v_mfma_f32_16x16x32_bf16 v[92:95], v[148:151], v[214:217], v[92:95]
	v_mfma_f32_16x16x32_bf16 v[84:87], v[156:159], v[214:217], v[84:87]
	s_setprio 0
	s_setprio 1
	v_mfma_f32_16x16x32_bf16 v[80:83], v[160:163], v[176:179], v[80:83]
	v_mfma_f32_16x16x32_bf16 v[88:91], v[168:171], v[176:179], v[88:91]
	v_mfma_f32_16x16x32_bf16 v[108:111], v[160:163], v[194:197], v[108:111]
	v_mfma_f32_16x16x32_bf16 v[112:115], v[168:171], v[194:197], v[112:115]
	v_mfma_f32_16x16x32_bf16 v[116:119], v[160:163], v[202:205], v[116:119]
	v_mfma_f32_16x16x32_bf16 v[104:107], v[168:171], v[202:205], v[104:107]
	v_mfma_f32_16x16x32_bf16 v[68:71], v[160:163], v[210:213], v[68:71]
	v_mfma_f32_16x16x32_bf16 v[64:67], v[168:171], v[210:213], v[64:67]
	v_mfma_f32_16x16x32_bf16 v[80:83], v[164:167], v[190:193], v[80:83]
	v_mfma_f32_16x16x32_bf16 v[88:91], v[172:175], v[190:193], v[88:91]
	v_mfma_f32_16x16x32_bf16 v[108:111], v[164:167], v[198:201], v[108:111]
	v_mfma_f32_16x16x32_bf16 v[112:115], v[172:175], v[198:201], v[112:115]
	v_mfma_f32_16x16x32_bf16 v[116:119], v[164:167], v[206:209], v[116:119]
	v_mfma_f32_16x16x32_bf16 v[104:107], v[172:175], v[206:209], v[104:107]
	v_mfma_f32_16x16x32_bf16 v[68:71], v[164:167], v[214:217], v[68:71]
	v_mfma_f32_16x16x32_bf16 v[64:67], v[172:175], v[214:217], v[64:67]
	s_setprio 0
	s_setprio 1
	v_mfma_f32_16x16x32_bf16 v[60:63], v[144:147], v[220:223], v[60:63]
	v_mfma_f32_16x16x32_bf16 v[56:59], v[152:155], v[220:223], v[56:59]
	v_mfma_f32_16x16x32_bf16 v[44:47], v[144:147], v[228:231], v[44:47]
	v_mfma_f32_16x16x32_bf16 v[40:43], v[152:155], v[228:231], v[40:43]
	v_mfma_f32_16x16x32_bf16 v[28:31], v[144:147], v[236:239], v[28:31]
	v_mfma_f32_16x16x32_bf16 v[24:27], v[152:155], v[236:239], v[24:27]
	v_mfma_f32_16x16x32_bf16 v[12:15], v[144:147], v[244:247], v[12:15]
	v_mfma_f32_16x16x32_bf16 v[8:11], v[152:155], v[244:247], v[8:11]
	v_mfma_f32_16x16x32_bf16 v[60:63], v[148:151], v[224:227], v[60:63]
	v_mfma_f32_16x16x32_bf16 v[56:59], v[156:159], v[224:227], v[56:59]
	v_mfma_f32_16x16x32_bf16 v[44:47], v[148:151], v[232:235], v[44:47]
	v_mfma_f32_16x16x32_bf16 v[40:43], v[156:159], v[232:235], v[40:43]
	v_mfma_f32_16x16x32_bf16 v[28:31], v[148:151], v[240:243], v[28:31]
	v_mfma_f32_16x16x32_bf16 v[24:27], v[156:159], v[240:243], v[24:27]
	v_mfma_f32_16x16x32_bf16 v[12:15], v[148:151], v[248:251], v[12:15]
	v_mfma_f32_16x16x32_bf16 v[8:11], v[156:159], v[248:251], v[8:11]
	s_setprio 0
	s_setprio 1
	v_mfma_f32_16x16x32_bf16 v[52:55], v[160:163], v[220:223], v[52:55]
	v_mfma_f32_16x16x32_bf16 v[48:51], v[168:171], v[220:223], v[48:51]
	v_mfma_f32_16x16x32_bf16 v[36:39], v[160:163], v[228:231], v[36:39]
	v_mfma_f32_16x16x32_bf16 v[32:35], v[168:171], v[228:231], v[32:35]
	v_mfma_f32_16x16x32_bf16 v[20:23], v[160:163], v[236:239], v[20:23]
	v_mfma_f32_16x16x32_bf16 v[16:19], v[168:171], v[236:239], v[16:19]
	v_mfma_f32_16x16x32_bf16 v[4:7], v[160:163], v[244:247], v[4:7]
	v_mfma_f32_16x16x32_bf16 v[0:3], v[168:171], v[244:247], v[0:3]
	v_mfma_f32_16x16x32_bf16 v[52:55], v[164:167], v[224:227], v[52:55]
	v_mfma_f32_16x16x32_bf16 v[48:51], v[172:175], v[224:227], v[48:51]
	v_mfma_f32_16x16x32_bf16 v[36:39], v[164:167], v[232:235], v[36:39]
	v_mfma_f32_16x16x32_bf16 v[32:35], v[172:175], v[232:235], v[32:35]
	v_mfma_f32_16x16x32_bf16 v[20:23], v[164:167], v[240:243], v[20:23]
	v_mfma_f32_16x16x32_bf16 v[16:19], v[172:175], v[240:243], v[16:19]
	v_mfma_f32_16x16x32_bf16 v[4:7], v[164:167], v[248:251], v[4:7]
	v_mfma_f32_16x16x32_bf16 v[0:3], v[172:175], v[248:251], v[0:3]
	s_setprio 0
	s_waitcnt vmcnt(0)
	s_barrier
	s_add_u32 vcc_lo, s26, 0x0
	s_addc_u32 vcc_hi, s27, 0
	s_add_i32 m0, s30, 0x10000
	s_nop 0
	global_load_lds_dwordx4 v130, vcc
	s_add_i32 m0, s30, 0x12000
	s_nop 0
	global_load_lds_dwordx4 v134, vcc
	s_add_u32 vcc_lo, vcc_lo, 0x58000
	s_addc_u32 vcc_hi, vcc_hi, 0
	s_add_i32 m0, s30, 0x11000
	s_nop 0
	global_load_lds_dwordx4 v130, vcc
	s_add_i32 m0, s30, 0x13000
	s_nop 0
	global_load_lds_dwordx4 v134, vcc
	s_add_u32 vcc_lo, vcc_lo, 0x108000
	s_addc_u32 vcc_hi, vcc_hi, 0
	s_add_i32 m0, s30, 0x14000
	s_nop 0
	global_load_lds_dwordx4 v130, vcc
	s_add_i32 m0, s30, 0x16000
	s_nop 0
	global_load_lds_dwordx4 v134, vcc
	s_add_u32 vcc_lo, vcc_lo, 0x58000
	s_addc_u32 vcc_hi, vcc_hi, 0
	s_add_i32 m0, s30, 0x15000
	s_nop 0
	global_load_lds_dwordx4 v130, vcc
	s_add_i32 m0, s30, 0x17000
	s_nop 0
	global_load_lds_dwordx4 v134, vcc
	ds_read_b128 v[144:147], v185 offset:32768
	ds_read_b128 v[148:151], v185 offset:33792
	ds_read_b128 v[152:155], v185 offset:34816
	ds_read_b128 v[156:159], v185 offset:35840
	ds_read_b128 v[160:163], v186 offset:32768
	ds_read_b128 v[164:167], v186 offset:33792
	ds_read_b128 v[168:171], v186 offset:34816
	ds_read_b128 v[172:175], v186 offset:35840
	ds_read_b128 v[176:179], v187 offset:32768
	ds_read_b128 v[190:193], v187 offset:33792
	ds_read_b128 v[194:197], v187 offset:34816
	ds_read_b128 v[198:201], v187 offset:35840
	ds_read_b128 v[202:205], v187 offset:36864
	ds_read_b128 v[206:209], v187 offset:37888
	ds_read_b128 v[210:213], v187 offset:38912
	ds_read_b128 v[214:217], v187 offset:39936
	ds_read_b128 v[220:223], v187 offset:49152
	ds_read_b128 v[224:227], v187 offset:50176
	ds_read_b128 v[228:231], v187 offset:51200
	ds_read_b128 v[232:235], v187 offset:52224
	ds_read_b128 v[236:239], v187 offset:53248
	ds_read_b128 v[240:243], v187 offset:54272
	ds_read_b128 v[244:247], v187 offset:55296
	ds_read_b128 v[248:251], v187 offset:56320
	s_nop 15
	s_nop 15
	s_waitcnt lgkmcnt(0)
	s_barrier
	s_setprio 1
	v_mfma_f32_16x16x32_bf16 v[72:75], v[144:147], v[176:179], v[72:75]
	v_mfma_f32_16x16x32_bf16 v[76:79], v[152:155], v[176:179], v[76:79]
	v_mfma_f32_16x16x32_bf16 v[96:99], v[144:147], v[194:197], v[96:99]
	v_mfma_f32_16x16x32_bf16 v[100:103], v[152:155], v[194:197], v[100:103]
	v_mfma_f32_16x16x32_bf16 v[120:123], v[144:147], v[202:205], v[120:123]
	v_mfma_f32_16x16x32_bf16 v[124:127], v[152:155], v[202:205], v[124:127]
	v_mfma_f32_16x16x32_bf16 v[92:95], v[144:147], v[210:213], v[92:95]
	v_mfma_f32_16x16x32_bf16 v[84:87], v[152:155], v[210:213], v[84:87]
	v_mfma_f32_16x16x32_bf16 v[72:75], v[148:151], v[190:193], v[72:75]
	v_mfma_f32_16x16x32_bf16 v[76:79], v[156:159], v[190:193], v[76:79]
	v_mfma_f32_16x16x32_bf16 v[96:99], v[148:151], v[198:201], v[96:99]
	v_mfma_f32_16x16x32_bf16 v[100:103], v[156:159], v[198:201], v[100:103]
	v_mfma_f32_16x16x32_bf16 v[120:123], v[148:151], v[206:209], v[120:123]
	v_mfma_f32_16x16x32_bf16 v[124:127], v[156:159], v[206:209], v[124:127]
	v_mfma_f32_16x16x32_bf16 v[92:95], v[148:151], v[214:217], v[92:95]
	v_mfma_f32_16x16x32_bf16 v[84:87], v[156:159], v[214:217], v[84:87]
	s_setprio 0
	s_setprio 1
	v_mfma_f32_16x16x32_bf16 v[80:83], v[160:163], v[176:179], v[80:83]
	v_mfma_f32_16x16x32_bf16 v[88:91], v[168:171], v[176:179], v[88:91]
	v_mfma_f32_16x16x32_bf16 v[108:111], v[160:163], v[194:197], v[108:111]
	v_mfma_f32_16x16x32_bf16 v[112:115], v[168:171], v[194:197], v[112:115]
	v_mfma_f32_16x16x32_bf16 v[116:119], v[160:163], v[202:205], v[116:119]
	v_mfma_f32_16x16x32_bf16 v[104:107], v[168:171], v[202:205], v[104:107]
	v_mfma_f32_16x16x32_bf16 v[68:71], v[160:163], v[210:213], v[68:71]
	v_mfma_f32_16x16x32_bf16 v[64:67], v[168:171], v[210:213], v[64:67]
	v_mfma_f32_16x16x32_bf16 v[80:83], v[164:167], v[190:193], v[80:83]
	v_mfma_f32_16x16x32_bf16 v[88:91], v[172:175], v[190:193], v[88:91]
	v_mfma_f32_16x16x32_bf16 v[108:111], v[164:167], v[198:201], v[108:111]
	v_mfma_f32_16x16x32_bf16 v[112:115], v[172:175], v[198:201], v[112:115]
	v_mfma_f32_16x16x32_bf16 v[116:119], v[164:167], v[206:209], v[116:119]
	v_mfma_f32_16x16x32_bf16 v[104:107], v[172:175], v[206:209], v[104:107]
	v_mfma_f32_16x16x32_bf16 v[68:71], v[164:167], v[214:217], v[68:71]
	v_mfma_f32_16x16x32_bf16 v[64:67], v[172:175], v[214:217], v[64:67]
	s_setprio 0
	s_setprio 1
	v_mfma_f32_16x16x32_bf16 v[60:63], v[144:147], v[220:223], v[60:63]
	v_mfma_f32_16x16x32_bf16 v[56:59], v[152:155], v[220:223], v[56:59]
	v_mfma_f32_16x16x32_bf16 v[44:47], v[144:147], v[228:231], v[44:47]
	v_mfma_f32_16x16x32_bf16 v[40:43], v[152:155], v[228:231], v[40:43]
	v_mfma_f32_16x16x32_bf16 v[28:31], v[144:147], v[236:239], v[28:31]
	v_mfma_f32_16x16x32_bf16 v[24:27], v[152:155], v[236:239], v[24:27]
	v_mfma_f32_16x16x32_bf16 v[12:15], v[144:147], v[244:247], v[12:15]
	v_mfma_f32_16x16x32_bf16 v[8:11], v[152:155], v[244:247], v[8:11]
	v_mfma_f32_16x16x32_bf16 v[60:63], v[148:151], v[224:227], v[60:63]
	v_mfma_f32_16x16x32_bf16 v[56:59], v[156:159], v[224:227], v[56:59]
	v_mfma_f32_16x16x32_bf16 v[44:47], v[148:151], v[232:235], v[44:47]
	v_mfma_f32_16x16x32_bf16 v[40:43], v[156:159], v[232:235], v[40:43]
	v_mfma_f32_16x16x32_bf16 v[28:31], v[148:151], v[240:243], v[28:31]
	v_mfma_f32_16x16x32_bf16 v[24:27], v[156:159], v[240:243], v[24:27]
	v_mfma_f32_16x16x32_bf16 v[12:15], v[148:151], v[248:251], v[12:15]
	v_mfma_f32_16x16x32_bf16 v[8:11], v[156:159], v[248:251], v[8:11]
	s_setprio 0
	s_setprio 1
	v_mfma_f32_16x16x32_bf16 v[52:55], v[160:163], v[220:223], v[52:55]
	v_mfma_f32_16x16x32_bf16 v[48:51], v[168:171], v[220:223], v[48:51]
	v_mfma_f32_16x16x32_bf16 v[36:39], v[160:163], v[228:231], v[36:39]
	v_mfma_f32_16x16x32_bf16 v[32:35], v[168:171], v[228:231], v[32:35]
	v_mfma_f32_16x16x32_bf16 v[20:23], v[160:163], v[236:239], v[20:23]
	v_mfma_f32_16x16x32_bf16 v[16:19], v[168:171], v[236:239], v[16:19]
	v_mfma_f32_16x16x32_bf16 v[4:7], v[160:163], v[244:247], v[4:7]
	v_mfma_f32_16x16x32_bf16 v[0:3], v[168:171], v[244:247], v[0:3]
	v_mfma_f32_16x16x32_bf16 v[52:55], v[164:167], v[224:227], v[52:55]
	v_mfma_f32_16x16x32_bf16 v[48:51], v[172:175], v[224:227], v[48:51]
	v_mfma_f32_16x16x32_bf16 v[36:39], v[164:167], v[232:235], v[36:39]
	v_mfma_f32_16x16x32_bf16 v[32:35], v[172:175], v[232:235], v[32:35]
	v_mfma_f32_16x16x32_bf16 v[20:23], v[164:167], v[240:243], v[20:23]
	v_mfma_f32_16x16x32_bf16 v[16:19], v[172:175], v[240:243], v[16:19]
	v_mfma_f32_16x16x32_bf16 v[4:7], v[164:167], v[248:251], v[4:7]
	v_mfma_f32_16x16x32_bf16 v[0:3], v[172:175], v[248:251], v[0:3]
	s_setprio 0
	s_waitcnt vmcnt(0)
	s_barrier
	s_add_i32 s56, s56, 2
	s_add_u32 s46, s46, 0x100
	s_addc_u32 s47, s47, 0
	s_cmpk_gt_u32 s56, 0x55
	s_mov_b64 s[22:23], s[24:25]
	s_cbranch_scc0 .LBB0_940
	s_branch .Lk64_done_p7
.Lk64_trail_p7:
	s_add_u32 vcc_lo, s22, 0x80
	s_addc_u32 vcc_hi, s23, 0
	s_add_i32 m0, s30, 0xa000
	s_nop 0
	global_load_lds_dwordx4 v132, vcc
	s_add_u32 vcc_lo, vcc_lo, 0x58000
	s_addc_u32 vcc_hi, vcc_hi, 0
	s_add_i32 m0, s30, 0x9000
	s_nop 0
	global_load_lds_dwordx4 v128, vcc
	s_add_u32 vcc_lo, vcc_lo, 0x108000
	s_addc_u32 vcc_hi, vcc_hi, 0
	s_add_i32 m0, s30, 0xe000
	s_nop 0
	global_load_lds_dwordx4 v132, vcc
	s_add_u32 vcc_lo, vcc_lo, 0x58000
	s_addc_u32 vcc_hi, vcc_hi, 0
	s_add_i32 m0, s30, 0xd000
	s_nop 0
	global_load_lds_dwordx4 v128, vcc
	s_add_u32 vcc_lo, s28, 0x0
	s_addc_u32 vcc_hi, s29, 0
	s_mov_b32 m0, s30
	s_nop 0
	global_load_lds_dwordx4 v128, vcc
	s_sub_u32 vcc_lo, vcc_lo, 0x58000
	s_subb_u32 vcc_hi, vcc_hi, 0
	s_sub_i32 m0, s30, 0x1000
	s_nop 0
	global_load_lds_dwordx4 v128, vcc
	s_add_u32 vcc_lo, vcc_lo, 0x1b8000
	s_addc_u32 vcc_hi, vcc_hi, 0
	s_add_i32 m0, s30, 0x4000
	s_nop 0
	global_load_lds_dwordx4 v128, vcc
	s_sub_u32 vcc_lo, vcc_lo, 0x58000
	s_subb_u32 vcc_hi, vcc_hi, 0
	s_add_i32 m0, s30, 0x3000
	s_nop 0
	global_load_lds_dwordx4 v128, vcc
	ds_read_b128 v[144:147], v185 offset:0
	ds_read_b128 v[148:151], v185 offset:1024
	ds_read_b128 v[152:155], v185 offset:2048
	ds_read_b128 v[156:159], v185 offset:3072
	ds_read_b128 v[160:163], v186 offset:0
	ds_read_b128 v[164:167], v186 offset:1024
	ds_read_b128 v[168:171], v186 offset:2048
	ds_read_b128 v[172:175], v186 offset:3072
	ds_read_b128 v[176:179], v187 offset:0
	ds_read_b128 v[190:193], v187 offset:1024
	ds_read_b128 v[194:197], v187 offset:2048
	ds_read_b128 v[198:201], v187 offset:3072
	ds_read_b128 v[202:205], v187 offset:4096
	ds_read_b128 v[206:209], v187 offset:5120
	ds_read_b128 v[210:213], v187 offset:6144
	ds_read_b128 v[214:217], v187 offset:7168
	ds_read_b128 v[220:223], v187 offset:16384
	ds_read_b128 v[224:227], v187 offset:17408
	ds_read_b128 v[228:231], v187 offset:18432
	ds_read_b128 v[232:235], v187 offset:19456
	ds_read_b128 v[236:239], v187 offset:20480
	ds_read_b128 v[240:243], v187 offset:21504
	ds_read_b128 v[244:247], v187 offset:22528
	ds_read_b128 v[248:251], v187 offset:23552
	s_nop 15
	s_nop 15
	s_waitcnt lgkmcnt(0)
	s_barrier
	s_setprio 1
	v_mfma_f32_16x16x32_bf16 v[72:75], v[144:147], v[176:179], v[72:75]
	v_mfma_f32_16x16x32_bf16 v[76:79], v[152:155], v[176:179], v[76:79]
	v_mfma_f32_16x16x32_bf16 v[96:99], v[144:147], v[194:197], v[96:99]
	v_mfma_f32_16x16x32_bf16 v[100:103], v[152:155], v[194:197], v[100:103]
	v_mfma_f32_16x16x32_bf16 v[120:123], v[144:147], v[202:205], v[120:123]
	v_mfma_f32_16x16x32_bf16 v[124:127], v[152:155], v[202:205], v[124:127]
	v_mfma_f32_16x16x32_bf16 v[92:95], v[144:147], v[210:213], v[92:95]
	v_mfma_f32_16x16x32_bf16 v[84:87], v[152:155], v[210:213], v[84:87]
	v_mfma_f32_16x16x32_bf16 v[72:75], v[148:151], v[190:193], v[72:75]
	v_mfma_f32_16x16x32_bf16 v[76:79], v[156:159], v[190:193], v[76:79]
	v_mfma_f32_16x16x32_bf16 v[96:99], v[148:151], v[198:201], v[96:99]
	v_mfma_f32_16x16x32_bf16 v[100:103], v[156:159], v[198:201], v[100:103]
	v_mfma_f32_16x16x32_bf16 v[120:123], v[148:151], v[206:209], v[120:123]
	v_mfma_f32_16x16x32_bf16 v[124:127], v[156:159], v[206:209], v[124:127]
	v_mfma_f32_16x16x32_bf16 v[92:95], v[148:151], v[214:217], v[92:95]
	v_mfma_f32_16x16x32_bf16 v[84:87], v[156:159], v[214:217], v[84:87]
	s_setprio 0
	s_setprio 1
	v_mfma_f32_16x16x32_bf16 v[80:83], v[160:163], v[176:179], v[80:83]
	v_mfma_f32_16x16x32_bf16 v[88:91], v[168:171], v[176:179], v[88:91]
	v_mfma_f32_16x16x32_bf16 v[108:111], v[160:163], v[194:197], v[108:111]
	v_mfma_f32_16x16x32_bf16 v[112:115], v[168:171], v[194:197], v[112:115]
	v_mfma_f32_16x16x32_bf16 v[116:119], v[160:163], v[202:205], v[116:119]
	v_mfma_f32_16x16x32_bf16 v[104:107], v[168:171], v[202:205], v[104:107]
	v_mfma_f32_16x16x32_bf16 v[68:71], v[160:163], v[210:213], v[68:71]
	v_mfma_f32_16x16x32_bf16 v[64:67], v[168:171], v[210:213], v[64:67]
	v_mfma_f32_16x16x32_bf16 v[80:83], v[164:167], v[190:193], v[80:83]
	v_mfma_f32_16x16x32_bf16 v[88:91], v[172:175], v[190:193], v[88:91]
	v_mfma_f32_16x16x32_bf16 v[108:111], v[164:167], v[198:201], v[108:111]
	v_mfma_f32_16x16x32_bf16 v[112:115], v[172:175], v[198:201], v[112:115]
	v_mfma_f32_16x16x32_bf16 v[116:119], v[164:167], v[206:209], v[116:119]
	v_mfma_f32_16x16x32_bf16 v[104:107], v[172:175], v[206:209], v[104:107]
	v_mfma_f32_16x16x32_bf16 v[68:71], v[164:167], v[214:217], v[68:71]
	v_mfma_f32_16x16x32_bf16 v[64:67], v[172:175], v[214:217], v[64:67]
	s_setprio 0
	s_setprio 1
	v_mfma_f32_16x16x32_bf16 v[60:63], v[144:147], v[220:223], v[60:63]
	v_mfma_f32_16x16x32_bf16 v[56:59], v[152:155], v[220:223], v[56:59]
	v_mfma_f32_16x16x32_bf16 v[44:47], v[144:147], v[228:231], v[44:47]
	v_mfma_f32_16x16x32_bf16 v[40:43], v[152:155], v[228:231], v[40:43]
	v_mfma_f32_16x16x32_bf16 v[28:31], v[144:147], v[236:239], v[28:31]
	v_mfma_f32_16x16x32_bf16 v[24:27], v[152:155], v[236:239], v[24:27]
	v_mfma_f32_16x16x32_bf16 v[12:15], v[144:147], v[244:247], v[12:15]
	v_mfma_f32_16x16x32_bf16 v[8:11], v[152:155], v[244:247], v[8:11]
	v_mfma_f32_16x16x32_bf16 v[60:63], v[148:151], v[224:227], v[60:63]
	v_mfma_f32_16x16x32_bf16 v[56:59], v[156:159], v[224:227], v[56:59]
	v_mfma_f32_16x16x32_bf16 v[44:47], v[148:151], v[232:235], v[44:47]
	v_mfma_f32_16x16x32_bf16 v[40:43], v[156:159], v[232:235], v[40:43]
	v_mfma_f32_16x16x32_bf16 v[28:31], v[148:151], v[240:243], v[28:31]
	v_mfma_f32_16x16x32_bf16 v[24:27], v[156:159], v[240:243], v[24:27]
	v_mfma_f32_16x16x32_bf16 v[12:15], v[148:151], v[248:251], v[12:15]
	v_mfma_f32_16x16x32_bf16 v[8:11], v[156:159], v[248:251], v[8:11]
	s_setprio 0
	s_setprio 1
	v_mfma_f32_16x16x32_bf16 v[52:55], v[160:163], v[220:223], v[52:55]
	v_mfma_f32_16x16x32_bf16 v[48:51], v[168:171], v[220:223], v[48:51]
	v_mfma_f32_16x16x32_bf16 v[36:39], v[160:163], v[228:231], v[36:39]
	v_mfma_f32_16x16x32_bf16 v[32:35], v[168:171], v[228:231], v[32:35]
	v_mfma_f32_16x16x32_bf16 v[20:23], v[160:163], v[236:239], v[20:23]
	v_mfma_f32_16x16x32_bf16 v[16:19], v[168:171], v[236:239], v[16:19]
	v_mfma_f32_16x16x32_bf16 v[4:7], v[160:163], v[244:247], v[4:7]
	v_mfma_f32_16x16x32_bf16 v[0:3], v[168:171], v[244:247], v[0:3]
	v_mfma_f32_16x16x32_bf16 v[52:55], v[164:167], v[224:227], v[52:55]
	v_mfma_f32_16x16x32_bf16 v[48:51], v[172:175], v[224:227], v[48:51]
	v_mfma_f32_16x16x32_bf16 v[36:39], v[164:167], v[232:235], v[36:39]
	v_mfma_f32_16x16x32_bf16 v[32:35], v[172:175], v[232:235], v[32:35]
	v_mfma_f32_16x16x32_bf16 v[20:23], v[164:167], v[240:243], v[20:23]
	v_mfma_f32_16x16x32_bf16 v[16:19], v[172:175], v[240:243], v[16:19]
	v_mfma_f32_16x16x32_bf16 v[4:7], v[164:167], v[248:251], v[4:7]
	v_mfma_f32_16x16x32_bf16 v[0:3], v[172:175], v[248:251], v[0:3]
	s_setprio 0
	s_waitcnt vmcnt(0)
	s_barrier
	s_add_u32 vcc_lo, s28, 0x0
	s_addc_u32 vcc_hi, s29, 0
	s_add_i32 m0, s30, 0x2000
	s_nop 0
	global_load_lds_dwordx4 v132, vcc
	s_add_u32 vcc_lo, vcc_lo, 0x58000
	s_addc_u32 vcc_hi, vcc_hi, 0
	s_add_i32 m0, s30, 0x1000
	s_nop 0
	global_load_lds_dwordx4 v128, vcc
	s_add_u32 vcc_lo, vcc_lo, 0x108000
	s_addc_u32 vcc_hi, vcc_hi, 0
	s_add_i32 m0, s30, 0x6000
	s_nop 0
	global_load_lds_dwordx4 v132, vcc
	s_add_u32 vcc_lo, vcc_lo, 0x58000
	s_addc_u32 vcc_hi, vcc_hi, 0
	s_add_i32 m0, s30, 0x5000
	s_nop 0
	global_load_lds_dwordx4 v128, vcc
	s_add_u32 vcc_lo, s28, 0x80
	s_addc_u32 vcc_hi, s29, 0
	s_add_i32 m0, s30, 0x8000
	s_nop 0
	global_load_lds_dwordx4 v128, vcc
	s_sub_u32 vcc_lo, vcc_lo, 0x58000
	s_subb_u32 vcc_hi, vcc_hi, 0
	s_add_i32 m0, s30, 0x7000
	s_nop 0
	global_load_lds_dwordx4 v128, vcc
	s_add_u32 vcc_lo, vcc_lo, 0x1b8000
	s_addc_u32 vcc_hi, vcc_hi, 0
	s_add_i32 m0, s30, 0xc000
	s_nop 0
	global_load_lds_dwordx4 v128, vcc
	s_sub_u32 vcc_lo, vcc_lo, 0x58000
	s_subb_u32 vcc_hi, vcc_hi, 0
	s_add_i32 m0, s30, 0xb000
	s_nop 0
	global_load_lds_dwordx4 v128, vcc
	ds_read_b128 v[144:147], v185 offset:32768
	ds_read_b128 v[148:151], v185 offset:33792
	ds_read_b128 v[152:155], v185 offset:34816
	ds_read_b128 v[156:159], v185 offset:35840
	ds_read_b128 v[160:163], v186 offset:32768
	ds_read_b128 v[164:167], v186 offset:33792
	ds_read_b128 v[168:171], v186 offset:34816
	ds_read_b128 v[172:175], v186 offset:35840
	ds_read_b128 v[176:179], v187 offset:32768
	ds_read_b128 v[190:193], v187 offset:33792
	ds_read_b128 v[194:197], v187 offset:34816
	ds_read_b128 v[198:201], v187 offset:35840
	ds_read_b128 v[202:205], v187 offset:36864
	ds_read_b128 v[206:209], v187 offset:37888
	ds_read_b128 v[210:213], v187 offset:38912
	ds_read_b128 v[214:217], v187 offset:39936
	ds_read_b128 v[220:223], v187 offset:49152
	ds_read_b128 v[224:227], v187 offset:50176
	ds_read_b128 v[228:231], v187 offset:51200
	ds_read_b128 v[232:235], v187 offset:52224
	ds_read_b128 v[236:239], v187 offset:53248
	ds_read_b128 v[240:243], v187 offset:54272
	ds_read_b128 v[244:247], v187 offset:55296
	ds_read_b128 v[248:251], v187 offset:56320
	s_nop 15
	s_nop 15
	s_waitcnt lgkmcnt(0)
	s_barrier
	s_setprio 1
	v_mfma_f32_16x16x32_bf16 v[72:75], v[144:147], v[176:179], v[72:75]
	v_mfma_f32_16x16x32_bf16 v[76:79], v[152:155], v[176:179], v[76:79]
	v_mfma_f32_16x16x32_bf16 v[96:99], v[144:147], v[194:197], v[96:99]
	v_mfma_f32_16x16x32_bf16 v[100:103], v[152:155], v[194:197], v[100:103]
	v_mfma_f32_16x16x32_bf16 v[120:123], v[144:147], v[202:205], v[120:123]
	v_mfma_f32_16x16x32_bf16 v[124:127], v[152:155], v[202:205], v[124:127]
	v_mfma_f32_16x16x32_bf16 v[92:95], v[144:147], v[210:213], v[92:95]
	v_mfma_f32_16x16x32_bf16 v[84:87], v[152:155], v[210:213], v[84:87]
	v_mfma_f32_16x16x32_bf16 v[72:75], v[148:151], v[190:193], v[72:75]
	v_mfma_f32_16x16x32_bf16 v[76:79], v[156:159], v[190:193], v[76:79]
	v_mfma_f32_16x16x32_bf16 v[96:99], v[148:151], v[198:201], v[96:99]
	v_mfma_f32_16x16x32_bf16 v[100:103], v[156:159], v[198:201], v[100:103]
	v_mfma_f32_16x16x32_bf16 v[120:123], v[148:151], v[206:209], v[120:123]
	v_mfma_f32_16x16x32_bf16 v[124:127], v[156:159], v[206:209], v[124:127]
	v_mfma_f32_16x16x32_bf16 v[92:95], v[148:151], v[214:217], v[92:95]
	v_mfma_f32_16x16x32_bf16 v[84:87], v[156:159], v[214:217], v[84:87]
	s_setprio 0
	s_setprio 1
	v_mfma_f32_16x16x32_bf16 v[80:83], v[160:163], v[176:179], v[80:83]
	v_mfma_f32_16x16x32_bf16 v[88:91], v[168:171], v[176:179], v[88:91]
	v_mfma_f32_16x16x32_bf16 v[108:111], v[160:163], v[194:197], v[108:111]
	v_mfma_f32_16x16x32_bf16 v[112:115], v[168:171], v[194:197], v[112:115]
	v_mfma_f32_16x16x32_bf16 v[116:119], v[160:163], v[202:205], v[116:119]
	v_mfma_f32_16x16x32_bf16 v[104:107], v[168:171], v[202:205], v[104:107]
	v_mfma_f32_16x16x32_bf16 v[68:71], v[160:163], v[210:213], v[68:71]
	v_mfma_f32_16x16x32_bf16 v[64:67], v[168:171], v[210:213], v[64:67]
	v_mfma_f32_16x16x32_bf16 v[80:83], v[164:167], v[190:193], v[80:83]
	v_mfma_f32_16x16x32_bf16 v[88:91], v[172:175], v[190:193], v[88:91]
	v_mfma_f32_16x16x32_bf16 v[108:111], v[164:167], v[198:201], v[108:111]
	v_mfma_f32_16x16x32_bf16 v[112:115], v[172:175], v[198:201], v[112:115]
	v_mfma_f32_16x16x32_bf16 v[116:119], v[164:167], v[206:209], v[116:119]
	v_mfma_f32_16x16x32_bf16 v[104:107], v[172:175], v[206:209], v[104:107]
	v_mfma_f32_16x16x32_bf16 v[68:71], v[164:167], v[214:217], v[68:71]
	v_mfma_f32_16x16x32_bf16 v[64:67], v[172:175], v[214:217], v[64:67]
	s_setprio 0
	s_setprio 1
	v_mfma_f32_16x16x32_bf16 v[60:63], v[144:147], v[220:223], v[60:63]
	v_mfma_f32_16x16x32_bf16 v[56:59], v[152:155], v[220:223], v[56:59]
	v_mfma_f32_16x16x32_bf16 v[44:47], v[144:147], v[228:231], v[44:47]
	v_mfma_f32_16x16x32_bf16 v[40:43], v[152:155], v[228:231], v[40:43]
	v_mfma_f32_16x16x32_bf16 v[28:31], v[144:147], v[236:239], v[28:31]
	v_mfma_f32_16x16x32_bf16 v[24:27], v[152:155], v[236:239], v[24:27]
	v_mfma_f32_16x16x32_bf16 v[12:15], v[144:147], v[244:247], v[12:15]
	v_mfma_f32_16x16x32_bf16 v[8:11], v[152:155], v[244:247], v[8:11]
	v_mfma_f32_16x16x32_bf16 v[60:63], v[148:151], v[224:227], v[60:63]
	v_mfma_f32_16x16x32_bf16 v[56:59], v[156:159], v[224:227], v[56:59]
	v_mfma_f32_16x16x32_bf16 v[44:47], v[148:151], v[232:235], v[44:47]
	v_mfma_f32_16x16x32_bf16 v[40:43], v[156:159], v[232:235], v[40:43]
	v_mfma_f32_16x16x32_bf16 v[28:31], v[148:151], v[240:243], v[28:31]
	v_mfma_f32_16x16x32_bf16 v[24:27], v[156:159], v[240:243], v[24:27]
	v_mfma_f32_16x16x32_bf16 v[12:15], v[148:151], v[248:251], v[12:15]
	v_mfma_f32_16x16x32_bf16 v[8:11], v[156:159], v[248:251], v[8:11]
	s_setprio 0
	s_setprio 1
	v_mfma_f32_16x16x32_bf16 v[52:55], v[160:163], v[220:223], v[52:55]
	v_mfma_f32_16x16x32_bf16 v[48:51], v[168:171], v[220:223], v[48:51]
	v_mfma_f32_16x16x32_bf16 v[36:39], v[160:163], v[228:231], v[36:39]
	v_mfma_f32_16x16x32_bf16 v[32:35], v[168:171], v[228:231], v[32:35]
	v_mfma_f32_16x16x32_bf16 v[20:23], v[160:163], v[236:239], v[20:23]
	v_mfma_f32_16x16x32_bf16 v[16:19], v[168:171], v[236:239], v[16:19]
	v_mfma_f32_16x16x32_bf16 v[4:7], v[160:163], v[244:247], v[4:7]
	v_mfma_f32_16x16x32_bf16 v[0:3], v[168:171], v[244:247], v[0:3]
	v_mfma_f32_16x16x32_bf16 v[52:55], v[164:167], v[224:227], v[52:55]
	v_mfma_f32_16x16x32_bf16 v[48:51], v[172:175], v[224:227], v[48:51]
	v_mfma_f32_16x16x32_bf16 v[36:39], v[164:167], v[232:235], v[36:39]
	v_mfma_f32_16x16x32_bf16 v[32:35], v[172:175], v[232:235], v[32:35]
	v_mfma_f32_16x16x32_bf16 v[20:23], v[164:167], v[240:243], v[20:23]
	v_mfma_f32_16x16x32_bf16 v[16:19], v[172:175], v[240:243], v[16:19]
	v_mfma_f32_16x16x32_bf16 v[4:7], v[164:167], v[248:251], v[4:7]
	v_mfma_f32_16x16x32_bf16 v[0:3], v[172:175], v[248:251], v[0:3]
	s_setprio 0
	s_waitcnt vmcnt(0)
	s_barrier
	s_add_i32 s56, s56, 2
	s_add_u32 s46, s46, 0x100
	s_addc_u32 s47, s47, 0
	s_cmpk_gt_u32 s56, 0x55
	s_mov_b64 s[22:23], s[24:25]
	s_cbranch_scc0 .LBB0_940
.Lk64_done_p7:
	s_and_b64 vcc, exec, s[12:13]
	s_cbranch_vccz .LBB0_943
	s_barrier
